# v033 + MLA general ds_read hoisting pass (up to 4 MFMAs earlier, waits regenerated)
# baseline (speedup 1.0000x reference)
; template <bool NA>
; __device__ __forceinline__ void attn_unit(LAS unsigned char* lds, const bf16_t* Q, const bf16_t* Kg, const bf16_t* Kr, const bf16_t* Vt, bf16_t* O,
;                                           int h, int seqrow0, int q0, int t0, int NT, int rows, int g0, const float* rpb_h, int wid) {
;     ...
;         for (int t = 0; t < NT; t += 8) {
;             A_STEP(sA0, sA1, tmA, sB0, sB1, tmB, t);
;             A_STEP(sB0, sB1, tmB, sA0, sA1, tmA, t + 1);
;             A_STEP(sA0, sA1, tmA, sB0, sB1, tmB, t + 2);
;             A_STEP(sB0, sB1, tmB, sA0, sA1, tmA, t + 3);
;             A_STEP(sA0, sA1, tmA, sB0, sB1, tmB, t + 4);
;             A_STEP(sB0, sB1, tmB, sA0, sA1, tmA, t + 5);
;             A_STEP(sA0, sA1, tmA, sB0, sB1, tmB, t + 6);
;             A_STEP(sB0, sB1, tmB, sA0, sA1, tmA, t + 7);
;         }
.LBB0_893:
	ds_read_b128 v[118:121], v181 offset:32
	ds_read_b128 v[138:141], v181 offset:6688
	s_waitcnt lgkmcnt(3)
	v_mfma_f32_32x32x16_bf16 v[80:95], v[64:67], v[144:147], v[32:47]
	v_exp_f32_e32 v117, v122
	v_exp_f32_e32 v142, v123
	v_exp_f32_e32 v143, v124
	v_exp_f32_e32 v202, v125
	v_exp_f32_e32 v126, v126
	v_exp_f32_e32 v127, v127
	s_waitcnt lgkmcnt(2)
	v_mfma_f32_32x32x16_bf16 v[64:79], v[112:115], v[144:147], v[32:47]
	ds_read_b128 v[112:115], v181 offset:64
	ds_read_b128 v[122:125], v181 offset:6720
	s_waitcnt lgkmcnt(3)
	v_mfma_f32_32x32x16_bf16 v[80:95], v[118:121], v[148:151], v[80:95]
	v_cvt_pk_bf16_f32 v118, v117, v142
	v_add_f32_e32 v117, v143, v117
	v_add_f32_e32 v120, v202, v142
	v_add_f32_e32 v117, v126, v117
	s_waitcnt lgkmcnt(2)
	v_mfma_f32_32x32x16_bf16 v[64:79], v[138:141], v[148:151], v[64:79]
	v_add_f32_e32 v121, v127, v120
	v_exp_f32_e32 v203, v128
	v_exp_f32_e32 v204, v129
	v_exp_f32_e32 v205, v130
	v_exp_f32_e32 v213, v131
	v_exp_f32_e32 v214, v132
	v_exp_f32_e32 v215, v133
	v_cvt_pk_bf16_f32 v119, v143, v202
	v_cvt_pk_bf16_f32 v120, v126, v127
	ds_read_b128 v[126:129], v181 offset:96
	ds_read_b128 v[130:133], v181 offset:6752
	s_waitcnt lgkmcnt(3)
	v_mfma_f32_32x32x16_bf16 v[80:95], v[112:115], v[152:155], v[80:95]
	v_add_f32_e32 v112, v203, v117
	v_add_f32_e32 v113, v204, v121
	v_add_f32_e32 v114, v205, v112
	v_add_f32_e32 v113, v213, v113
	v_add_f32_e32 v114, v214, v114
	v_add_f32_e32 v115, v215, v113
	s_waitcnt lgkmcnt(2)
	v_mfma_f32_32x32x16_bf16 v[64:79], v[122:125], v[152:155], v[64:79]
	ds_read_b128 v[122:125], v181 offset:128
	v_exp_f32_e32 v138, v134
	v_exp_f32_e32 v139, v135
	v_exp_f32_e32 v140, v136
	v_exp_f32_e32 v141, v137
	ds_read_b128 v[134:137], v181 offset:6784
	v_cvt_pk_bf16_f32 v121, v203, v204
	v_cvt_pk_bf16_f32 v112, v205, v213
	v_cvt_pk_bf16_f32 v113, v214, v215
	s_waitcnt lgkmcnt(3)
	v_mfma_f32_32x32x16_bf16 v[80:95], v[126:129], v[156:159], v[80:95]
	v_exp_f32_e32 v117, v96
	v_exp_f32_e32 v142, v97
	v_add_f32_e32 v96, v138, v114
	v_add_f32_e32 v97, v139, v115
	v_exp_f32_e32 v203, v100
	v_exp_f32_e32 v204, v101
	s_waitcnt lgkmcnt(2)
	v_mfma_f32_32x32x16_bf16 v[64:79], v[130:133], v[156:159], v[64:79]
	v_add_f32_e32 v100, v140, v96
	v_add_f32_e32 v101, v141, v97
	v_exp_f32_e32 v143, v98
	v_exp_f32_e32 v202, v99
	ds_read_b128 v[96:99], v181 offset:160
	ds_read_b128 v[126:129], v181 offset:6816
	v_cvt_pk_bf16_f32 v114, v138, v139
	v_cvt_pk_bf16_f32 v115, v140, v141
	s_waitcnt lgkmcnt(3)
	v_mfma_f32_32x32x16_bf16 v[80:95], v[122:125], v[160:163], v[80:95]
	v_exp_f32_e32 v130, v102
	v_add_f32_e32 v102, v117, v100
	v_add_f32_e32 v101, v142, v101
	v_exp_f32_e32 v131, v104
	v_add_f32_e32 v102, v143, v102
	v_add_f32_e32 v104, v202, v101
	s_waitcnt lgkmcnt(2)
	v_mfma_f32_32x32x16_bf16 v[64:79], v[134:137], v[160:163], v[64:79]
	v_cvt_pk_bf16_f32 v100, v117, v142
	v_add_f32_e32 v117, v203, v102
	v_add_f32_e32 v134, v204, v104
	v_exp_f32_e32 v103, v103
	v_exp_f32_e32 v132, v105
	v_exp_f32_e32 v133, v106
	v_exp_f32_e32 v138, v107
	ds_read_b128 v[104:107], v211 offset:27648
	ds_read_b128 v[122:125], v211 offset:32256
	v_cvt_pk_bf16_f32 v101, v143, v202
	v_cvt_pk_bf16_f32 v102, v203, v204
	s_waitcnt lgkmcnt(3)
	v_mfma_f32_32x32x16_bf16 v[80:95], v[96:99], v[164:167], v[80:95]
	v_add_f32_e32 v96, v130, v117
	v_add_f32_e32 v97, v103, v134
	v_add_f32_e32 v98, v131, v96
	v_add_f32_e32 v97, v132, v97
	v_add_f32_e32 v98, v133, v98
	v_add_f32_e32 v99, v138, v97
	s_waitcnt lgkmcnt(2)
	v_mfma_f32_32x32x16_bf16 v[64:79], v[126:129], v[164:167], v[64:79]
	v_exp_f32_e32 v135, v108
	v_exp_f32_e32 v136, v109
	v_exp_f32_e32 v137, v110
	v_exp_f32_e32 v139, v111
	ds_read_b128 v[108:111], v211 offset:27680
	ds_read_b128 v[126:129], v211 offset:32288
	v_cvt_pk_bf16_f32 v103, v130, v103
	v_cvt_pk_bf16_f32 v96, v131, v132
	v_cvt_pk_bf16_f32 v97, v133, v138
	s_waitcnt lgkmcnt(3)
	v_mfma_f32_32x32x16_bf16 v[0:15], v[104:107], v[118:121], v[0:15]
	v_add_f32_e32 v104, v135, v98
	v_add_f32_e32 v99, v136, v99
	v_add_f32_e32 v117, v137, v104
	ds_read_b128 v[104:107], v211 offset:27712
	v_add_f32_e32 v130, v139, v99
	v_cvt_pk_bf16_f32 v98, v135, v136
	v_cvt_pk_bf16_f32 v99, v137, v139
	s_waitcnt lgkmcnt(3)
	v_mfma_f32_32x32x16_bf16 v[16:31], v[122:125], v[118:121], v[16:31]
	s_waitcnt lgkmcnt(2)
	v_mfma_f32_32x32x16_bf16 v[0:15], v[108:111], v[112:115], v[0:15]
	ds_read_b128 v[108:111], v211 offset:32320
	s_waitcnt lgkmcnt(2)
	v_mfma_f32_32x32x16_bf16 v[16:31], v[126:129], v[112:115], v[16:31]
	ds_read_b128 v[112:115], v211 offset:27744
	ds_read_b128 v[118:121], v211 offset:32352
	s_waitcnt lgkmcnt(3)
	v_mfma_f32_32x32x16_bf16 v[0:15], v[104:107], v[100:103], v[0:15]
	s_waitcnt lgkmcnt(2)
	v_mfma_f32_32x32x16_bf16 v[16:31], v[108:111], v[100:103], v[16:31]
	s_waitcnt lgkmcnt(1)
	v_mfma_f32_32x32x16_bf16 v[0:15], v[112:115], v[96:99], v[0:15]
	v_add_f32_e32 v221, v117, v130
	v_cmp_lt_f32_e32 vcc, s58, v221
	v_add_f32_e32 v116, v116, v221
	s_waitcnt lgkmcnt(0)
	v_mfma_f32_32x32x16_bf16 v[16:31], v[118:121], v[96:99], v[16:31]
	s_waitcnt vmcnt(0)
	s_add_u32 s10, s10, 0x400
	s_addc_u32 s11, s11, 0
	v_lshl_add_u64 v[200:201], v[200:201], 0, v[168:169]
	s_cmpk_lt_u32 s16, 0x78
	v_lshl_add_u64 v[196:197], v[196:197], 0, v[198:199]
	s_barrier
	s_cbranch_scc0 .LBB0_873

.LBB0_905:
	ds_read_b128 v[118:121], v181 offset:13344
	ds_read_b128 v[122:125], v181 offset:20000
	s_waitcnt lgkmcnt(3)
	v_mfma_f32_32x32x16_bf16 v[128:143], v[96:99], v[144:147], v[32:47]
	v_exp_f32_e32 v117, v80
	v_exp_f32_e32 v126, v81
	v_exp_f32_e32 v127, v82
	v_exp_f32_e32 v213, v83
	ds_read_b128 v[80:83], v181 offset:13376
	v_exp_f32_e32 v214, v84
	v_exp_f32_e32 v215, v85
	s_waitcnt lgkmcnt(3)
	v_mfma_f32_32x32x16_bf16 v[96:111], v[112:115], v[144:147], v[32:47]
	ds_read_b128 v[112:115], v181 offset:20032
	s_waitcnt lgkmcnt(3)
	v_mfma_f32_32x32x16_bf16 v[128:143], v[118:121], v[148:151], v[128:143]
	v_exp_f32_e32 v216, v86
	v_exp_f32_e32 v217, v88
	v_add_f32_e32 v88, v127, v117
	v_add_f32_e32 v86, v213, v126
	s_waitcnt lgkmcnt(2)
	v_mfma_f32_32x32x16_bf16 v[96:111], v[122:125], v[148:151], v[96:111]
	v_cvt_pk_bf16_f32 v84, v117, v126
	v_add_f32_e32 v117, v214, v88
	v_add_f32_e32 v122, v215, v86
	v_exp_f32_e32 v87, v87
	v_exp_f32_e32 v218, v89
	v_exp_f32_e32 v219, v90
	v_exp_f32_e32 v220, v91
	ds_read_b128 v[88:91], v181 offset:13408
	ds_read_b128 v[118:121], v181 offset:20064
	v_cvt_pk_bf16_f32 v85, v127, v213
	v_cvt_pk_bf16_f32 v86, v214, v215
	s_waitcnt lgkmcnt(3)
	v_mfma_f32_32x32x16_bf16 v[128:143], v[80:83], v[152:155], v[128:143]
	v_add_f32_e32 v80, v216, v117
	v_add_f32_e32 v81, v87, v122
	v_add_f32_e32 v82, v217, v80
	v_add_f32_e32 v81, v218, v81
	v_add_f32_e32 v82, v219, v82
	v_add_f32_e32 v83, v220, v81
	s_waitcnt lgkmcnt(2)
	v_mfma_f32_32x32x16_bf16 v[96:111], v[112:115], v[152:155], v[96:111]
	v_exp_f32_e32 v123, v92
	v_exp_f32_e32 v124, v93
	v_exp_f32_e32 v125, v94
	v_exp_f32_e32 v126, v95
	ds_read_b128 v[92:95], v181 offset:13440
	ds_read_b128 v[112:115], v181 offset:20096
	v_cvt_pk_bf16_f32 v87, v216, v87
	v_cvt_pk_bf16_f32 v80, v217, v218
	v_cvt_pk_bf16_f32 v81, v219, v220
	s_waitcnt lgkmcnt(3)
	v_mfma_f32_32x32x16_bf16 v[128:143], v[88:91], v[156:159], v[128:143]
	v_exp_f32_e32 v117, v64
	v_exp_f32_e32 v122, v65
	v_add_f32_e32 v64, v123, v82
	v_add_f32_e32 v65, v124, v83
	v_exp_f32_e32 v214, v68
	v_exp_f32_e32 v215, v69
	s_waitcnt lgkmcnt(2)
	v_mfma_f32_32x32x16_bf16 v[96:111], v[118:121], v[156:159], v[96:111]
	v_add_f32_e32 v68, v125, v64
	v_add_f32_e32 v69, v126, v65
	v_exp_f32_e32 v127, v66
	v_exp_f32_e32 v213, v67
	ds_read_b128 v[64:67], v181 offset:13472
	ds_read_b128 v[88:91], v181 offset:20128
	v_cvt_pk_bf16_f32 v82, v123, v124
	v_cvt_pk_bf16_f32 v83, v125, v126
	s_waitcnt lgkmcnt(3)
	v_mfma_f32_32x32x16_bf16 v[128:143], v[92:95], v[160:163], v[128:143]
	v_exp_f32_e32 v118, v70
	v_add_f32_e32 v70, v117, v68
	v_add_f32_e32 v69, v122, v69
	v_exp_f32_e32 v119, v72
	v_add_f32_e32 v70, v127, v70
	v_add_f32_e32 v72, v213, v69
	s_waitcnt lgkmcnt(2)
	v_mfma_f32_32x32x16_bf16 v[96:111], v[112:115], v[160:163], v[96:111]
	v_add_f32_e32 v112, v214, v70
	v_add_f32_e32 v113, v215, v72
	v_exp_f32_e32 v71, v71
	v_exp_f32_e32 v120, v73
	v_exp_f32_e32 v121, v74
	v_exp_f32_e32 v123, v75
	ds_read_b128 v[72:75], v210 offset:53248
	ds_read_b128 v[92:95], v210 offset:57856
	v_cvt_pk_bf16_f32 v68, v117, v122
	v_cvt_pk_bf16_f32 v69, v127, v213
	v_cvt_pk_bf16_f32 v70, v214, v215
	s_waitcnt lgkmcnt(3)
	v_mfma_f32_32x32x16_bf16 v[128:143], v[64:67], v[164:167], v[128:143]
	v_add_f32_e32 v64, v118, v112
	v_add_f32_e32 v65, v71, v113
	v_add_f32_e32 v66, v119, v64
	v_add_f32_e32 v65, v120, v65
	v_add_f32_e32 v66, v121, v66
	v_add_f32_e32 v67, v123, v65
	s_waitcnt lgkmcnt(2)
	v_mfma_f32_32x32x16_bf16 v[96:111], v[88:91], v[164:167], v[96:111]
	v_exp_f32_e32 v114, v76
	v_exp_f32_e32 v115, v77
	v_exp_f32_e32 v117, v78
	v_exp_f32_e32 v122, v79
	ds_read_b128 v[76:79], v210 offset:53280
	ds_read_b128 v[88:91], v210 offset:57888
	v_cvt_pk_bf16_f32 v71, v118, v71
	v_cvt_pk_bf16_f32 v64, v119, v120
	v_cvt_pk_bf16_f32 v65, v121, v123
	s_waitcnt lgkmcnt(3)
	v_mfma_f32_32x32x16_bf16 v[0:15], v[72:75], v[84:87], v[0:15]
	v_add_f32_e32 v72, v114, v66
	v_add_f32_e32 v67, v115, v67
	v_add_f32_e32 v112, v117, v72
	ds_read_b128 v[72:75], v210 offset:53312
	v_add_f32_e32 v113, v122, v67
	v_cvt_pk_bf16_f32 v66, v114, v115
	v_cvt_pk_bf16_f32 v67, v117, v122
	s_waitcnt lgkmcnt(3)
	v_mfma_f32_32x32x16_bf16 v[16:31], v[92:95], v[84:87], v[16:31]
	s_waitcnt lgkmcnt(2)
	v_mfma_f32_32x32x16_bf16 v[0:15], v[76:79], v[80:83], v[0:15]
	ds_read_b128 v[76:79], v210 offset:57920
	s_waitcnt lgkmcnt(2)
	v_mfma_f32_32x32x16_bf16 v[16:31], v[88:91], v[80:83], v[16:31]
	ds_read_b128 v[80:83], v210 offset:53344
	ds_read_b128 v[88:91], v210 offset:57952
	s_waitcnt lgkmcnt(3)
	v_mfma_f32_32x32x16_bf16 v[0:15], v[72:75], v[68:71], v[0:15]
	s_waitcnt lgkmcnt(2)
	v_mfma_f32_32x32x16_bf16 v[16:31], v[76:79], v[68:71], v[16:31]
	s_waitcnt lgkmcnt(1)
	v_mfma_f32_32x32x16_bf16 v[0:15], v[80:83], v[64:67], v[0:15]
	v_add_f32_e32 v221, v112, v113
	v_cmp_lt_f32_e32 vcc, s58, v221
	v_add_f32_e32 v86, v116, v221
	s_waitcnt lgkmcnt(0)
	v_mfma_f32_32x32x16_bf16 v[16:31], v[88:91], v[64:67], v[16:31]
	ds_read_b128 v[64:67], v181 offset:26624
	ds_read_b128 v[80:83], v181 offset:33280
	s_cbranch_vccz .LBB0_907
	v_mov_b32_e32 v222, v221
	v_mov_b32_e32 v223, v221
	s_nop 1
	v_permlane32_swap_b32_e32 v222, v223
	v_add_f32_e32 v222, v222, v223
	v_log_f32_e32 v222, v222
	s_nop 0
	v_max_f32_e32 v33, 0, v222
	v_exp_f32_e64 v34, -v33
	v_add_f32_e32 v212, v212, v33
	v_xor_b32_e32 v32, 0x80000000, v212
	v_sub_f32_e32 v143, v143, v33
	v_pk_mul_f32 v[14:15], v[14:15], v[34:35] op_sel_hi:[1,0]
	v_pk_mul_f32 v[12:13], v[12:13], v[34:35] op_sel_hi:[1,0]
	v_pk_mul_f32 v[10:11], v[10:11], v[34:35] op_sel_hi:[1,0]
	v_pk_mul_f32 v[8:9], v[8:9], v[34:35] op_sel_hi:[1,0]
	v_pk_mul_f32 v[6:7], v[6:7], v[34:35] op_sel_hi:[1,0]
	v_pk_mul_f32 v[4:5], v[4:5], v[34:35] op_sel_hi:[1,0]
	v_pk_mul_f32 v[2:3], v[2:3], v[34:35] op_sel_hi:[1,0]
	v_pk_mul_f32 v[0:1], v[0:1], v[34:35] op_sel_hi:[1,0]
	v_pk_mul_f32 v[30:31], v[30:31], v[34:35] op_sel_hi:[1,0]
	v_pk_mul_f32 v[28:29], v[28:29], v[34:35] op_sel_hi:[1,0]
	v_pk_mul_f32 v[26:27], v[26:27], v[34:35] op_sel_hi:[1,0]
	v_pk_mul_f32 v[24:25], v[24:25], v[34:35] op_sel_hi:[1,0]
	v_pk_mul_f32 v[22:23], v[22:23], v[34:35] op_sel_hi:[1,0]
	v_pk_mul_f32 v[20:21], v[20:21], v[34:35] op_sel_hi:[1,0]
	v_pk_mul_f32 v[18:19], v[18:19], v[34:35] op_sel_hi:[1,0]
	v_pk_mul_f32 v[16:17], v[16:17], v[34:35] op_sel_hi:[1,0]
	v_sub_f32_e32 v142, v142, v33
	v_sub_f32_e32 v141, v141, v33
	v_sub_f32_e32 v140, v140, v33
	v_sub_f32_e32 v139, v139, v33
	v_sub_f32_e32 v138, v138, v33
	v_sub_f32_e32 v137, v137, v33
	v_sub_f32_e32 v136, v136, v33
	v_sub_f32_e32 v135, v135, v33
	v_sub_f32_e32 v134, v134, v33
	v_sub_f32_e32 v133, v133, v33
	v_sub_f32_e32 v132, v132, v33
	v_sub_f32_e32 v131, v131, v33
	v_sub_f32_e32 v130, v130, v33
	v_sub_f32_e32 v129, v129, v33
	v_sub_f32_e32 v128, v128, v33
	v_sub_f32_e32 v111, v111, v33
	v_sub_f32_e32 v110, v110, v33
	v_sub_f32_e32 v109, v109, v33
	v_sub_f32_e32 v108, v108, v33
	v_sub_f32_e32 v107, v107, v33
	v_sub_f32_e32 v106, v106, v33
	v_sub_f32_e32 v105, v105, v33
	v_sub_f32_e32 v104, v104, v33
	v_sub_f32_e32 v103, v103, v33
	v_sub_f32_e32 v102, v102, v33
	v_sub_f32_e32 v101, v101, v33
	v_sub_f32_e32 v100, v100, v33
	v_sub_f32_e32 v99, v99, v33
	v_sub_f32_e32 v98, v98, v33
	v_sub_f32_e32 v97, v97, v33
	v_sub_f32_e32 v96, v96, v33
	v_mul_f32_e32 v86, v86, v34
	v_mov_b32_e32 v33, v32
	v_mov_b32_e32 v34, v32
	v_mov_b32_e32 v35, v32
	v_mov_b32_e32 v36, v32
	v_mov_b32_e32 v37, v32
	v_mov_b32_e32 v38, v32
	v_mov_b32_e32 v39, v32
	v_mov_b32_e32 v40, v32
	v_mov_b32_e32 v41, v32
	v_mov_b32_e32 v42, v32
	v_mov_b32_e32 v43, v32
	v_mov_b32_e32 v44, v32
	v_mov_b32_e32 v45, v32
	v_mov_b32_e32 v46, v32
	v_mov_b32_e32 v47, v32
	v_mov_b32_e32 v48, v32
	v_mov_b32_e32 v49, v32
	v_mov_b32_e32 v50, v32
	v_mov_b32_e32 v51, v32
	v_mov_b32_e32 v52, v32
	v_mov_b32_e32 v53, v32
	v_mov_b32_e32 v54, v32
	v_mov_b32_e32 v55, v32
	v_mov_b32_e32 v56, v32
	v_mov_b32_e32 v57, v32
	v_mov_b32_e32 v58, v32
	v_mov_b32_e32 v59, v32
	v_mov_b32_e32 v60, v32
	v_mov_b32_e32 v61, v32
	v_mov_b32_e32 v62, v32
	v_mov_b32_e32 v63, v32

.LBB0_911:
	ds_read_b128 v[88:91], v181 offset:26656
	ds_read_b128 v[92:95], v181 offset:33312
	s_waitcnt lgkmcnt(3)
	v_mfma_f32_32x32x16_bf16 v[112:127], v[64:67], v[144:147], v[32:47]
	v_exp_f32_e32 v87, v128
	v_exp_f32_e32 v213, v129
	v_exp_f32_e32 v214, v130
	v_exp_f32_e32 v215, v131
	v_exp_f32_e32 v132, v132
	v_exp_f32_e32 v133, v133
	s_waitcnt lgkmcnt(2)
	v_mfma_f32_32x32x16_bf16 v[64:79], v[80:83], v[144:147], v[32:47]
	ds_read_b128 v[80:83], v181 offset:26688
	ds_read_b128 v[128:131], v181 offset:33344
	s_waitcnt lgkmcnt(3)
	v_mfma_f32_32x32x16_bf16 v[112:127], v[88:91], v[148:151], v[112:127]
	v_cvt_pk_bf16_f32 v88, v87, v213
	v_add_f32_e32 v87, v214, v87
	v_add_f32_e32 v90, v215, v213
	v_add_f32_e32 v87, v132, v87
	s_waitcnt lgkmcnt(2)
	v_mfma_f32_32x32x16_bf16 v[64:79], v[92:95], v[148:151], v[64:79]
	ds_read_b128 v[92:95], v181 offset:26720
	v_add_f32_e32 v91, v133, v90
	v_exp_f32_e32 v216, v134
	v_exp_f32_e32 v217, v135
	v_exp_f32_e32 v136, v136
	v_exp_f32_e32 v137, v137
	v_exp_f32_e32 v138, v138
	v_exp_f32_e32 v139, v139
	v_cvt_pk_bf16_f32 v89, v214, v215
	v_cvt_pk_bf16_f32 v90, v132, v133
	ds_read_b128 v[132:135], v181 offset:33376
	s_waitcnt lgkmcnt(3)
	v_mfma_f32_32x32x16_bf16 v[112:127], v[80:83], v[152:155], v[112:127]
	v_add_f32_e32 v80, v216, v87
	v_add_f32_e32 v81, v217, v91
	v_add_f32_e32 v82, v136, v80
	v_add_f32_e32 v81, v137, v81
	v_add_f32_e32 v82, v138, v82
	v_add_f32_e32 v83, v139, v81
	s_waitcnt lgkmcnt(2)
	v_mfma_f32_32x32x16_bf16 v[64:79], v[128:131], v[152:155], v[64:79]
	ds_read_b128 v[128:131], v181 offset:26752
	v_exp_f32_e32 v140, v140
	v_exp_f32_e32 v141, v141
	v_exp_f32_e32 v142, v142
	v_exp_f32_e32 v143, v143
	v_cvt_pk_bf16_f32 v91, v216, v217
	v_cvt_pk_bf16_f32 v80, v136, v137
	v_cvt_pk_bf16_f32 v81, v138, v139
	ds_read_b128 v[136:139], v181 offset:33408
	s_waitcnt lgkmcnt(3)
	v_mfma_f32_32x32x16_bf16 v[112:127], v[92:95], v[156:159], v[112:127]
	v_exp_f32_e32 v87, v96
	v_add_f32_e32 v92, v140, v82
	v_add_f32_e32 v83, v141, v83
	v_exp_f32_e32 v216, v100
	v_exp_f32_e32 v217, v101
	v_add_f32_e32 v100, v142, v92
	ds_read_b128 v[92:95], v181 offset:26784
	s_waitcnt lgkmcnt(3)
	v_mfma_f32_32x32x16_bf16 v[64:79], v[132:135], v[156:159], v[64:79]
	v_add_f32_e32 v101, v143, v83
	v_exp_f32_e32 v213, v97
	v_exp_f32_e32 v214, v98
	v_exp_f32_e32 v215, v99
	ds_read_b128 v[96:99], v181 offset:33440
	v_cvt_pk_bf16_f32 v82, v140, v141
	v_cvt_pk_bf16_f32 v83, v142, v143
	s_waitcnt lgkmcnt(3)
	v_mfma_f32_32x32x16_bf16 v[112:127], v[128:131], v[160:163], v[112:127]
	v_exp_f32_e32 v132, v102
	v_add_f32_e32 v102, v87, v100
	v_add_f32_e32 v101, v213, v101
	v_cvt_pk_bf16_f32 v100, v87, v213
	v_add_f32_e32 v87, v214, v102
	v_add_f32_e32 v102, v215, v101
	s_waitcnt lgkmcnt(2)
	v_mfma_f32_32x32x16_bf16 v[64:79], v[136:139], v[160:163], v[64:79]
	v_add_f32_e32 v87, v216, v87
	v_add_f32_e32 v136, v217, v102
	v_exp_f32_e32 v103, v103
	v_exp_f32_e32 v133, v104
	v_exp_f32_e32 v134, v105
	v_exp_f32_e32 v135, v106
	v_exp_f32_e32 v140, v107
	ds_read_b128 v[104:107], v210 offset:62464
	ds_read_b128 v[128:131], v211 offset:13824
	v_cvt_pk_bf16_f32 v101, v214, v215
	v_cvt_pk_bf16_f32 v102, v216, v217
	s_waitcnt lgkmcnt(3)
	v_mfma_f32_32x32x16_bf16 v[112:127], v[92:95], v[164:167], v[112:127]
	v_add_f32_e32 v87, v132, v87
	v_add_f32_e32 v92, v103, v136
	v_add_f32_e32 v87, v133, v87
	v_add_f32_e32 v93, v134, v92
	v_add_f32_e32 v87, v135, v87
	v_add_f32_e32 v94, v140, v93
	s_waitcnt lgkmcnt(2)
	v_mfma_f32_32x32x16_bf16 v[64:79], v[96:99], v[164:167], v[64:79]
	ds_read_b128 v[96:99], v210 offset:62496
	v_exp_f32_e32 v137, v108
	v_exp_f32_e32 v138, v109
	v_exp_f32_e32 v139, v110
	v_exp_f32_e32 v141, v111
	ds_read_b128 v[108:111], v211 offset:13856
	v_cvt_pk_bf16_f32 v103, v132, v103
	v_cvt_pk_bf16_f32 v92, v133, v134
	v_cvt_pk_bf16_f32 v93, v135, v140
	s_waitcnt lgkmcnt(3)
	v_mfma_f32_32x32x16_bf16 v[0:15], v[104:107], v[88:91], v[0:15]
	v_add_f32_e32 v87, v137, v87
	v_add_f32_e32 v95, v138, v94
	v_add_f32_e32 v132, v139, v87
	v_add_f32_e32 v133, v141, v95
	v_cvt_pk_bf16_f32 v94, v137, v138
	v_cvt_pk_bf16_f32 v95, v139, v141
	s_waitcnt lgkmcnt(2)
	v_mfma_f32_32x32x16_bf16 v[16:31], v[128:131], v[88:91], v[16:31]
	ds_read_b128 v[88:91], v210 offset:62528
	s_waitcnt lgkmcnt(2)
	v_mfma_f32_32x32x16_bf16 v[0:15], v[96:99], v[80:83], v[0:15]
	ds_read_b128 v[96:99], v211 offset:13888
	s_waitcnt lgkmcnt(2)
	v_mfma_f32_32x32x16_bf16 v[16:31], v[108:111], v[80:83], v[16:31]
	ds_read_b128 v[80:83], v210 offset:62560
	ds_read_b128 v[104:107], v211 offset:13920
	s_waitcnt lgkmcnt(3)
	v_mfma_f32_32x32x16_bf16 v[0:15], v[88:91], v[100:103], v[0:15]
	s_waitcnt lgkmcnt(2)
	v_mfma_f32_32x32x16_bf16 v[16:31], v[96:99], v[100:103], v[16:31]
	s_waitcnt lgkmcnt(1)
	v_mfma_f32_32x32x16_bf16 v[0:15], v[80:83], v[92:95], v[0:15]
	v_add_f32_e32 v221, v132, v133
	v_cmp_lt_f32_e32 vcc, s58, v221
	v_add_f32_e32 v102, v86, v221
	s_waitcnt lgkmcnt(0)
	v_mfma_f32_32x32x16_bf16 v[16:31], v[104:107], v[92:95], v[16:31]
	s_waitcnt vmcnt(0)
	s_barrier
	ds_read_b128 v[80:83], v181 offset:39936
	ds_read_b128 v[96:99], v181 offset:46592
	s_cbranch_vccz .LBB0_913
	v_mov_b32_e32 v222, v221
	v_mov_b32_e32 v223, v221
	s_nop 1
	v_permlane32_swap_b32_e32 v222, v223
	v_add_f32_e32 v222, v222, v223
	v_log_f32_e32 v222, v222
	s_nop 0
	v_max_f32_e32 v33, 0, v222
	v_exp_f32_e64 v34, -v33
	v_add_f32_e32 v212, v212, v33
	v_xor_b32_e32 v32, 0x80000000, v212
	v_sub_f32_e32 v127, v127, v33
	v_pk_mul_f32 v[14:15], v[14:15], v[34:35] op_sel_hi:[1,0]
	v_pk_mul_f32 v[12:13], v[12:13], v[34:35] op_sel_hi:[1,0]
	v_pk_mul_f32 v[10:11], v[10:11], v[34:35] op_sel_hi:[1,0]
	v_pk_mul_f32 v[8:9], v[8:9], v[34:35] op_sel_hi:[1,0]
	v_pk_mul_f32 v[6:7], v[6:7], v[34:35] op_sel_hi:[1,0]
	v_pk_mul_f32 v[4:5], v[4:5], v[34:35] op_sel_hi:[1,0]
	v_pk_mul_f32 v[2:3], v[2:3], v[34:35] op_sel_hi:[1,0]
	v_pk_mul_f32 v[0:1], v[0:1], v[34:35] op_sel_hi:[1,0]
	v_pk_mul_f32 v[30:31], v[30:31], v[34:35] op_sel_hi:[1,0]
	v_pk_mul_f32 v[28:29], v[28:29], v[34:35] op_sel_hi:[1,0]
	v_pk_mul_f32 v[26:27], v[26:27], v[34:35] op_sel_hi:[1,0]
	v_pk_mul_f32 v[24:25], v[24:25], v[34:35] op_sel_hi:[1,0]
	v_pk_mul_f32 v[22:23], v[22:23], v[34:35] op_sel_hi:[1,0]
	v_pk_mul_f32 v[20:21], v[20:21], v[34:35] op_sel_hi:[1,0]
	v_pk_mul_f32 v[18:19], v[18:19], v[34:35] op_sel_hi:[1,0]
	v_pk_mul_f32 v[16:17], v[16:17], v[34:35] op_sel_hi:[1,0]
	v_sub_f32_e32 v126, v126, v33
	v_sub_f32_e32 v125, v125, v33
	v_sub_f32_e32 v124, v124, v33
	v_sub_f32_e32 v123, v123, v33
	v_sub_f32_e32 v122, v122, v33
	v_sub_f32_e32 v121, v121, v33
	v_sub_f32_e32 v120, v120, v33
	v_sub_f32_e32 v119, v119, v33
	v_sub_f32_e32 v118, v118, v33
	v_sub_f32_e32 v117, v117, v33
	v_sub_f32_e32 v116, v116, v33
	v_sub_f32_e32 v115, v115, v33
	v_sub_f32_e32 v114, v114, v33
	v_sub_f32_e32 v113, v113, v33
	v_sub_f32_e32 v112, v112, v33
	v_sub_f32_e32 v79, v79, v33
	v_sub_f32_e32 v78, v78, v33
	v_sub_f32_e32 v77, v77, v33
	v_sub_f32_e32 v76, v76, v33
	v_sub_f32_e32 v75, v75, v33
	v_sub_f32_e32 v74, v74, v33
	v_sub_f32_e32 v73, v73, v33
	v_sub_f32_e32 v72, v72, v33
	v_sub_f32_e32 v71, v71, v33
	v_sub_f32_e32 v70, v70, v33
	v_sub_f32_e32 v69, v69, v33
	v_sub_f32_e32 v68, v68, v33
	v_sub_f32_e32 v67, v67, v33
	v_sub_f32_e32 v66, v66, v33
	v_sub_f32_e32 v65, v65, v33
	v_sub_f32_e32 v64, v64, v33
	v_mul_f32_e32 v102, v102, v34
	v_mov_b32_e32 v33, v32
	v_mov_b32_e32 v34, v32
	v_mov_b32_e32 v35, v32
	v_mov_b32_e32 v36, v32
	v_mov_b32_e32 v37, v32
	v_mov_b32_e32 v38, v32
	v_mov_b32_e32 v39, v32
	v_mov_b32_e32 v40, v32
	v_mov_b32_e32 v41, v32
	v_mov_b32_e32 v42, v32
	v_mov_b32_e32 v43, v32
	v_mov_b32_e32 v44, v32
	v_mov_b32_e32 v45, v32
	v_mov_b32_e32 v46, v32
	v_mov_b32_e32 v47, v32
	v_mov_b32_e32 v48, v32
	v_mov_b32_e32 v49, v32
	v_mov_b32_e32 v50, v32
	v_mov_b32_e32 v51, v32
	v_mov_b32_e32 v52, v32
	v_mov_b32_e32 v53, v32
	v_mov_b32_e32 v54, v32
	v_mov_b32_e32 v55, v32
	v_mov_b32_e32 v56, v32
	v_mov_b32_e32 v57, v32
	v_mov_b32_e32 v58, v32
	v_mov_b32_e32 v59, v32
	v_mov_b32_e32 v60, v32
	v_mov_b32_e32 v61, v32
	v_mov_b32_e32 v62, v32
	v_mov_b32_e32 v63, v32

.LBB0_917:
	ds_read_b128 v[104:107], v181 offset:39968
	ds_read_b128 v[108:111], v181 offset:46624
	s_waitcnt lgkmcnt(3)
	v_mfma_f32_32x32x16_bf16 v[128:143], v[80:83], v[144:147], v[32:47]
	v_exp_f32_e32 v103, v112
	v_exp_f32_e32 v213, v113
	v_exp_f32_e32 v214, v114
	v_exp_f32_e32 v215, v115
	v_exp_f32_e32 v116, v116
	v_exp_f32_e32 v117, v117
	s_waitcnt lgkmcnt(2)
	v_mfma_f32_32x32x16_bf16 v[80:95], v[96:99], v[144:147], v[32:47]
	ds_read_b128 v[96:99], v181 offset:40000
	ds_read_b128 v[112:115], v181 offset:46656
	s_waitcnt lgkmcnt(3)
	v_mfma_f32_32x32x16_bf16 v[128:143], v[104:107], v[148:151], v[128:143]
	v_cvt_pk_bf16_f32 v104, v103, v213
	v_add_f32_e32 v103, v214, v103
	v_add_f32_e32 v106, v215, v213
	v_add_f32_e32 v103, v116, v103
	s_waitcnt lgkmcnt(2)
	v_mfma_f32_32x32x16_bf16 v[80:95], v[108:111], v[148:151], v[80:95]
	ds_read_b128 v[108:111], v181 offset:40032
	v_add_f32_e32 v107, v117, v106
	v_exp_f32_e32 v216, v118
	v_exp_f32_e32 v217, v119
	v_exp_f32_e32 v120, v120
	v_exp_f32_e32 v121, v121
	v_exp_f32_e32 v122, v122
	v_exp_f32_e32 v123, v123
	v_cvt_pk_bf16_f32 v105, v214, v215
	v_cvt_pk_bf16_f32 v106, v116, v117
	ds_read_b128 v[116:119], v181 offset:46688
	s_waitcnt lgkmcnt(3)
	v_mfma_f32_32x32x16_bf16 v[128:143], v[96:99], v[152:155], v[128:143]
	v_add_f32_e32 v96, v216, v103
	v_add_f32_e32 v97, v217, v107
	v_add_f32_e32 v98, v120, v96
	v_add_f32_e32 v97, v121, v97
	v_add_f32_e32 v98, v122, v98
	v_add_f32_e32 v99, v123, v97
	s_waitcnt lgkmcnt(2)
	v_mfma_f32_32x32x16_bf16 v[80:95], v[112:115], v[152:155], v[80:95]
	ds_read_b128 v[112:115], v181 offset:40064
	v_exp_f32_e32 v124, v124
	v_exp_f32_e32 v125, v125
	v_exp_f32_e32 v126, v126
	v_exp_f32_e32 v127, v127
	v_cvt_pk_bf16_f32 v107, v216, v217
	v_cvt_pk_bf16_f32 v96, v120, v121
	v_cvt_pk_bf16_f32 v97, v122, v123
	ds_read_b128 v[120:123], v181 offset:46720
	s_waitcnt lgkmcnt(3)
	v_mfma_f32_32x32x16_bf16 v[128:143], v[108:111], v[156:159], v[128:143]
	v_exp_f32_e32 v103, v64
	v_exp_f32_e32 v213, v65
	v_add_f32_e32 v64, v124, v98
	v_add_f32_e32 v65, v125, v99
	v_exp_f32_e32 v216, v68
	v_exp_f32_e32 v217, v69
	s_waitcnt lgkmcnt(2)
	v_mfma_f32_32x32x16_bf16 v[80:95], v[116:119], v[156:159], v[80:95]
	v_add_f32_e32 v68, v126, v64
	v_add_f32_e32 v69, v127, v65
	v_exp_f32_e32 v214, v66
	v_exp_f32_e32 v215, v67
	ds_read_b128 v[64:67], v181 offset:40096
	ds_read_b128 v[108:111], v181 offset:46752
	v_cvt_pk_bf16_f32 v98, v124, v125
	v_cvt_pk_bf16_f32 v99, v126, v127
	s_waitcnt lgkmcnt(3)
	v_mfma_f32_32x32x16_bf16 v[128:143], v[112:115], v[160:163], v[128:143]
	v_exp_f32_e32 v118, v73
	v_exp_f32_e32 v116, v70
	v_add_f32_e32 v70, v103, v68
	v_add_f32_e32 v69, v213, v69
	v_exp_f32_e32 v117, v72
	v_add_f32_e32 v70, v214, v70
	s_waitcnt lgkmcnt(2)
	v_mfma_f32_32x32x16_bf16 v[80:95], v[120:123], v[160:163], v[80:95]
	v_add_f32_e32 v72, v215, v69
	v_cvt_pk_bf16_f32 v68, v103, v213
	v_add_f32_e32 v103, v216, v70
	v_add_f32_e32 v120, v217, v72
	v_exp_f32_e32 v71, v71
	v_exp_f32_e32 v119, v74
	v_exp_f32_e32 v124, v75
	ds_read_b128 v[72:75], v211 offset:18432
	ds_read_b128 v[112:115], v211 offset:23040
	v_cvt_pk_bf16_f32 v69, v214, v215
	v_cvt_pk_bf16_f32 v70, v216, v217
	s_waitcnt lgkmcnt(3)
	v_mfma_f32_32x32x16_bf16 v[128:143], v[64:67], v[164:167], v[128:143]
	v_add_f32_e32 v64, v116, v103
	v_add_f32_e32 v65, v71, v120
	v_add_f32_e32 v66, v117, v64
	v_add_f32_e32 v65, v118, v65
	v_add_f32_e32 v66, v119, v66
	v_add_f32_e32 v67, v124, v65
	s_waitcnt lgkmcnt(2)
	v_mfma_f32_32x32x16_bf16 v[80:95], v[108:111], v[164:167], v[80:95]
	v_exp_f32_e32 v121, v76
	v_exp_f32_e32 v122, v77
	v_exp_f32_e32 v123, v78
	v_exp_f32_e32 v125, v79
	ds_read_b128 v[76:79], v211 offset:18464
	ds_read_b128 v[108:111], v211 offset:23072
	v_cvt_pk_bf16_f32 v71, v116, v71
	v_cvt_pk_bf16_f32 v64, v117, v118
	v_cvt_pk_bf16_f32 v65, v119, v124
	s_waitcnt lgkmcnt(3)
	v_mfma_f32_32x32x16_bf16 v[0:15], v[72:75], v[104:107], v[0:15]
	v_add_f32_e32 v72, v121, v66
	v_add_f32_e32 v67, v122, v67
	v_add_f32_e32 v103, v123, v72
	ds_read_b128 v[72:75], v211 offset:18496
	v_add_f32_e32 v116, v125, v67
	v_cvt_pk_bf16_f32 v66, v121, v122
	v_cvt_pk_bf16_f32 v67, v123, v125
	s_waitcnt lgkmcnt(3)
	v_mfma_f32_32x32x16_bf16 v[16:31], v[112:115], v[104:107], v[16:31]
	s_waitcnt lgkmcnt(2)
	v_mfma_f32_32x32x16_bf16 v[0:15], v[76:79], v[96:99], v[0:15]
	ds_read_b128 v[76:79], v211 offset:23104
	s_waitcnt lgkmcnt(2)
	v_mfma_f32_32x32x16_bf16 v[16:31], v[108:111], v[96:99], v[16:31]
	ds_read_b128 v[96:99], v211 offset:18528
	ds_read_b128 v[104:107], v211 offset:23136
	s_waitcnt lgkmcnt(3)
	v_mfma_f32_32x32x16_bf16 v[0:15], v[72:75], v[68:71], v[0:15]
	s_waitcnt lgkmcnt(2)
	v_mfma_f32_32x32x16_bf16 v[16:31], v[76:79], v[68:71], v[16:31]
	s_waitcnt lgkmcnt(1)
	v_mfma_f32_32x32x16_bf16 v[0:15], v[96:99], v[64:67], v[0:15]
	v_add_f32_e32 v221, v103, v116
	v_cmp_lt_f32_e32 vcc, s58, v221
	v_add_f32_e32 v118, v102, v221
	s_waitcnt lgkmcnt(0)
	v_mfma_f32_32x32x16_bf16 v[16:31], v[104:107], v[64:67], v[16:31]
	ds_read_b128 v[64:67], v181
	ds_read_b128 v[112:115], v181 offset:6656
	s_cbranch_vccz .LBB0_919
	v_mov_b32_e32 v222, v221
	v_mov_b32_e32 v223, v221
	s_nop 1
	v_permlane32_swap_b32_e32 v222, v223
	v_add_f32_e32 v222, v222, v223
	v_log_f32_e32 v222, v222
	s_nop 0
	v_max_f32_e32 v33, 0, v222
	v_exp_f32_e64 v34, -v33
	v_add_f32_e32 v212, v212, v33
	v_xor_b32_e32 v32, 0x80000000, v212
	v_sub_f32_e32 v143, v143, v33
	v_pk_mul_f32 v[14:15], v[14:15], v[34:35] op_sel_hi:[1,0]
	v_pk_mul_f32 v[12:13], v[12:13], v[34:35] op_sel_hi:[1,0]
	v_pk_mul_f32 v[10:11], v[10:11], v[34:35] op_sel_hi:[1,0]
	v_pk_mul_f32 v[8:9], v[8:9], v[34:35] op_sel_hi:[1,0]
	v_pk_mul_f32 v[6:7], v[6:7], v[34:35] op_sel_hi:[1,0]
	v_pk_mul_f32 v[4:5], v[4:5], v[34:35] op_sel_hi:[1,0]
	v_pk_mul_f32 v[2:3], v[2:3], v[34:35] op_sel_hi:[1,0]
	v_pk_mul_f32 v[0:1], v[0:1], v[34:35] op_sel_hi:[1,0]
	v_pk_mul_f32 v[30:31], v[30:31], v[34:35] op_sel_hi:[1,0]
	v_pk_mul_f32 v[28:29], v[28:29], v[34:35] op_sel_hi:[1,0]
	v_pk_mul_f32 v[26:27], v[26:27], v[34:35] op_sel_hi:[1,0]
	v_pk_mul_f32 v[24:25], v[24:25], v[34:35] op_sel_hi:[1,0]
	v_pk_mul_f32 v[22:23], v[22:23], v[34:35] op_sel_hi:[1,0]
	v_pk_mul_f32 v[20:21], v[20:21], v[34:35] op_sel_hi:[1,0]
	v_pk_mul_f32 v[18:19], v[18:19], v[34:35] op_sel_hi:[1,0]
	v_pk_mul_f32 v[16:17], v[16:17], v[34:35] op_sel_hi:[1,0]
	v_sub_f32_e32 v142, v142, v33
	v_sub_f32_e32 v141, v141, v33
	v_sub_f32_e32 v140, v140, v33
	v_sub_f32_e32 v139, v139, v33
	v_sub_f32_e32 v138, v138, v33
	v_sub_f32_e32 v137, v137, v33
	v_sub_f32_e32 v136, v136, v33
	v_sub_f32_e32 v135, v135, v33
	v_sub_f32_e32 v134, v134, v33
	v_sub_f32_e32 v133, v133, v33
	v_sub_f32_e32 v132, v132, v33
	v_sub_f32_e32 v131, v131, v33
	v_sub_f32_e32 v130, v130, v33
	v_sub_f32_e32 v129, v129, v33
	v_sub_f32_e32 v128, v128, v33
	v_sub_f32_e32 v95, v95, v33
	v_sub_f32_e32 v94, v94, v33
	v_sub_f32_e32 v93, v93, v33
	v_sub_f32_e32 v92, v92, v33
	v_sub_f32_e32 v91, v91, v33
	v_sub_f32_e32 v90, v90, v33
	v_sub_f32_e32 v89, v89, v33
	v_sub_f32_e32 v88, v88, v33
	v_sub_f32_e32 v87, v87, v33
	v_sub_f32_e32 v86, v86, v33
	v_sub_f32_e32 v85, v85, v33
	v_sub_f32_e32 v84, v84, v33
	v_sub_f32_e32 v83, v83, v33
	v_sub_f32_e32 v82, v82, v33
	v_sub_f32_e32 v81, v81, v33
	v_sub_f32_e32 v80, v80, v33
	v_mul_f32_e32 v118, v118, v34
	v_mov_b32_e32 v33, v32
	v_mov_b32_e32 v34, v32
	v_mov_b32_e32 v35, v32
	v_mov_b32_e32 v36, v32
	v_mov_b32_e32 v37, v32
	v_mov_b32_e32 v38, v32
	v_mov_b32_e32 v39, v32
	v_mov_b32_e32 v40, v32
	v_mov_b32_e32 v41, v32
	v_mov_b32_e32 v42, v32
	v_mov_b32_e32 v43, v32
	v_mov_b32_e32 v44, v32
	v_mov_b32_e32 v45, v32
	v_mov_b32_e32 v46, v32
	v_mov_b32_e32 v47, v32
	v_mov_b32_e32 v48, v32
	v_mov_b32_e32 v49, v32
	v_mov_b32_e32 v50, v32
	v_mov_b32_e32 v51, v32
	v_mov_b32_e32 v52, v32
	v_mov_b32_e32 v53, v32
	v_mov_b32_e32 v54, v32
	v_mov_b32_e32 v55, v32
	v_mov_b32_e32 v56, v32
	v_mov_b32_e32 v57, v32
	v_mov_b32_e32 v58, v32
	v_mov_b32_e32 v59, v32
	v_mov_b32_e32 v60, v32
	v_mov_b32_e32 v61, v32
	v_mov_b32_e32 v62, v32
	v_mov_b32_e32 v63, v32

.LBB0_923:
	ds_read_b128 v[120:123], v181 offset:32
	ds_read_b128 v[124:127], v181 offset:6688
	s_waitcnt lgkmcnt(3)
	v_mfma_f32_32x32x16_bf16 v[96:111], v[64:67], v[144:147], v[32:47]
	v_exp_f32_e32 v119, v128
	v_exp_f32_e32 v213, v129
	v_exp_f32_e32 v214, v130
	v_exp_f32_e32 v215, v131
	v_exp_f32_e32 v132, v132
	v_exp_f32_e32 v133, v133
	s_waitcnt lgkmcnt(2)
	v_mfma_f32_32x32x16_bf16 v[64:79], v[112:115], v[144:147], v[32:47]
	ds_read_b128 v[112:115], v181 offset:64
	ds_read_b128 v[128:131], v181 offset:6720
	s_waitcnt lgkmcnt(3)
	v_mfma_f32_32x32x16_bf16 v[96:111], v[120:123], v[148:151], v[96:111]
	v_cvt_pk_bf16_f32 v120, v119, v213
	v_add_f32_e32 v119, v214, v119
	v_add_f32_e32 v122, v215, v213
	v_add_f32_e32 v119, v132, v119
	s_waitcnt lgkmcnt(2)
	v_mfma_f32_32x32x16_bf16 v[64:79], v[124:127], v[148:151], v[64:79]
	ds_read_b128 v[124:127], v181 offset:96
	v_add_f32_e32 v123, v133, v122
	v_exp_f32_e32 v216, v134
	v_exp_f32_e32 v217, v135
	v_exp_f32_e32 v136, v136
	v_exp_f32_e32 v137, v137
	v_exp_f32_e32 v138, v138
	v_exp_f32_e32 v139, v139
	v_cvt_pk_bf16_f32 v121, v214, v215
	v_cvt_pk_bf16_f32 v122, v132, v133
	ds_read_b128 v[132:135], v181 offset:6752
	s_waitcnt lgkmcnt(3)
	v_mfma_f32_32x32x16_bf16 v[96:111], v[112:115], v[152:155], v[96:111]
	v_add_f32_e32 v112, v216, v119
	v_add_f32_e32 v113, v217, v123
	v_add_f32_e32 v114, v136, v112
	v_add_f32_e32 v113, v137, v113
	v_add_f32_e32 v114, v138, v114
	v_add_f32_e32 v115, v139, v113
	s_waitcnt lgkmcnt(2)
	v_mfma_f32_32x32x16_bf16 v[64:79], v[128:131], v[152:155], v[64:79]
	ds_read_b128 v[128:131], v181 offset:128
	v_exp_f32_e32 v140, v140
	v_exp_f32_e32 v141, v141
	v_exp_f32_e32 v142, v142
	v_exp_f32_e32 v143, v143
	v_cvt_pk_bf16_f32 v123, v216, v217
	v_cvt_pk_bf16_f32 v112, v136, v137
	v_cvt_pk_bf16_f32 v113, v138, v139
	ds_read_b128 v[136:139], v181 offset:6784
	s_waitcnt lgkmcnt(3)
	v_mfma_f32_32x32x16_bf16 v[96:111], v[124:127], v[156:159], v[96:111]
	v_exp_f32_e32 v119, v80
	v_exp_f32_e32 v213, v81
	v_add_f32_e32 v80, v140, v114
	v_add_f32_e32 v81, v141, v115
	v_exp_f32_e32 v216, v84
	v_exp_f32_e32 v217, v85
	s_waitcnt lgkmcnt(2)
	v_mfma_f32_32x32x16_bf16 v[64:79], v[132:135], v[156:159], v[64:79]
	v_add_f32_e32 v84, v142, v80
	v_add_f32_e32 v85, v143, v81
	v_exp_f32_e32 v214, v82
	v_exp_f32_e32 v215, v83
	ds_read_b128 v[80:83], v181 offset:160
	ds_read_b128 v[124:127], v181 offset:6816
	v_cvt_pk_bf16_f32 v114, v140, v141
	v_cvt_pk_bf16_f32 v115, v142, v143
	s_waitcnt lgkmcnt(3)
	v_mfma_f32_32x32x16_bf16 v[96:111], v[128:131], v[160:163], v[96:111]
	v_exp_f32_e32 v132, v86
	v_add_f32_e32 v86, v119, v84
	v_add_f32_e32 v85, v213, v85
	v_exp_f32_e32 v133, v88
	v_add_f32_e32 v86, v214, v86
	v_add_f32_e32 v88, v215, v85
	s_waitcnt lgkmcnt(2)
	v_mfma_f32_32x32x16_bf16 v[64:79], v[136:139], v[160:163], v[64:79]
	v_cvt_pk_bf16_f32 v84, v119, v213
	v_add_f32_e32 v119, v216, v86
	v_add_f32_e32 v136, v217, v88
	v_exp_f32_e32 v87, v87
	v_exp_f32_e32 v134, v89
	v_exp_f32_e32 v135, v90
	v_exp_f32_e32 v140, v91
	ds_read_b128 v[88:91], v211 offset:27648
	ds_read_b128 v[128:131], v211 offset:32256
	v_cvt_pk_bf16_f32 v85, v214, v215
	v_cvt_pk_bf16_f32 v86, v216, v217
	s_waitcnt lgkmcnt(3)
	v_mfma_f32_32x32x16_bf16 v[96:111], v[80:83], v[164:167], v[96:111]
	v_add_f32_e32 v80, v132, v119
	v_add_f32_e32 v81, v87, v136
	v_add_f32_e32 v82, v133, v80
	v_add_f32_e32 v81, v134, v81
	v_add_f32_e32 v82, v135, v82
	v_add_f32_e32 v83, v140, v81
	s_waitcnt lgkmcnt(2)
	v_mfma_f32_32x32x16_bf16 v[64:79], v[124:127], v[164:167], v[64:79]
	v_exp_f32_e32 v137, v92
	v_exp_f32_e32 v138, v93
	v_exp_f32_e32 v139, v94
	v_exp_f32_e32 v141, v95
	ds_read_b128 v[92:95], v211 offset:27680
	ds_read_b128 v[124:127], v211 offset:32288
	v_cvt_pk_bf16_f32 v87, v132, v87
	v_cvt_pk_bf16_f32 v80, v133, v134
	v_cvt_pk_bf16_f32 v81, v135, v140
	s_waitcnt lgkmcnt(3)
	v_mfma_f32_32x32x16_bf16 v[0:15], v[88:91], v[120:123], v[0:15]
	v_add_f32_e32 v88, v137, v82
	v_add_f32_e32 v83, v138, v83
	v_add_f32_e32 v119, v139, v88
	ds_read_b128 v[88:91], v211 offset:27712
	v_add_f32_e32 v132, v141, v83
	v_cvt_pk_bf16_f32 v82, v137, v138
	v_cvt_pk_bf16_f32 v83, v139, v141
	s_waitcnt lgkmcnt(3)
	v_mfma_f32_32x32x16_bf16 v[16:31], v[128:131], v[120:123], v[16:31]
	s_waitcnt lgkmcnt(2)
	v_mfma_f32_32x32x16_bf16 v[0:15], v[92:95], v[112:115], v[0:15]
	ds_read_b128 v[92:95], v211 offset:32320
	s_waitcnt lgkmcnt(2)
	v_mfma_f32_32x32x16_bf16 v[16:31], v[124:127], v[112:115], v[16:31]
	ds_read_b128 v[112:115], v211 offset:27744
	ds_read_b128 v[120:123], v211 offset:32352
	s_waitcnt lgkmcnt(3)
	v_mfma_f32_32x32x16_bf16 v[0:15], v[88:91], v[84:87], v[0:15]
	s_waitcnt lgkmcnt(2)
	v_mfma_f32_32x32x16_bf16 v[16:31], v[92:95], v[84:87], v[16:31]
	s_waitcnt lgkmcnt(1)
	v_mfma_f32_32x32x16_bf16 v[0:15], v[112:115], v[80:83], v[0:15]
	v_add_f32_e32 v221, v119, v132
	v_cmp_lt_f32_e32 vcc, s58, v221
	v_add_f32_e32 v118, v118, v221
	s_waitcnt lgkmcnt(0)
	v_mfma_f32_32x32x16_bf16 v[16:31], v[120:123], v[80:83], v[16:31]
	s_waitcnt vmcnt(0)
	s_barrier
	ds_read_b128 v[80:83], v181 offset:13312
	ds_read_b128 v[112:115], v181 offset:19968
	s_cbranch_vccz .LBB0_925
	v_mov_b32_e32 v222, v221
	v_mov_b32_e32 v223, v221
	s_nop 1
	v_permlane32_swap_b32_e32 v222, v223
	v_add_f32_e32 v222, v222, v223
	v_log_f32_e32 v222, v222
	s_nop 0
	v_max_f32_e32 v33, 0, v222
	v_exp_f32_e64 v34, -v33
	v_add_f32_e32 v212, v212, v33
	v_xor_b32_e32 v32, 0x80000000, v212
	v_sub_f32_e32 v111, v111, v33
	v_pk_mul_f32 v[14:15], v[14:15], v[34:35] op_sel_hi:[1,0]
	v_pk_mul_f32 v[12:13], v[12:13], v[34:35] op_sel_hi:[1,0]
	v_pk_mul_f32 v[10:11], v[10:11], v[34:35] op_sel_hi:[1,0]
	v_pk_mul_f32 v[8:9], v[8:9], v[34:35] op_sel_hi:[1,0]
	v_pk_mul_f32 v[6:7], v[6:7], v[34:35] op_sel_hi:[1,0]
	v_pk_mul_f32 v[4:5], v[4:5], v[34:35] op_sel_hi:[1,0]
	v_pk_mul_f32 v[2:3], v[2:3], v[34:35] op_sel_hi:[1,0]
	v_pk_mul_f32 v[0:1], v[0:1], v[34:35] op_sel_hi:[1,0]
	v_pk_mul_f32 v[30:31], v[30:31], v[34:35] op_sel_hi:[1,0]
	v_pk_mul_f32 v[28:29], v[28:29], v[34:35] op_sel_hi:[1,0]
	v_pk_mul_f32 v[26:27], v[26:27], v[34:35] op_sel_hi:[1,0]
	v_pk_mul_f32 v[24:25], v[24:25], v[34:35] op_sel_hi:[1,0]
	v_pk_mul_f32 v[22:23], v[22:23], v[34:35] op_sel_hi:[1,0]
	v_pk_mul_f32 v[20:21], v[20:21], v[34:35] op_sel_hi:[1,0]
	v_pk_mul_f32 v[18:19], v[18:19], v[34:35] op_sel_hi:[1,0]
	v_pk_mul_f32 v[16:17], v[16:17], v[34:35] op_sel_hi:[1,0]
	v_sub_f32_e32 v110, v110, v33
	v_sub_f32_e32 v109, v109, v33
	v_sub_f32_e32 v108, v108, v33
	v_sub_f32_e32 v107, v107, v33
	v_sub_f32_e32 v106, v106, v33
	v_sub_f32_e32 v105, v105, v33
	v_sub_f32_e32 v104, v104, v33
	v_sub_f32_e32 v103, v103, v33
	v_sub_f32_e32 v102, v102, v33
	v_sub_f32_e32 v101, v101, v33
	v_sub_f32_e32 v100, v100, v33
	v_sub_f32_e32 v99, v99, v33
	v_sub_f32_e32 v98, v98, v33
	v_sub_f32_e32 v97, v97, v33
	v_sub_f32_e32 v96, v96, v33
	v_sub_f32_e32 v79, v79, v33
	v_sub_f32_e32 v78, v78, v33
	v_sub_f32_e32 v77, v77, v33
	v_sub_f32_e32 v76, v76, v33
	v_sub_f32_e32 v75, v75, v33
	v_sub_f32_e32 v74, v74, v33
	v_sub_f32_e32 v73, v73, v33
	v_sub_f32_e32 v72, v72, v33
	v_sub_f32_e32 v71, v71, v33
	v_sub_f32_e32 v70, v70, v33
	v_sub_f32_e32 v69, v69, v33
	v_sub_f32_e32 v68, v68, v33
	v_sub_f32_e32 v67, v67, v33
	v_sub_f32_e32 v66, v66, v33
	v_sub_f32_e32 v65, v65, v33
	v_sub_f32_e32 v64, v64, v33
	v_mul_f32_e32 v118, v118, v34
	v_mov_b32_e32 v33, v32
	v_mov_b32_e32 v34, v32
	v_mov_b32_e32 v35, v32
	v_mov_b32_e32 v36, v32
	v_mov_b32_e32 v37, v32
	v_mov_b32_e32 v38, v32
	v_mov_b32_e32 v39, v32
	v_mov_b32_e32 v40, v32
	v_mov_b32_e32 v41, v32
	v_mov_b32_e32 v42, v32
	v_mov_b32_e32 v43, v32
	v_mov_b32_e32 v44, v32
	v_mov_b32_e32 v45, v32
	v_mov_b32_e32 v46, v32
	v_mov_b32_e32 v47, v32
	v_mov_b32_e32 v48, v32
	v_mov_b32_e32 v49, v32
	v_mov_b32_e32 v50, v32
	v_mov_b32_e32 v51, v32
	v_mov_b32_e32 v52, v32
	v_mov_b32_e32 v53, v32
	v_mov_b32_e32 v54, v32
	v_mov_b32_e32 v55, v32
	v_mov_b32_e32 v56, v32
	v_mov_b32_e32 v57, v32
	v_mov_b32_e32 v58, v32
	v_mov_b32_e32 v59, v32
	v_mov_b32_e32 v60, v32
	v_mov_b32_e32 v61, v32
	v_mov_b32_e32 v62, v32
	v_mov_b32_e32 v63, v32

.LBB0_929:
	ds_read_b128 v[138:141], v181 offset:13344
	ds_read_b128 v[214:217], v181 offset:20000
	s_waitcnt lgkmcnt(3)
	v_mfma_f32_32x32x16_bf16 v[122:137], v[80:83], v[144:147], v[32:47]
	v_exp_f32_e32 v116, v96
	v_exp_f32_e32 v117, v97
	v_exp_f32_e32 v119, v98
	v_exp_f32_e32 v120, v99
	ds_read_b128 v[96:99], v181 offset:13376
	v_exp_f32_e32 v121, v100
	v_exp_f32_e32 v142, v101
	s_waitcnt lgkmcnt(3)
	v_mfma_f32_32x32x16_bf16 v[80:95], v[112:115], v[144:147], v[32:47]
	ds_read_b128 v[112:115], v181 offset:20032
	s_waitcnt lgkmcnt(3)
	v_mfma_f32_32x32x16_bf16 v[122:137], v[138:141], v[148:151], v[122:137]
	v_exp_f32_e32 v143, v102
	v_exp_f32_e32 v213, v104
	v_add_f32_e32 v104, v119, v116
	v_add_f32_e32 v102, v120, v117
	s_waitcnt lgkmcnt(2)
	v_mfma_f32_32x32x16_bf16 v[80:95], v[214:217], v[148:151], v[80:95]
	v_cvt_pk_bf16_f32 v100, v116, v117
	v_add_f32_e32 v116, v121, v104
	v_add_f32_e32 v117, v142, v102
	v_exp_f32_e32 v103, v103
	v_exp_f32_e32 v218, v105
	v_exp_f32_e32 v219, v106
	v_exp_f32_e32 v220, v107
	ds_read_b128 v[104:107], v181 offset:13408
	ds_read_b128 v[138:141], v181 offset:20064
	v_cvt_pk_bf16_f32 v101, v119, v120
	v_cvt_pk_bf16_f32 v102, v121, v142
	s_waitcnt lgkmcnt(3)
	v_mfma_f32_32x32x16_bf16 v[122:137], v[96:99], v[152:155], v[122:137]
	v_add_f32_e32 v96, v143, v116
	v_add_f32_e32 v97, v103, v117
	v_add_f32_e32 v98, v213, v96
	v_add_f32_e32 v97, v218, v97
	v_add_f32_e32 v98, v219, v98
	v_add_f32_e32 v99, v220, v97
	s_waitcnt lgkmcnt(2)
	v_mfma_f32_32x32x16_bf16 v[80:95], v[112:115], v[152:155], v[80:95]
	v_exp_f32_e32 v119, v108
	v_exp_f32_e32 v120, v109
	v_exp_f32_e32 v121, v110
	v_exp_f32_e32 v142, v111
	ds_read_b128 v[108:111], v181 offset:13440
	ds_read_b128 v[112:115], v181 offset:20096
	v_cvt_pk_bf16_f32 v103, v143, v103
	v_cvt_pk_bf16_f32 v96, v213, v218
	v_cvt_pk_bf16_f32 v97, v219, v220
	s_waitcnt lgkmcnt(3)
	v_mfma_f32_32x32x16_bf16 v[122:137], v[104:107], v[156:159], v[122:137]
	v_exp_f32_e32 v116, v64
	v_exp_f32_e32 v117, v65
	v_add_f32_e32 v64, v119, v98
	v_add_f32_e32 v65, v120, v99
	v_exp_f32_e32 v214, v68
	v_exp_f32_e32 v215, v69
	s_waitcnt lgkmcnt(2)
	v_mfma_f32_32x32x16_bf16 v[80:95], v[138:141], v[156:159], v[80:95]
	v_add_f32_e32 v68, v121, v64
	v_add_f32_e32 v69, v142, v65
	v_exp_f32_e32 v143, v66
	v_exp_f32_e32 v213, v67
	ds_read_b128 v[64:67], v181 offset:13472
	ds_read_b128 v[104:107], v181 offset:20128
	v_cvt_pk_bf16_f32 v98, v119, v120
	v_cvt_pk_bf16_f32 v99, v121, v142
	s_waitcnt lgkmcnt(3)
	v_mfma_f32_32x32x16_bf16 v[122:137], v[108:111], v[160:163], v[122:137]
	v_exp_f32_e32 v119, v70
	v_add_f32_e32 v70, v116, v68
	v_add_f32_e32 v69, v117, v69
	v_exp_f32_e32 v120, v72
	v_add_f32_e32 v70, v143, v70
	v_add_f32_e32 v72, v213, v69
	s_waitcnt lgkmcnt(2)
	v_mfma_f32_32x32x16_bf16 v[80:95], v[112:115], v[160:163], v[80:95]
	v_add_f32_e32 v112, v214, v70
	v_add_f32_e32 v113, v215, v72
	v_exp_f32_e32 v71, v71
	v_exp_f32_e32 v121, v73
	v_exp_f32_e32 v138, v74
	v_exp_f32_e32 v139, v75
	ds_read_b128 v[72:75], v210 offset:53248
	ds_read_b128 v[108:111], v210 offset:57856
	v_cvt_pk_bf16_f32 v68, v116, v117
	v_cvt_pk_bf16_f32 v69, v143, v213
	v_cvt_pk_bf16_f32 v70, v214, v215
	s_waitcnt lgkmcnt(3)
	v_mfma_f32_32x32x16_bf16 v[122:137], v[64:67], v[164:167], v[122:137]
	v_add_f32_e32 v64, v119, v112
	v_add_f32_e32 v65, v71, v113
	v_add_f32_e32 v66, v120, v64
	v_add_f32_e32 v65, v121, v65
	v_add_f32_e32 v66, v138, v66
	v_add_f32_e32 v67, v139, v65
	s_waitcnt lgkmcnt(2)
	v_mfma_f32_32x32x16_bf16 v[80:95], v[104:107], v[164:167], v[80:95]
	v_exp_f32_e32 v114, v76
	v_exp_f32_e32 v115, v77
	v_exp_f32_e32 v116, v78
	v_exp_f32_e32 v117, v79
	ds_read_b128 v[76:79], v210 offset:53280
	ds_read_b128 v[104:107], v210 offset:57888
	v_cvt_pk_bf16_f32 v71, v119, v71
	v_cvt_pk_bf16_f32 v64, v120, v121
	v_cvt_pk_bf16_f32 v65, v138, v139
	s_waitcnt lgkmcnt(3)
	v_mfma_f32_32x32x16_bf16 v[0:15], v[72:75], v[100:103], v[0:15]
	v_add_f32_e32 v72, v114, v66
	v_add_f32_e32 v67, v115, v67
	v_add_f32_e32 v112, v116, v72
	ds_read_b128 v[72:75], v210 offset:53312
	v_add_f32_e32 v113, v117, v67
	v_cvt_pk_bf16_f32 v66, v114, v115
	v_cvt_pk_bf16_f32 v67, v116, v117
	s_waitcnt lgkmcnt(3)
	v_mfma_f32_32x32x16_bf16 v[16:31], v[108:111], v[100:103], v[16:31]
	s_waitcnt lgkmcnt(2)
	v_mfma_f32_32x32x16_bf16 v[0:15], v[76:79], v[96:99], v[0:15]
	ds_read_b128 v[76:79], v210 offset:57920
	s_waitcnt lgkmcnt(2)
	v_mfma_f32_32x32x16_bf16 v[16:31], v[104:107], v[96:99], v[16:31]
	ds_read_b128 v[96:99], v210 offset:53344
	ds_read_b128 v[102:105], v210 offset:57952
	s_waitcnt lgkmcnt(3)
	v_mfma_f32_32x32x16_bf16 v[0:15], v[72:75], v[68:71], v[0:15]
	s_waitcnt lgkmcnt(2)
	v_mfma_f32_32x32x16_bf16 v[16:31], v[76:79], v[68:71], v[16:31]
	s_waitcnt lgkmcnt(1)
	v_mfma_f32_32x32x16_bf16 v[0:15], v[96:99], v[64:67], v[0:15]
	v_add_f32_e32 v221, v112, v113
	v_cmp_lt_f32_e32 vcc, s58, v221
	v_add_f32_e32 v100, v118, v221
	s_waitcnt lgkmcnt(0)
	v_mfma_f32_32x32x16_bf16 v[16:31], v[102:105], v[64:67], v[16:31]
	ds_read_b128 v[64:67], v181 offset:26624
	ds_read_b128 v[96:99], v181 offset:33280
	s_cbranch_vccz .LBB0_931
	v_mov_b32_e32 v222, v221
	v_mov_b32_e32 v223, v221
	s_nop 1
	v_permlane32_swap_b32_e32 v222, v223
	v_add_f32_e32 v222, v222, v223
	v_log_f32_e32 v222, v222
	s_nop 0
	v_max_f32_e32 v33, 0, v222
	v_exp_f32_e64 v34, -v33
	v_add_f32_e32 v212, v212, v33
	v_xor_b32_e32 v32, 0x80000000, v212
	v_sub_f32_e32 v137, v137, v33
	v_pk_mul_f32 v[14:15], v[14:15], v[34:35] op_sel_hi:[1,0]
	v_pk_mul_f32 v[12:13], v[12:13], v[34:35] op_sel_hi:[1,0]
	v_pk_mul_f32 v[10:11], v[10:11], v[34:35] op_sel_hi:[1,0]
	v_pk_mul_f32 v[8:9], v[8:9], v[34:35] op_sel_hi:[1,0]
	v_pk_mul_f32 v[6:7], v[6:7], v[34:35] op_sel_hi:[1,0]
	v_pk_mul_f32 v[4:5], v[4:5], v[34:35] op_sel_hi:[1,0]
	v_pk_mul_f32 v[2:3], v[2:3], v[34:35] op_sel_hi:[1,0]
	v_pk_mul_f32 v[0:1], v[0:1], v[34:35] op_sel_hi:[1,0]
	v_pk_mul_f32 v[30:31], v[30:31], v[34:35] op_sel_hi:[1,0]
	v_pk_mul_f32 v[28:29], v[28:29], v[34:35] op_sel_hi:[1,0]
	v_pk_mul_f32 v[26:27], v[26:27], v[34:35] op_sel_hi:[1,0]
	v_pk_mul_f32 v[24:25], v[24:25], v[34:35] op_sel_hi:[1,0]
	v_pk_mul_f32 v[22:23], v[22:23], v[34:35] op_sel_hi:[1,0]
	v_pk_mul_f32 v[20:21], v[20:21], v[34:35] op_sel_hi:[1,0]
	v_pk_mul_f32 v[18:19], v[18:19], v[34:35] op_sel_hi:[1,0]
	v_pk_mul_f32 v[16:17], v[16:17], v[34:35] op_sel_hi:[1,0]
	v_sub_f32_e32 v136, v136, v33
	v_sub_f32_e32 v135, v135, v33
	v_sub_f32_e32 v134, v134, v33
	v_sub_f32_e32 v133, v133, v33
	v_sub_f32_e32 v132, v132, v33
	v_sub_f32_e32 v131, v131, v33
	v_sub_f32_e32 v130, v130, v33
	v_sub_f32_e32 v129, v129, v33
	v_sub_f32_e32 v128, v128, v33
	v_sub_f32_e32 v127, v127, v33
	v_sub_f32_e32 v126, v126, v33
	v_sub_f32_e32 v125, v125, v33
	v_sub_f32_e32 v124, v124, v33
	v_sub_f32_e32 v123, v123, v33
	v_sub_f32_e32 v122, v122, v33
	v_sub_f32_e32 v95, v95, v33
	v_sub_f32_e32 v94, v94, v33
	v_sub_f32_e32 v93, v93, v33
	v_sub_f32_e32 v92, v92, v33
	v_sub_f32_e32 v91, v91, v33
	v_sub_f32_e32 v90, v90, v33
	v_sub_f32_e32 v89, v89, v33
	v_sub_f32_e32 v88, v88, v33
	v_sub_f32_e32 v87, v87, v33
	v_sub_f32_e32 v86, v86, v33
	v_sub_f32_e32 v85, v85, v33
	v_sub_f32_e32 v84, v84, v33
	v_sub_f32_e32 v83, v83, v33
	v_sub_f32_e32 v82, v82, v33
	v_sub_f32_e32 v81, v81, v33
	v_sub_f32_e32 v80, v80, v33
	v_mul_f32_e32 v100, v100, v34
	v_mov_b32_e32 v33, v32
	v_mov_b32_e32 v34, v32
	v_mov_b32_e32 v35, v32
	v_mov_b32_e32 v36, v32
	v_mov_b32_e32 v37, v32
	v_mov_b32_e32 v38, v32
	v_mov_b32_e32 v39, v32
	v_mov_b32_e32 v40, v32
	v_mov_b32_e32 v41, v32
	v_mov_b32_e32 v42, v32
	v_mov_b32_e32 v43, v32
	v_mov_b32_e32 v44, v32
	v_mov_b32_e32 v45, v32
	v_mov_b32_e32 v46, v32
	v_mov_b32_e32 v47, v32
	v_mov_b32_e32 v48, v32
	v_mov_b32_e32 v49, v32
	v_mov_b32_e32 v50, v32
	v_mov_b32_e32 v51, v32
	v_mov_b32_e32 v52, v32
	v_mov_b32_e32 v53, v32
	v_mov_b32_e32 v54, v32
	v_mov_b32_e32 v55, v32
	v_mov_b32_e32 v56, v32
	v_mov_b32_e32 v57, v32
	v_mov_b32_e32 v58, v32
	v_mov_b32_e32 v59, v32
	v_mov_b32_e32 v60, v32
	v_mov_b32_e32 v61, v32
	v_mov_b32_e32 v62, v32
	v_mov_b32_e32 v63, v32

.LBB0_935:
	ds_read_b128 v[102:105], v181 offset:26656
	ds_read_b128 v[138:141], v181 offset:33312
	s_waitcnt lgkmcnt(3)
	v_mfma_f32_32x32x16_bf16 v[106:121], v[64:67], v[144:147], v[32:47]
	v_exp_f32_e32 v101, v122
	v_exp_f32_e32 v142, v123
	v_exp_f32_e32 v143, v124
	v_exp_f32_e32 v202, v125
	v_exp_f32_e32 v126, v126
	v_exp_f32_e32 v127, v127
	s_waitcnt lgkmcnt(2)
	v_mfma_f32_32x32x16_bf16 v[64:79], v[96:99], v[144:147], v[32:47]
	ds_read_b128 v[96:99], v181 offset:26688
	ds_read_b128 v[122:125], v181 offset:33344
	s_waitcnt lgkmcnt(3)
	v_mfma_f32_32x32x16_bf16 v[106:121], v[102:105], v[148:151], v[106:121]
	v_cvt_pk_bf16_f32 v102, v101, v142
	v_add_f32_e32 v101, v143, v101
	v_add_f32_e32 v104, v202, v142
	v_add_f32_e32 v101, v126, v101
	s_waitcnt lgkmcnt(2)
	v_mfma_f32_32x32x16_bf16 v[64:79], v[138:141], v[148:151], v[64:79]
	v_add_f32_e32 v105, v127, v104
	v_exp_f32_e32 v203, v128
	v_exp_f32_e32 v204, v129
	v_exp_f32_e32 v205, v130
	v_exp_f32_e32 v213, v131
	v_exp_f32_e32 v214, v132
	v_exp_f32_e32 v215, v133
	v_cvt_pk_bf16_f32 v103, v143, v202
	v_cvt_pk_bf16_f32 v104, v126, v127
	ds_read_b128 v[126:129], v181 offset:26720
	ds_read_b128 v[130:133], v181 offset:33376
	s_waitcnt lgkmcnt(3)
	v_mfma_f32_32x32x16_bf16 v[106:121], v[96:99], v[152:155], v[106:121]
	v_add_f32_e32 v96, v203, v101
	v_add_f32_e32 v97, v204, v105
	v_add_f32_e32 v98, v205, v96
	v_add_f32_e32 v97, v213, v97
	v_add_f32_e32 v98, v214, v98
	v_add_f32_e32 v99, v215, v97
	s_waitcnt lgkmcnt(2)
	v_mfma_f32_32x32x16_bf16 v[64:79], v[122:125], v[152:155], v[64:79]
	ds_read_b128 v[122:125], v181 offset:26752
	v_exp_f32_e32 v138, v134
	v_exp_f32_e32 v139, v135
	v_exp_f32_e32 v140, v136
	v_exp_f32_e32 v141, v137
	ds_read_b128 v[134:137], v181 offset:33408
	v_cvt_pk_bf16_f32 v105, v203, v204
	v_cvt_pk_bf16_f32 v96, v205, v213
	v_cvt_pk_bf16_f32 v97, v214, v215
	s_waitcnt lgkmcnt(3)
	v_mfma_f32_32x32x16_bf16 v[106:121], v[126:129], v[156:159], v[106:121]
	v_exp_f32_e32 v101, v80
	v_exp_f32_e32 v142, v81
	v_add_f32_e32 v80, v138, v98
	v_add_f32_e32 v81, v139, v99
	v_exp_f32_e32 v203, v84
	v_exp_f32_e32 v204, v85
	s_waitcnt lgkmcnt(2)
	v_mfma_f32_32x32x16_bf16 v[64:79], v[130:133], v[156:159], v[64:79]
	v_add_f32_e32 v84, v140, v80
	v_add_f32_e32 v85, v141, v81
	v_exp_f32_e32 v143, v82
	v_exp_f32_e32 v202, v83
	ds_read_b128 v[80:83], v181 offset:26784
	ds_read_b128 v[126:129], v181 offset:33440
	v_cvt_pk_bf16_f32 v98, v138, v139
	v_cvt_pk_bf16_f32 v99, v140, v141
	s_waitcnt lgkmcnt(3)
	v_mfma_f32_32x32x16_bf16 v[106:121], v[122:125], v[160:163], v[106:121]
	v_exp_f32_e32 v87, v87
	v_exp_f32_e32 v130, v86
	v_add_f32_e32 v86, v101, v84
	v_add_f32_e32 v85, v142, v85
	v_exp_f32_e32 v131, v88
	v_add_f32_e32 v86, v143, v86
	s_waitcnt lgkmcnt(2)
	v_mfma_f32_32x32x16_bf16 v[64:79], v[134:137], v[160:163], v[64:79]
	v_add_f32_e32 v88, v202, v85
	v_cvt_pk_bf16_f32 v84, v101, v142
	v_add_f32_e32 v101, v203, v86
	v_add_f32_e32 v134, v204, v88
	v_exp_f32_e32 v132, v89
	v_exp_f32_e32 v133, v90
	v_exp_f32_e32 v138, v91
	ds_read_b128 v[88:91], v210 offset:62464
	ds_read_b128 v[122:125], v211 offset:13824
	v_cvt_pk_bf16_f32 v85, v143, v202
	v_cvt_pk_bf16_f32 v86, v203, v204
	s_waitcnt lgkmcnt(3)
	v_mfma_f32_32x32x16_bf16 v[106:121], v[80:83], v[164:167], v[106:121]
	v_add_f32_e32 v80, v130, v101
	v_add_f32_e32 v81, v87, v134
	v_add_f32_e32 v82, v131, v80
	v_add_f32_e32 v81, v132, v81
	v_add_f32_e32 v82, v133, v82
	v_add_f32_e32 v83, v138, v81
	s_waitcnt lgkmcnt(2)
	v_mfma_f32_32x32x16_bf16 v[64:79], v[126:129], v[164:167], v[64:79]
	v_exp_f32_e32 v135, v92
	v_exp_f32_e32 v136, v93
	v_exp_f32_e32 v137, v94
	v_exp_f32_e32 v139, v95
	ds_read_b128 v[92:95], v210 offset:62496
	ds_read_b128 v[126:129], v211 offset:13856
	v_cvt_pk_bf16_f32 v87, v130, v87
	v_cvt_pk_bf16_f32 v80, v131, v132
	v_cvt_pk_bf16_f32 v81, v133, v138
	s_waitcnt lgkmcnt(3)
	v_mfma_f32_32x32x16_bf16 v[0:15], v[88:91], v[102:105], v[0:15]
	v_add_f32_e32 v88, v135, v82
	v_add_f32_e32 v83, v136, v83
	v_add_f32_e32 v101, v137, v88
	ds_read_b128 v[88:91], v210 offset:62528
	v_add_f32_e32 v130, v139, v83
	v_cvt_pk_bf16_f32 v82, v135, v136
	v_cvt_pk_bf16_f32 v83, v137, v139
	s_waitcnt lgkmcnt(3)
	v_mfma_f32_32x32x16_bf16 v[16:31], v[122:125], v[102:105], v[16:31]
	s_waitcnt lgkmcnt(2)
	v_mfma_f32_32x32x16_bf16 v[0:15], v[92:95], v[96:99], v[0:15]
	ds_read_b128 v[92:95], v211 offset:13888
	s_waitcnt lgkmcnt(2)
	v_mfma_f32_32x32x16_bf16 v[16:31], v[126:129], v[96:99], v[16:31]
	ds_read_b128 v[96:99], v210 offset:62560
	ds_read_b128 v[102:105], v211 offset:13920
	s_waitcnt lgkmcnt(3)
	v_mfma_f32_32x32x16_bf16 v[0:15], v[88:91], v[84:87], v[0:15]
	s_waitcnt lgkmcnt(2)
	v_mfma_f32_32x32x16_bf16 v[16:31], v[92:95], v[84:87], v[16:31]
	s_waitcnt lgkmcnt(1)
	v_mfma_f32_32x32x16_bf16 v[0:15], v[96:99], v[80:83], v[0:15]
	v_add_f32_e32 v221, v101, v130
	v_cmp_lt_f32_e32 vcc, s58, v221
	v_add_f32_e32 v88, v100, v221
	s_waitcnt lgkmcnt(0)
	v_mfma_f32_32x32x16_bf16 v[16:31], v[102:105], v[80:83], v[16:31]
	s_waitcnt vmcnt(0)
	s_barrier
	ds_read_b128 v[84:87], v181 offset:39936
	ds_read_b128 v[80:83], v181 offset:46592
	s_cbranch_vccz .LBB0_937
	v_mov_b32_e32 v222, v221
	v_mov_b32_e32 v223, v221
	s_nop 1
	v_permlane32_swap_b32_e32 v222, v223
	v_add_f32_e32 v222, v222, v223
	v_log_f32_e32 v222, v222
	s_nop 0
	v_max_f32_e32 v33, 0, v222
	v_exp_f32_e64 v34, -v33
	v_add_f32_e32 v212, v212, v33
	v_xor_b32_e32 v32, 0x80000000, v212
	v_sub_f32_e32 v121, v121, v33
	v_pk_mul_f32 v[14:15], v[14:15], v[34:35] op_sel_hi:[1,0]
	v_pk_mul_f32 v[12:13], v[12:13], v[34:35] op_sel_hi:[1,0]
	v_pk_mul_f32 v[10:11], v[10:11], v[34:35] op_sel_hi:[1,0]
	v_pk_mul_f32 v[8:9], v[8:9], v[34:35] op_sel_hi:[1,0]
	v_pk_mul_f32 v[6:7], v[6:7], v[34:35] op_sel_hi:[1,0]
	v_pk_mul_f32 v[4:5], v[4:5], v[34:35] op_sel_hi:[1,0]
	v_pk_mul_f32 v[2:3], v[2:3], v[34:35] op_sel_hi:[1,0]
	v_pk_mul_f32 v[0:1], v[0:1], v[34:35] op_sel_hi:[1,0]
	v_pk_mul_f32 v[30:31], v[30:31], v[34:35] op_sel_hi:[1,0]
	v_pk_mul_f32 v[28:29], v[28:29], v[34:35] op_sel_hi:[1,0]
	v_pk_mul_f32 v[26:27], v[26:27], v[34:35] op_sel_hi:[1,0]
	v_pk_mul_f32 v[24:25], v[24:25], v[34:35] op_sel_hi:[1,0]
	v_pk_mul_f32 v[22:23], v[22:23], v[34:35] op_sel_hi:[1,0]
	v_pk_mul_f32 v[20:21], v[20:21], v[34:35] op_sel_hi:[1,0]
	v_pk_mul_f32 v[18:19], v[18:19], v[34:35] op_sel_hi:[1,0]
	v_pk_mul_f32 v[16:17], v[16:17], v[34:35] op_sel_hi:[1,0]
	v_sub_f32_e32 v120, v120, v33
	v_sub_f32_e32 v119, v119, v33
	v_sub_f32_e32 v118, v118, v33
	v_sub_f32_e32 v117, v117, v33
	v_sub_f32_e32 v116, v116, v33
	v_sub_f32_e32 v115, v115, v33
	v_sub_f32_e32 v114, v114, v33
	v_sub_f32_e32 v113, v113, v33
	v_sub_f32_e32 v112, v112, v33
	v_sub_f32_e32 v111, v111, v33
	v_sub_f32_e32 v110, v110, v33
	v_sub_f32_e32 v109, v109, v33
	v_sub_f32_e32 v108, v108, v33
	v_sub_f32_e32 v107, v107, v33
	v_sub_f32_e32 v106, v106, v33
	v_sub_f32_e32 v79, v79, v33
	v_sub_f32_e32 v78, v78, v33
	v_sub_f32_e32 v77, v77, v33
	v_sub_f32_e32 v76, v76, v33
	v_sub_f32_e32 v75, v75, v33
	v_sub_f32_e32 v74, v74, v33
	v_sub_f32_e32 v73, v73, v33
	v_sub_f32_e32 v72, v72, v33
	v_sub_f32_e32 v71, v71, v33
	v_sub_f32_e32 v70, v70, v33
	v_sub_f32_e32 v69, v69, v33
	v_sub_f32_e32 v68, v68, v33
	v_sub_f32_e32 v67, v67, v33
	v_sub_f32_e32 v66, v66, v33
	v_sub_f32_e32 v65, v65, v33
	v_sub_f32_e32 v64, v64, v33
	v_mul_f32_e32 v88, v88, v34
	v_mov_b32_e32 v33, v32
	v_mov_b32_e32 v34, v32
	v_mov_b32_e32 v35, v32
	v_mov_b32_e32 v36, v32
	v_mov_b32_e32 v37, v32
	v_mov_b32_e32 v38, v32
	v_mov_b32_e32 v39, v32
	v_mov_b32_e32 v40, v32
	v_mov_b32_e32 v41, v32
	v_mov_b32_e32 v42, v32
	v_mov_b32_e32 v43, v32
	v_mov_b32_e32 v44, v32
	v_mov_b32_e32 v45, v32
	v_mov_b32_e32 v46, v32
	v_mov_b32_e32 v47, v32
	v_mov_b32_e32 v48, v32
	v_mov_b32_e32 v49, v32
	v_mov_b32_e32 v50, v32
	v_mov_b32_e32 v51, v32
	v_mov_b32_e32 v52, v32
	v_mov_b32_e32 v53, v32
	v_mov_b32_e32 v54, v32
	v_mov_b32_e32 v55, v32
	v_mov_b32_e32 v56, v32
	v_mov_b32_e32 v57, v32
	v_mov_b32_e32 v58, v32
	v_mov_b32_e32 v59, v32
	v_mov_b32_e32 v60, v32
	v_mov_b32_e32 v61, v32
	v_mov_b32_e32 v62, v32
	v_mov_b32_e32 v63, v32

.LBB0_941:
	s_waitcnt lgkmcnt(1)
	v_mfma_f32_32x32x16_bf16 v[122:137], v[84:87], v[144:147], v[32:47]
	ds_read_b128 v[84:87], v181 offset:39968
	ds_read_b128 v[90:93], v181 offset:46624
	v_exp_f32_e32 v89, v106
	v_exp_f32_e32 v94, v107
	v_exp_f32_e32 v95, v108
	v_exp_f32_e32 v142, v109
	v_exp_f32_e32 v143, v110
	v_exp_f32_e32 v202, v111
	s_waitcnt lgkmcnt(2)
	v_mfma_f32_32x32x16_bf16 v[96:111], v[80:83], v[144:147], v[32:47]
	ds_read_b128 v[80:83], v181 offset:40000
	ds_read_b128 v[138:141], v181 offset:46656
	s_waitcnt lgkmcnt(3)
	v_mfma_f32_32x32x16_bf16 v[122:137], v[84:87], v[148:151], v[122:137]
	v_exp_f32_e32 v116, v116
	v_add_f32_e32 v87, v95, v89
	v_add_f32_e32 v86, v142, v94
	v_cvt_pk_bf16_f32 v84, v89, v94
	s_waitcnt lgkmcnt(2)
	v_mfma_f32_32x32x16_bf16 v[96:111], v[90:93], v[148:151], v[96:111]
	ds_read_b128 v[90:93], v181 offset:40032
	v_add_f32_e32 v87, v143, v87
	v_add_f32_e32 v89, v202, v86
	v_exp_f32_e32 v203, v112
	v_exp_f32_e32 v204, v113
	v_exp_f32_e32 v205, v114
	v_exp_f32_e32 v213, v115
	ds_read_b128 v[112:115], v181 offset:46688
	v_exp_f32_e32 v117, v117
	v_cvt_pk_bf16_f32 v85, v95, v142
	v_cvt_pk_bf16_f32 v86, v143, v202
	s_waitcnt lgkmcnt(3)
	v_mfma_f32_32x32x16_bf16 v[122:137], v[80:83], v[152:155], v[122:137]
	v_add_f32_e32 v80, v203, v87
	v_add_f32_e32 v81, v204, v89
	v_add_f32_e32 v82, v205, v80
	v_add_f32_e32 v81, v213, v81
	v_add_f32_e32 v82, v116, v82
	v_add_f32_e32 v83, v117, v81
	s_waitcnt lgkmcnt(2)
	v_mfma_f32_32x32x16_bf16 v[96:111], v[138:141], v[152:155], v[96:111]
	v_exp_f32_e32 v94, v118
	v_exp_f32_e32 v95, v119
	v_exp_f32_e32 v120, v120
	v_exp_f32_e32 v121, v121
	v_cvt_pk_bf16_f32 v87, v203, v204
	v_cvt_pk_bf16_f32 v80, v205, v213
	v_cvt_pk_bf16_f32 v81, v116, v117
	ds_read_b128 v[116:119], v181 offset:40064
	ds_read_b128 v[138:141], v181 offset:46720
	s_waitcnt lgkmcnt(3)
	v_mfma_f32_32x32x16_bf16 v[122:137], v[90:93], v[156:159], v[122:137]
	v_exp_f32_e32 v89, v64
	v_exp_f32_e32 v142, v65
	v_add_f32_e32 v64, v94, v82
	v_add_f32_e32 v65, v95, v83
	v_exp_f32_e32 v203, v68
	v_exp_f32_e32 v204, v69
	s_waitcnt lgkmcnt(2)
	v_mfma_f32_32x32x16_bf16 v[96:111], v[112:115], v[156:159], v[96:111]
	v_add_f32_e32 v68, v120, v64
	v_add_f32_e32 v69, v121, v65
	v_exp_f32_e32 v143, v66
	v_exp_f32_e32 v202, v67
	ds_read_b128 v[64:67], v181 offset:40096
	ds_read_b128 v[90:93], v181 offset:46752
	v_cvt_pk_bf16_f32 v82, v94, v95
	v_cvt_pk_bf16_f32 v83, v120, v121
	s_waitcnt lgkmcnt(3)
	v_mfma_f32_32x32x16_bf16 v[122:137], v[116:119], v[160:163], v[122:137]
	v_exp_f32_e32 v116, v74
	v_exp_f32_e32 v94, v70
	v_add_f32_e32 v70, v89, v68
	v_add_f32_e32 v69, v142, v69
	v_exp_f32_e32 v95, v72
	v_add_f32_e32 v70, v143, v70
	s_waitcnt lgkmcnt(2)
	v_mfma_f32_32x32x16_bf16 v[96:111], v[138:141], v[160:163], v[96:111]
	v_add_f32_e32 v72, v202, v69
	v_cvt_pk_bf16_f32 v68, v89, v142
	v_add_f32_e32 v89, v203, v70
	v_add_f32_e32 v118, v204, v72
	v_exp_f32_e32 v71, v71
	v_exp_f32_e32 v120, v73
	v_exp_f32_e32 v117, v75
	ds_read_b128 v[72:75], v211 offset:18432
	ds_read_b128 v[112:115], v211 offset:23040
	v_cvt_pk_bf16_f32 v69, v143, v202
	v_cvt_pk_bf16_f32 v70, v203, v204
	s_waitcnt lgkmcnt(3)
	v_mfma_f32_32x32x16_bf16 v[122:137], v[64:67], v[164:167], v[122:137]
	v_add_f32_e32 v64, v94, v89
	v_add_f32_e32 v65, v71, v118
	v_add_f32_e32 v66, v95, v64
	v_add_f32_e32 v65, v120, v65
	v_add_f32_e32 v66, v116, v66
	v_add_f32_e32 v67, v117, v65
	s_waitcnt lgkmcnt(2)
	v_mfma_f32_32x32x16_bf16 v[96:111], v[90:93], v[164:167], v[96:111]
	v_exp_f32_e32 v119, v76
	v_exp_f32_e32 v121, v77
	v_exp_f32_e32 v138, v78
	v_exp_f32_e32 v139, v79
	ds_read_b128 v[76:79], v211 offset:18464
	ds_read_b128 v[90:93], v211 offset:23072
	v_cvt_pk_bf16_f32 v71, v94, v71
	v_cvt_pk_bf16_f32 v64, v95, v120
	v_cvt_pk_bf16_f32 v65, v116, v117
	s_waitcnt lgkmcnt(3)
	v_mfma_f32_32x32x16_bf16 v[0:15], v[72:75], v[84:87], v[0:15]
	v_add_f32_e32 v72, v119, v66
	v_add_f32_e32 v67, v121, v67
	v_add_f32_e32 v89, v138, v72
	ds_read_b128 v[72:75], v211 offset:18496
	v_add_f32_e32 v94, v139, v67
	v_cvt_pk_bf16_f32 v66, v119, v121
	v_cvt_pk_bf16_f32 v67, v138, v139
	s_waitcnt lgkmcnt(3)
	v_mfma_f32_32x32x16_bf16 v[16:31], v[112:115], v[84:87], v[16:31]
	s_waitcnt lgkmcnt(2)
	v_mfma_f32_32x32x16_bf16 v[0:15], v[76:79], v[80:83], v[0:15]
	ds_read_b128 v[76:79], v211 offset:23104
	s_waitcnt lgkmcnt(2)
	v_mfma_f32_32x32x16_bf16 v[16:31], v[90:93], v[80:83], v[16:31]
	ds_read_b128 v[80:83], v211 offset:18528
	ds_read_b128 v[84:87], v211 offset:23136
	s_waitcnt lgkmcnt(3)
	v_mfma_f32_32x32x16_bf16 v[0:15], v[72:75], v[68:71], v[0:15]
	s_waitcnt lgkmcnt(2)
	v_mfma_f32_32x32x16_bf16 v[16:31], v[76:79], v[68:71], v[16:31]
	s_waitcnt lgkmcnt(1)
	v_mfma_f32_32x32x16_bf16 v[0:15], v[80:83], v[64:67], v[0:15]
	v_add_f32_e32 v221, v89, v94
	v_cmp_lt_f32_e32 vcc, s58, v221
	v_add_f32_e32 v116, v88, v221
	s_waitcnt lgkmcnt(0)
	v_mfma_f32_32x32x16_bf16 v[16:31], v[84:87], v[64:67], v[16:31]
	ds_read_b128 v[64:67], v181
	ds_read_b128 v[112:115], v181 offset:6656
	s_cbranch_vccz .LBB0_943
	v_mov_b32_e32 v222, v221
	v_mov_b32_e32 v223, v221
	s_nop 1
	v_permlane32_swap_b32_e32 v222, v223
	v_add_f32_e32 v222, v222, v223
	v_log_f32_e32 v222, v222
	s_nop 0
	v_max_f32_e32 v33, 0, v222
	v_exp_f32_e64 v34, -v33
	v_add_f32_e32 v212, v212, v33
	v_xor_b32_e32 v32, 0x80000000, v212
	v_sub_f32_e32 v137, v137, v33
	v_pk_mul_f32 v[14:15], v[14:15], v[34:35] op_sel_hi:[1,0]
	v_pk_mul_f32 v[12:13], v[12:13], v[34:35] op_sel_hi:[1,0]
	v_pk_mul_f32 v[10:11], v[10:11], v[34:35] op_sel_hi:[1,0]
	v_pk_mul_f32 v[8:9], v[8:9], v[34:35] op_sel_hi:[1,0]
	v_pk_mul_f32 v[6:7], v[6:7], v[34:35] op_sel_hi:[1,0]
	v_pk_mul_f32 v[4:5], v[4:5], v[34:35] op_sel_hi:[1,0]
	v_pk_mul_f32 v[2:3], v[2:3], v[34:35] op_sel_hi:[1,0]
	v_pk_mul_f32 v[0:1], v[0:1], v[34:35] op_sel_hi:[1,0]
	v_pk_mul_f32 v[30:31], v[30:31], v[34:35] op_sel_hi:[1,0]
	v_pk_mul_f32 v[28:29], v[28:29], v[34:35] op_sel_hi:[1,0]
	v_pk_mul_f32 v[26:27], v[26:27], v[34:35] op_sel_hi:[1,0]
	v_pk_mul_f32 v[24:25], v[24:25], v[34:35] op_sel_hi:[1,0]
	v_pk_mul_f32 v[22:23], v[22:23], v[34:35] op_sel_hi:[1,0]
	v_pk_mul_f32 v[20:21], v[20:21], v[34:35] op_sel_hi:[1,0]
	v_pk_mul_f32 v[18:19], v[18:19], v[34:35] op_sel_hi:[1,0]
	v_pk_mul_f32 v[16:17], v[16:17], v[34:35] op_sel_hi:[1,0]
	v_sub_f32_e32 v136, v136, v33
	v_sub_f32_e32 v135, v135, v33
	v_sub_f32_e32 v134, v134, v33
	v_sub_f32_e32 v133, v133, v33
	v_sub_f32_e32 v132, v132, v33
	v_sub_f32_e32 v131, v131, v33
	v_sub_f32_e32 v130, v130, v33
	v_sub_f32_e32 v129, v129, v33
	v_sub_f32_e32 v128, v128, v33
	v_sub_f32_e32 v127, v127, v33
	v_sub_f32_e32 v126, v126, v33
	v_sub_f32_e32 v125, v125, v33
	v_sub_f32_e32 v124, v124, v33
	v_sub_f32_e32 v123, v123, v33
	v_sub_f32_e32 v122, v122, v33
	v_sub_f32_e32 v111, v111, v33
	v_sub_f32_e32 v110, v110, v33
	v_sub_f32_e32 v109, v109, v33
	v_sub_f32_e32 v108, v108, v33
	v_sub_f32_e32 v107, v107, v33
	v_sub_f32_e32 v106, v106, v33
	v_sub_f32_e32 v105, v105, v33
	v_sub_f32_e32 v104, v104, v33
	v_sub_f32_e32 v103, v103, v33
	v_sub_f32_e32 v102, v102, v33
	v_sub_f32_e32 v101, v101, v33
	v_sub_f32_e32 v100, v100, v33
	v_sub_f32_e32 v99, v99, v33
	v_sub_f32_e32 v98, v98, v33
	v_sub_f32_e32 v97, v97, v33
	v_sub_f32_e32 v96, v96, v33
	v_mul_f32_e32 v116, v116, v34
	v_mov_b32_e32 v33, v32
	v_mov_b32_e32 v34, v32
	v_mov_b32_e32 v35, v32
	v_mov_b32_e32 v36, v32
	v_mov_b32_e32 v37, v32
	v_mov_b32_e32 v38, v32
	v_mov_b32_e32 v39, v32
	v_mov_b32_e32 v40, v32
	v_mov_b32_e32 v41, v32
	v_mov_b32_e32 v42, v32
	v_mov_b32_e32 v43, v32
	v_mov_b32_e32 v44, v32
	v_mov_b32_e32 v45, v32
	v_mov_b32_e32 v46, v32
	v_mov_b32_e32 v47, v32
	v_mov_b32_e32 v48, v32
	v_mov_b32_e32 v49, v32
	v_mov_b32_e32 v50, v32
	v_mov_b32_e32 v51, v32
	v_mov_b32_e32 v52, v32
	v_mov_b32_e32 v53, v32
	v_mov_b32_e32 v54, v32
	v_mov_b32_e32 v55, v32
	v_mov_b32_e32 v56, v32
	v_mov_b32_e32 v57, v32
	v_mov_b32_e32 v58, v32
	v_mov_b32_e32 v59, v32
	v_mov_b32_e32 v60, v32
	v_mov_b32_e32 v61, v32
	v_mov_b32_e32 v62, v32
	v_mov_b32_e32 v63, v32

; template <bool NA>
; __device__ __forceinline__ void attn_unit(LAS unsigned char* lds, const bf16_t* Q, const bf16_t* Kg, const bf16_t* Kr, const bf16_t* Vt, bf16_t* O,
;                                           int h, int seqrow0, int q0, int t0, int NT, int rows, int g0, const float* rpb_h, int wid) {
;     ...
;         for (int t = 0; t < NT; t += 8) {
;             A_STEP(sA0, sA1, tmA, sB0, sB1, tmB, t);
;             A_STEP(sB0, sB1, tmB, sA0, sA1, tmA, t + 1);
;             A_STEP(sA0, sA1, tmA, sB0, sB1, tmB, t + 2);
;             A_STEP(sB0, sB1, tmB, sA0, sA1, tmA, t + 3);
;             A_STEP(sA0, sA1, tmA, sB0, sB1, tmB, t + 4);
;             A_STEP(sB0, sB1, tmB, sA0, sA1, tmA, t + 5);
;             A_STEP(sA0, sA1, tmA, sB0, sB1, tmB, t + 6);
;             A_STEP(sB0, sB1, tmB, sA0, sA1, tmA, t + 7);
;         }
.LBB0_970:
	ds_read_b128 v[118:121], v181 offset:32
	ds_read_b128 v[138:141], v181 offset:6688
	s_waitcnt lgkmcnt(3)
	v_mfma_f32_32x32x16_bf16 v[80:95], v[64:67], v[144:147], v[32:47]
	v_exp_f32_e32 v117, v122
	v_exp_f32_e32 v142, v123
	v_exp_f32_e32 v143, v124
	v_exp_f32_e32 v202, v125
	v_exp_f32_e32 v126, v126
	v_exp_f32_e32 v127, v127
	s_waitcnt lgkmcnt(2)
	v_mfma_f32_32x32x16_bf16 v[64:79], v[112:115], v[144:147], v[32:47]
	ds_read_b128 v[112:115], v181 offset:64
	ds_read_b128 v[122:125], v181 offset:6720
	s_waitcnt lgkmcnt(3)
	v_mfma_f32_32x32x16_bf16 v[80:95], v[118:121], v[148:151], v[80:95]
	v_cvt_pk_bf16_f32 v118, v117, v142
	v_add_f32_e32 v117, v143, v117
	v_add_f32_e32 v120, v202, v142
	v_add_f32_e32 v117, v126, v117
	s_waitcnt lgkmcnt(2)
	v_mfma_f32_32x32x16_bf16 v[64:79], v[138:141], v[148:151], v[64:79]
	v_add_f32_e32 v121, v127, v120
	v_exp_f32_e32 v203, v128
	v_exp_f32_e32 v204, v129
	v_exp_f32_e32 v205, v130
	v_exp_f32_e32 v213, v131
	v_exp_f32_e32 v214, v132
	v_exp_f32_e32 v215, v133
	v_cvt_pk_bf16_f32 v119, v143, v202
	v_cvt_pk_bf16_f32 v120, v126, v127
	ds_read_b128 v[126:129], v181 offset:96
	ds_read_b128 v[130:133], v181 offset:6752
	s_waitcnt lgkmcnt(3)
	v_mfma_f32_32x32x16_bf16 v[80:95], v[112:115], v[152:155], v[80:95]
	v_add_f32_e32 v112, v203, v117
	v_add_f32_e32 v113, v204, v121
	v_add_f32_e32 v114, v205, v112
	v_add_f32_e32 v113, v213, v113
	v_add_f32_e32 v114, v214, v114
	v_add_f32_e32 v115, v215, v113
	s_waitcnt lgkmcnt(2)
	v_mfma_f32_32x32x16_bf16 v[64:79], v[122:125], v[152:155], v[64:79]
	ds_read_b128 v[122:125], v181 offset:128
	v_exp_f32_e32 v138, v134
	v_exp_f32_e32 v139, v135
	v_exp_f32_e32 v140, v136
	v_exp_f32_e32 v141, v137
	ds_read_b128 v[134:137], v181 offset:6784
	v_cvt_pk_bf16_f32 v121, v203, v204
	v_cvt_pk_bf16_f32 v112, v205, v213
	v_cvt_pk_bf16_f32 v113, v214, v215
	s_waitcnt lgkmcnt(3)
	v_mfma_f32_32x32x16_bf16 v[80:95], v[126:129], v[156:159], v[80:95]
	v_exp_f32_e32 v117, v96
	v_exp_f32_e32 v142, v97
	v_add_f32_e32 v96, v138, v114
	v_add_f32_e32 v97, v139, v115
	v_exp_f32_e32 v203, v100
	v_exp_f32_e32 v204, v101
	s_waitcnt lgkmcnt(2)
	v_mfma_f32_32x32x16_bf16 v[64:79], v[130:133], v[156:159], v[64:79]
	v_add_f32_e32 v100, v140, v96
	v_add_f32_e32 v101, v141, v97
	v_exp_f32_e32 v143, v98
	v_exp_f32_e32 v202, v99
	ds_read_b128 v[96:99], v181 offset:160
	ds_read_b128 v[126:129], v181 offset:6816
	v_cvt_pk_bf16_f32 v114, v138, v139
	v_cvt_pk_bf16_f32 v115, v140, v141
	s_waitcnt lgkmcnt(3)
	v_mfma_f32_32x32x16_bf16 v[80:95], v[122:125], v[160:163], v[80:95]
	v_exp_f32_e32 v130, v102
	v_add_f32_e32 v102, v117, v100
	v_add_f32_e32 v101, v142, v101
	v_exp_f32_e32 v131, v104
	v_add_f32_e32 v102, v143, v102
	v_add_f32_e32 v104, v202, v101
	s_waitcnt lgkmcnt(2)
	v_mfma_f32_32x32x16_bf16 v[64:79], v[134:137], v[160:163], v[64:79]
	v_cvt_pk_bf16_f32 v100, v117, v142
	v_add_f32_e32 v117, v203, v102
	v_add_f32_e32 v134, v204, v104
	v_exp_f32_e32 v103, v103
	v_exp_f32_e32 v132, v105
	v_exp_f32_e32 v133, v106
	v_exp_f32_e32 v138, v107
	ds_read_b128 v[104:107], v211 offset:27648
	ds_read_b128 v[122:125], v211 offset:32256
	v_cvt_pk_bf16_f32 v101, v143, v202
	v_cvt_pk_bf16_f32 v102, v203, v204
	s_waitcnt lgkmcnt(3)
	v_mfma_f32_32x32x16_bf16 v[80:95], v[96:99], v[164:167], v[80:95]
	v_add_f32_e32 v96, v130, v117
	v_add_f32_e32 v97, v103, v134
	v_add_f32_e32 v98, v131, v96
	v_add_f32_e32 v97, v132, v97
	v_add_f32_e32 v98, v133, v98
	v_add_f32_e32 v99, v138, v97
	s_waitcnt lgkmcnt(2)
	v_mfma_f32_32x32x16_bf16 v[64:79], v[126:129], v[164:167], v[64:79]
	v_exp_f32_e32 v135, v108
	v_exp_f32_e32 v136, v109
	v_exp_f32_e32 v137, v110
	v_exp_f32_e32 v139, v111
	ds_read_b128 v[108:111], v211 offset:27680
	ds_read_b128 v[126:129], v211 offset:32288
	v_cvt_pk_bf16_f32 v103, v130, v103
	v_cvt_pk_bf16_f32 v96, v131, v132
	v_cvt_pk_bf16_f32 v97, v133, v138
	s_waitcnt lgkmcnt(3)
	v_mfma_f32_32x32x16_bf16 v[0:15], v[104:107], v[118:121], v[0:15]
	v_add_f32_e32 v104, v135, v98
	v_add_f32_e32 v99, v136, v99
	v_add_f32_e32 v117, v137, v104
	ds_read_b128 v[104:107], v211 offset:27712
	v_add_f32_e32 v130, v139, v99
	v_cvt_pk_bf16_f32 v98, v135, v136
	v_cvt_pk_bf16_f32 v99, v137, v139
	s_waitcnt lgkmcnt(3)
	v_mfma_f32_32x32x16_bf16 v[16:31], v[122:125], v[118:121], v[16:31]
	s_waitcnt lgkmcnt(2)
	v_mfma_f32_32x32x16_bf16 v[0:15], v[108:111], v[112:115], v[0:15]
	ds_read_b128 v[108:111], v211 offset:32320
	s_waitcnt lgkmcnt(2)
	v_mfma_f32_32x32x16_bf16 v[16:31], v[126:129], v[112:115], v[16:31]
	ds_read_b128 v[112:115], v211 offset:27744
	ds_read_b128 v[118:121], v211 offset:32352
	s_waitcnt lgkmcnt(3)
	v_mfma_f32_32x32x16_bf16 v[0:15], v[104:107], v[100:103], v[0:15]
	s_waitcnt lgkmcnt(2)
	v_mfma_f32_32x32x16_bf16 v[16:31], v[108:111], v[100:103], v[16:31]
	s_waitcnt lgkmcnt(1)
	v_mfma_f32_32x32x16_bf16 v[0:15], v[112:115], v[96:99], v[0:15]
	v_add_f32_e32 v221, v117, v130
	v_cmp_lt_f32_e32 vcc, s59, v221
	v_add_f32_e32 v116, v116, v221
	s_waitcnt lgkmcnt(0)
	v_mfma_f32_32x32x16_bf16 v[16:31], v[118:121], v[96:99], v[16:31]
	s_waitcnt vmcnt(0)
	s_add_u32 s10, s10, 0x400
	s_addc_u32 s11, s11, 0
	v_lshl_add_u64 v[200:201], v[200:201], 0, v[168:169]
	s_cmpk_lt_u32 s16, 0xf8
	v_lshl_add_u64 v[196:197], v[196:197], 0, v[198:199]
	s_barrier
	s_cbranch_scc0 .LBB0_950

.LBB0_982:
	ds_read_b128 v[118:121], v181 offset:13344
	ds_read_b128 v[122:125], v181 offset:20000
	s_waitcnt lgkmcnt(3)
	v_mfma_f32_32x32x16_bf16 v[128:143], v[96:99], v[144:147], v[32:47]
	v_exp_f32_e32 v117, v80
	v_exp_f32_e32 v126, v81
	v_exp_f32_e32 v127, v82
	v_exp_f32_e32 v213, v83
	ds_read_b128 v[80:83], v181 offset:13376
	v_exp_f32_e32 v214, v84
	v_exp_f32_e32 v215, v85
	s_waitcnt lgkmcnt(3)
	v_mfma_f32_32x32x16_bf16 v[96:111], v[112:115], v[144:147], v[32:47]
	ds_read_b128 v[112:115], v181 offset:20032
	s_waitcnt lgkmcnt(3)
	v_mfma_f32_32x32x16_bf16 v[128:143], v[118:121], v[148:151], v[128:143]
	v_exp_f32_e32 v216, v86
	v_exp_f32_e32 v217, v88
	v_add_f32_e32 v88, v127, v117
	v_add_f32_e32 v86, v213, v126
	s_waitcnt lgkmcnt(2)
	v_mfma_f32_32x32x16_bf16 v[96:111], v[122:125], v[148:151], v[96:111]
	v_cvt_pk_bf16_f32 v84, v117, v126
	v_add_f32_e32 v117, v214, v88
	v_add_f32_e32 v122, v215, v86
	v_exp_f32_e32 v87, v87
	v_exp_f32_e32 v218, v89
	v_exp_f32_e32 v219, v90
	v_exp_f32_e32 v220, v91
	ds_read_b128 v[88:91], v181 offset:13408
	ds_read_b128 v[118:121], v181 offset:20064
	v_cvt_pk_bf16_f32 v85, v127, v213
	v_cvt_pk_bf16_f32 v86, v214, v215
	s_waitcnt lgkmcnt(3)
	v_mfma_f32_32x32x16_bf16 v[128:143], v[80:83], v[152:155], v[128:143]
	v_add_f32_e32 v80, v216, v117
	v_add_f32_e32 v81, v87, v122
	v_add_f32_e32 v82, v217, v80
	v_add_f32_e32 v81, v218, v81
	v_add_f32_e32 v82, v219, v82
	v_add_f32_e32 v83, v220, v81
	s_waitcnt lgkmcnt(2)
	v_mfma_f32_32x32x16_bf16 v[96:111], v[112:115], v[152:155], v[96:111]
	v_exp_f32_e32 v123, v92
	v_exp_f32_e32 v124, v93
	v_exp_f32_e32 v125, v94
	v_exp_f32_e32 v126, v95
	ds_read_b128 v[92:95], v181 offset:13440
	ds_read_b128 v[112:115], v181 offset:20096
	v_cvt_pk_bf16_f32 v87, v216, v87
	v_cvt_pk_bf16_f32 v80, v217, v218
	v_cvt_pk_bf16_f32 v81, v219, v220
	s_waitcnt lgkmcnt(3)
	v_mfma_f32_32x32x16_bf16 v[128:143], v[88:91], v[156:159], v[128:143]
	v_exp_f32_e32 v117, v64
	v_exp_f32_e32 v122, v65
	v_add_f32_e32 v64, v123, v82
	v_add_f32_e32 v65, v124, v83
	v_exp_f32_e32 v214, v68
	v_exp_f32_e32 v215, v69
	s_waitcnt lgkmcnt(2)
	v_mfma_f32_32x32x16_bf16 v[96:111], v[118:121], v[156:159], v[96:111]
	v_add_f32_e32 v68, v125, v64
	v_add_f32_e32 v69, v126, v65
	v_exp_f32_e32 v127, v66
	v_exp_f32_e32 v213, v67
	ds_read_b128 v[64:67], v181 offset:13472
	ds_read_b128 v[88:91], v181 offset:20128
	v_cvt_pk_bf16_f32 v82, v123, v124
	v_cvt_pk_bf16_f32 v83, v125, v126
	s_waitcnt lgkmcnt(3)
	v_mfma_f32_32x32x16_bf16 v[128:143], v[92:95], v[160:163], v[128:143]
	v_exp_f32_e32 v118, v70
	v_add_f32_e32 v70, v117, v68
	v_add_f32_e32 v69, v122, v69
	v_exp_f32_e32 v119, v72
	v_add_f32_e32 v70, v127, v70
	v_add_f32_e32 v72, v213, v69
	s_waitcnt lgkmcnt(2)
	v_mfma_f32_32x32x16_bf16 v[96:111], v[112:115], v[160:163], v[96:111]
	v_add_f32_e32 v112, v214, v70
	v_add_f32_e32 v113, v215, v72
	v_exp_f32_e32 v71, v71
	v_exp_f32_e32 v120, v73
	v_exp_f32_e32 v121, v74
	v_exp_f32_e32 v123, v75
	ds_read_b128 v[72:75], v210 offset:53248
	ds_read_b128 v[92:95], v210 offset:57856
	v_cvt_pk_bf16_f32 v68, v117, v122
	v_cvt_pk_bf16_f32 v69, v127, v213
	v_cvt_pk_bf16_f32 v70, v214, v215
	s_waitcnt lgkmcnt(3)
	v_mfma_f32_32x32x16_bf16 v[128:143], v[64:67], v[164:167], v[128:143]
	v_add_f32_e32 v64, v118, v112
	v_add_f32_e32 v65, v71, v113
	v_add_f32_e32 v66, v119, v64
	v_add_f32_e32 v65, v120, v65
	v_add_f32_e32 v66, v121, v66
	v_add_f32_e32 v67, v123, v65
	s_waitcnt lgkmcnt(2)
	v_mfma_f32_32x32x16_bf16 v[96:111], v[88:91], v[164:167], v[96:111]
	v_exp_f32_e32 v114, v76
	v_exp_f32_e32 v115, v77
	v_exp_f32_e32 v117, v78
	v_exp_f32_e32 v122, v79
	ds_read_b128 v[76:79], v210 offset:53280
	ds_read_b128 v[88:91], v210 offset:57888
	v_cvt_pk_bf16_f32 v71, v118, v71
	v_cvt_pk_bf16_f32 v64, v119, v120
	v_cvt_pk_bf16_f32 v65, v121, v123
	s_waitcnt lgkmcnt(3)
	v_mfma_f32_32x32x16_bf16 v[0:15], v[72:75], v[84:87], v[0:15]
	v_add_f32_e32 v72, v114, v66
	v_add_f32_e32 v67, v115, v67
	v_add_f32_e32 v112, v117, v72
	ds_read_b128 v[72:75], v210 offset:53312
	v_add_f32_e32 v113, v122, v67
	v_cvt_pk_bf16_f32 v66, v114, v115
	v_cvt_pk_bf16_f32 v67, v117, v122
	s_waitcnt lgkmcnt(3)
	v_mfma_f32_32x32x16_bf16 v[16:31], v[92:95], v[84:87], v[16:31]
	s_waitcnt lgkmcnt(2)
	v_mfma_f32_32x32x16_bf16 v[0:15], v[76:79], v[80:83], v[0:15]
	ds_read_b128 v[76:79], v210 offset:57920
	s_waitcnt lgkmcnt(2)
	v_mfma_f32_32x32x16_bf16 v[16:31], v[88:91], v[80:83], v[16:31]
	ds_read_b128 v[80:83], v210 offset:53344
	ds_read_b128 v[88:91], v210 offset:57952
	s_waitcnt lgkmcnt(3)
	v_mfma_f32_32x32x16_bf16 v[0:15], v[72:75], v[68:71], v[0:15]
	s_waitcnt lgkmcnt(2)
	v_mfma_f32_32x32x16_bf16 v[16:31], v[76:79], v[68:71], v[16:31]
	s_waitcnt lgkmcnt(1)
	v_mfma_f32_32x32x16_bf16 v[0:15], v[80:83], v[64:67], v[0:15]
	v_add_f32_e32 v221, v112, v113
	v_cmp_lt_f32_e32 vcc, s59, v221
	v_add_f32_e32 v86, v116, v221
	s_waitcnt lgkmcnt(0)
	v_mfma_f32_32x32x16_bf16 v[16:31], v[88:91], v[64:67], v[16:31]
	ds_read_b128 v[64:67], v181 offset:26624
	ds_read_b128 v[80:83], v181 offset:33280
	s_cbranch_vccz .LBB0_984
	v_mov_b32_e32 v222, v221
	v_mov_b32_e32 v223, v221
	s_nop 1
	v_permlane32_swap_b32_e32 v222, v223
	v_add_f32_e32 v222, v222, v223
	v_log_f32_e32 v222, v222
	s_nop 0
	v_max_f32_e32 v33, 0, v222
	v_exp_f32_e64 v34, -v33
	v_add_f32_e32 v212, v212, v33
	v_xor_b32_e32 v32, 0x80000000, v212
	v_sub_f32_e32 v143, v143, v33
	v_pk_mul_f32 v[14:15], v[14:15], v[34:35] op_sel_hi:[1,0]
	v_pk_mul_f32 v[12:13], v[12:13], v[34:35] op_sel_hi:[1,0]
	v_pk_mul_f32 v[10:11], v[10:11], v[34:35] op_sel_hi:[1,0]
	v_pk_mul_f32 v[8:9], v[8:9], v[34:35] op_sel_hi:[1,0]
	v_pk_mul_f32 v[6:7], v[6:7], v[34:35] op_sel_hi:[1,0]
	v_pk_mul_f32 v[4:5], v[4:5], v[34:35] op_sel_hi:[1,0]
	v_pk_mul_f32 v[2:3], v[2:3], v[34:35] op_sel_hi:[1,0]
	v_pk_mul_f32 v[0:1], v[0:1], v[34:35] op_sel_hi:[1,0]
	v_pk_mul_f32 v[30:31], v[30:31], v[34:35] op_sel_hi:[1,0]
	v_pk_mul_f32 v[28:29], v[28:29], v[34:35] op_sel_hi:[1,0]
	v_pk_mul_f32 v[26:27], v[26:27], v[34:35] op_sel_hi:[1,0]
	v_pk_mul_f32 v[24:25], v[24:25], v[34:35] op_sel_hi:[1,0]
	v_pk_mul_f32 v[22:23], v[22:23], v[34:35] op_sel_hi:[1,0]
	v_pk_mul_f32 v[20:21], v[20:21], v[34:35] op_sel_hi:[1,0]
	v_pk_mul_f32 v[18:19], v[18:19], v[34:35] op_sel_hi:[1,0]
	v_pk_mul_f32 v[16:17], v[16:17], v[34:35] op_sel_hi:[1,0]
	v_sub_f32_e32 v142, v142, v33
	v_sub_f32_e32 v141, v141, v33
	v_sub_f32_e32 v140, v140, v33
	v_sub_f32_e32 v139, v139, v33
	v_sub_f32_e32 v138, v138, v33
	v_sub_f32_e32 v137, v137, v33
	v_sub_f32_e32 v136, v136, v33
	v_sub_f32_e32 v135, v135, v33
	v_sub_f32_e32 v134, v134, v33
	v_sub_f32_e32 v133, v133, v33
	v_sub_f32_e32 v132, v132, v33
	v_sub_f32_e32 v131, v131, v33
	v_sub_f32_e32 v130, v130, v33
	v_sub_f32_e32 v129, v129, v33
	v_sub_f32_e32 v128, v128, v33
	v_sub_f32_e32 v111, v111, v33
	v_sub_f32_e32 v110, v110, v33
	v_sub_f32_e32 v109, v109, v33
	v_sub_f32_e32 v108, v108, v33
	v_sub_f32_e32 v107, v107, v33
	v_sub_f32_e32 v106, v106, v33
	v_sub_f32_e32 v105, v105, v33
	v_sub_f32_e32 v104, v104, v33
	v_sub_f32_e32 v103, v103, v33
	v_sub_f32_e32 v102, v102, v33
	v_sub_f32_e32 v101, v101, v33
	v_sub_f32_e32 v100, v100, v33
	v_sub_f32_e32 v99, v99, v33
	v_sub_f32_e32 v98, v98, v33
	v_sub_f32_e32 v97, v97, v33
	v_sub_f32_e32 v96, v96, v33
	v_mul_f32_e32 v86, v86, v34
	v_mov_b32_e32 v33, v32
	v_mov_b32_e32 v34, v32
	v_mov_b32_e32 v35, v32
	v_mov_b32_e32 v36, v32
	v_mov_b32_e32 v37, v32
	v_mov_b32_e32 v38, v32
	v_mov_b32_e32 v39, v32
	v_mov_b32_e32 v40, v32
	v_mov_b32_e32 v41, v32
	v_mov_b32_e32 v42, v32
	v_mov_b32_e32 v43, v32
	v_mov_b32_e32 v44, v32
	v_mov_b32_e32 v45, v32
	v_mov_b32_e32 v46, v32
	v_mov_b32_e32 v47, v32
	v_mov_b32_e32 v48, v32
	v_mov_b32_e32 v49, v32
	v_mov_b32_e32 v50, v32
	v_mov_b32_e32 v51, v32
	v_mov_b32_e32 v52, v32
	v_mov_b32_e32 v53, v32
	v_mov_b32_e32 v54, v32
	v_mov_b32_e32 v55, v32
	v_mov_b32_e32 v56, v32
	v_mov_b32_e32 v57, v32
	v_mov_b32_e32 v58, v32
	v_mov_b32_e32 v59, v32
	v_mov_b32_e32 v60, v32
	v_mov_b32_e32 v61, v32
	v_mov_b32_e32 v62, v32
	v_mov_b32_e32 v63, v32

.LBB0_988:
	ds_read_b128 v[88:91], v181 offset:26656
	ds_read_b128 v[92:95], v181 offset:33312
	s_waitcnt lgkmcnt(3)
	v_mfma_f32_32x32x16_bf16 v[112:127], v[64:67], v[144:147], v[32:47]
	v_exp_f32_e32 v87, v128
	v_exp_f32_e32 v213, v129
	v_exp_f32_e32 v214, v130
	v_exp_f32_e32 v215, v131
	v_exp_f32_e32 v132, v132
	v_exp_f32_e32 v133, v133
	s_waitcnt lgkmcnt(2)
	v_mfma_f32_32x32x16_bf16 v[64:79], v[80:83], v[144:147], v[32:47]
	ds_read_b128 v[80:83], v181 offset:26688
	ds_read_b128 v[128:131], v181 offset:33344
	s_waitcnt lgkmcnt(3)
	v_mfma_f32_32x32x16_bf16 v[112:127], v[88:91], v[148:151], v[112:127]
	v_cvt_pk_bf16_f32 v88, v87, v213
	v_add_f32_e32 v87, v214, v87
	v_add_f32_e32 v90, v215, v213
	v_add_f32_e32 v87, v132, v87
	s_waitcnt lgkmcnt(2)
	v_mfma_f32_32x32x16_bf16 v[64:79], v[92:95], v[148:151], v[64:79]
	ds_read_b128 v[92:95], v181 offset:26720
	v_add_f32_e32 v91, v133, v90
	v_exp_f32_e32 v216, v134
	v_exp_f32_e32 v217, v135
	v_exp_f32_e32 v136, v136
	v_exp_f32_e32 v137, v137
	v_exp_f32_e32 v138, v138
	v_exp_f32_e32 v139, v139
	v_cvt_pk_bf16_f32 v89, v214, v215
	v_cvt_pk_bf16_f32 v90, v132, v133
	ds_read_b128 v[132:135], v181 offset:33376
	s_waitcnt lgkmcnt(3)
	v_mfma_f32_32x32x16_bf16 v[112:127], v[80:83], v[152:155], v[112:127]
	v_add_f32_e32 v80, v216, v87
	v_add_f32_e32 v81, v217, v91
	v_add_f32_e32 v82, v136, v80
	v_add_f32_e32 v81, v137, v81
	v_add_f32_e32 v82, v138, v82
	v_add_f32_e32 v83, v139, v81
	s_waitcnt lgkmcnt(2)
	v_mfma_f32_32x32x16_bf16 v[64:79], v[128:131], v[152:155], v[64:79]
	ds_read_b128 v[128:131], v181 offset:26752
	v_exp_f32_e32 v140, v140
	v_exp_f32_e32 v141, v141
	v_exp_f32_e32 v142, v142
	v_exp_f32_e32 v143, v143
	v_cvt_pk_bf16_f32 v91, v216, v217
	v_cvt_pk_bf16_f32 v80, v136, v137
	v_cvt_pk_bf16_f32 v81, v138, v139
	ds_read_b128 v[136:139], v181 offset:33408
	s_waitcnt lgkmcnt(3)
	v_mfma_f32_32x32x16_bf16 v[112:127], v[92:95], v[156:159], v[112:127]
	v_exp_f32_e32 v87, v96
	v_add_f32_e32 v92, v140, v82
	v_add_f32_e32 v83, v141, v83
	v_exp_f32_e32 v216, v100
	v_exp_f32_e32 v217, v101
	v_add_f32_e32 v100, v142, v92
	ds_read_b128 v[92:95], v181 offset:26784
	s_waitcnt lgkmcnt(3)
	v_mfma_f32_32x32x16_bf16 v[64:79], v[132:135], v[156:159], v[64:79]
	v_add_f32_e32 v101, v143, v83
	v_exp_f32_e32 v213, v97
	v_exp_f32_e32 v214, v98
	v_exp_f32_e32 v215, v99
	ds_read_b128 v[96:99], v181 offset:33440
	v_cvt_pk_bf16_f32 v82, v140, v141
	v_cvt_pk_bf16_f32 v83, v142, v143
	s_waitcnt lgkmcnt(3)
	v_mfma_f32_32x32x16_bf16 v[112:127], v[128:131], v[160:163], v[112:127]
	v_exp_f32_e32 v132, v102
	v_add_f32_e32 v102, v87, v100
	v_add_f32_e32 v101, v213, v101
	v_cvt_pk_bf16_f32 v100, v87, v213
	v_add_f32_e32 v87, v214, v102
	v_add_f32_e32 v102, v215, v101
	s_waitcnt lgkmcnt(2)
	v_mfma_f32_32x32x16_bf16 v[64:79], v[136:139], v[160:163], v[64:79]
	v_add_f32_e32 v87, v216, v87
	v_add_f32_e32 v136, v217, v102
	v_exp_f32_e32 v103, v103
	v_exp_f32_e32 v133, v104
	v_exp_f32_e32 v134, v105
	v_exp_f32_e32 v135, v106
	v_exp_f32_e32 v140, v107
	ds_read_b128 v[104:107], v210 offset:62464
	ds_read_b128 v[128:131], v211 offset:13824
	v_cvt_pk_bf16_f32 v101, v214, v215
	v_cvt_pk_bf16_f32 v102, v216, v217
	s_waitcnt lgkmcnt(3)
	v_mfma_f32_32x32x16_bf16 v[112:127], v[92:95], v[164:167], v[112:127]
	v_add_f32_e32 v87, v132, v87
	v_add_f32_e32 v92, v103, v136
	v_add_f32_e32 v87, v133, v87
	v_add_f32_e32 v93, v134, v92
	v_add_f32_e32 v87, v135, v87
	v_add_f32_e32 v94, v140, v93
	s_waitcnt lgkmcnt(2)
	v_mfma_f32_32x32x16_bf16 v[64:79], v[96:99], v[164:167], v[64:79]
	ds_read_b128 v[96:99], v210 offset:62496
	v_exp_f32_e32 v137, v108
	v_exp_f32_e32 v138, v109
	v_exp_f32_e32 v139, v110
	v_exp_f32_e32 v141, v111
	ds_read_b128 v[108:111], v211 offset:13856
	v_cvt_pk_bf16_f32 v103, v132, v103
	v_cvt_pk_bf16_f32 v92, v133, v134
	v_cvt_pk_bf16_f32 v93, v135, v140
	s_waitcnt lgkmcnt(3)
	v_mfma_f32_32x32x16_bf16 v[0:15], v[104:107], v[88:91], v[0:15]
	v_add_f32_e32 v87, v137, v87
	v_add_f32_e32 v95, v138, v94
	v_add_f32_e32 v132, v139, v87
	v_add_f32_e32 v133, v141, v95
	v_cvt_pk_bf16_f32 v94, v137, v138
	v_cvt_pk_bf16_f32 v95, v139, v141
	s_waitcnt lgkmcnt(2)
	v_mfma_f32_32x32x16_bf16 v[16:31], v[128:131], v[88:91], v[16:31]
	ds_read_b128 v[88:91], v210 offset:62528
	s_waitcnt lgkmcnt(2)
	v_mfma_f32_32x32x16_bf16 v[0:15], v[96:99], v[80:83], v[0:15]
	ds_read_b128 v[96:99], v211 offset:13888
	s_waitcnt lgkmcnt(2)
	v_mfma_f32_32x32x16_bf16 v[16:31], v[108:111], v[80:83], v[16:31]
	ds_read_b128 v[80:83], v210 offset:62560
	ds_read_b128 v[104:107], v211 offset:13920
	s_waitcnt lgkmcnt(3)
	v_mfma_f32_32x32x16_bf16 v[0:15], v[88:91], v[100:103], v[0:15]
	s_waitcnt lgkmcnt(2)
	v_mfma_f32_32x32x16_bf16 v[16:31], v[96:99], v[100:103], v[16:31]
	s_waitcnt lgkmcnt(1)
	v_mfma_f32_32x32x16_bf16 v[0:15], v[80:83], v[92:95], v[0:15]
	v_add_f32_e32 v221, v132, v133
	v_cmp_lt_f32_e32 vcc, s59, v221
	v_add_f32_e32 v102, v86, v221
	s_waitcnt lgkmcnt(0)
	v_mfma_f32_32x32x16_bf16 v[16:31], v[104:107], v[92:95], v[16:31]
	s_waitcnt vmcnt(0)
	s_barrier
	ds_read_b128 v[80:83], v181 offset:39936
	ds_read_b128 v[96:99], v181 offset:46592
	s_cbranch_vccz .LBB0_990
	v_mov_b32_e32 v222, v221
	v_mov_b32_e32 v223, v221
	s_nop 1
	v_permlane32_swap_b32_e32 v222, v223
	v_add_f32_e32 v222, v222, v223
	v_log_f32_e32 v222, v222
	s_nop 0
	v_max_f32_e32 v33, 0, v222
	v_exp_f32_e64 v34, -v33
	v_add_f32_e32 v212, v212, v33
	v_xor_b32_e32 v32, 0x80000000, v212
	v_sub_f32_e32 v127, v127, v33
	v_pk_mul_f32 v[14:15], v[14:15], v[34:35] op_sel_hi:[1,0]
	v_pk_mul_f32 v[12:13], v[12:13], v[34:35] op_sel_hi:[1,0]
	v_pk_mul_f32 v[10:11], v[10:11], v[34:35] op_sel_hi:[1,0]
	v_pk_mul_f32 v[8:9], v[8:9], v[34:35] op_sel_hi:[1,0]
	v_pk_mul_f32 v[6:7], v[6:7], v[34:35] op_sel_hi:[1,0]
	v_pk_mul_f32 v[4:5], v[4:5], v[34:35] op_sel_hi:[1,0]
	v_pk_mul_f32 v[2:3], v[2:3], v[34:35] op_sel_hi:[1,0]
	v_pk_mul_f32 v[0:1], v[0:1], v[34:35] op_sel_hi:[1,0]
	v_pk_mul_f32 v[30:31], v[30:31], v[34:35] op_sel_hi:[1,0]
	v_pk_mul_f32 v[28:29], v[28:29], v[34:35] op_sel_hi:[1,0]
	v_pk_mul_f32 v[26:27], v[26:27], v[34:35] op_sel_hi:[1,0]
	v_pk_mul_f32 v[24:25], v[24:25], v[34:35] op_sel_hi:[1,0]
	v_pk_mul_f32 v[22:23], v[22:23], v[34:35] op_sel_hi:[1,0]
	v_pk_mul_f32 v[20:21], v[20:21], v[34:35] op_sel_hi:[1,0]
	v_pk_mul_f32 v[18:19], v[18:19], v[34:35] op_sel_hi:[1,0]
	v_pk_mul_f32 v[16:17], v[16:17], v[34:35] op_sel_hi:[1,0]
	v_sub_f32_e32 v126, v126, v33
	v_sub_f32_e32 v125, v125, v33
	v_sub_f32_e32 v124, v124, v33
	v_sub_f32_e32 v123, v123, v33
	v_sub_f32_e32 v122, v122, v33
	v_sub_f32_e32 v121, v121, v33
	v_sub_f32_e32 v120, v120, v33
	v_sub_f32_e32 v119, v119, v33
	v_sub_f32_e32 v118, v118, v33
	v_sub_f32_e32 v117, v117, v33
	v_sub_f32_e32 v116, v116, v33
	v_sub_f32_e32 v115, v115, v33
	v_sub_f32_e32 v114, v114, v33
	v_sub_f32_e32 v113, v113, v33
	v_sub_f32_e32 v112, v112, v33
	v_sub_f32_e32 v79, v79, v33
	v_sub_f32_e32 v78, v78, v33
	v_sub_f32_e32 v77, v77, v33
	v_sub_f32_e32 v76, v76, v33
	v_sub_f32_e32 v75, v75, v33
	v_sub_f32_e32 v74, v74, v33
	v_sub_f32_e32 v73, v73, v33
	v_sub_f32_e32 v72, v72, v33
	v_sub_f32_e32 v71, v71, v33
	v_sub_f32_e32 v70, v70, v33
	v_sub_f32_e32 v69, v69, v33
	v_sub_f32_e32 v68, v68, v33
	v_sub_f32_e32 v67, v67, v33
	v_sub_f32_e32 v66, v66, v33
	v_sub_f32_e32 v65, v65, v33
	v_sub_f32_e32 v64, v64, v33
	v_mul_f32_e32 v102, v102, v34
	v_mov_b32_e32 v33, v32
	v_mov_b32_e32 v34, v32
	v_mov_b32_e32 v35, v32
	v_mov_b32_e32 v36, v32
	v_mov_b32_e32 v37, v32
	v_mov_b32_e32 v38, v32
	v_mov_b32_e32 v39, v32
	v_mov_b32_e32 v40, v32
	v_mov_b32_e32 v41, v32
	v_mov_b32_e32 v42, v32
	v_mov_b32_e32 v43, v32
	v_mov_b32_e32 v44, v32
	v_mov_b32_e32 v45, v32
	v_mov_b32_e32 v46, v32
	v_mov_b32_e32 v47, v32
	v_mov_b32_e32 v48, v32
	v_mov_b32_e32 v49, v32
	v_mov_b32_e32 v50, v32
	v_mov_b32_e32 v51, v32
	v_mov_b32_e32 v52, v32
	v_mov_b32_e32 v53, v32
	v_mov_b32_e32 v54, v32
	v_mov_b32_e32 v55, v32
	v_mov_b32_e32 v56, v32
	v_mov_b32_e32 v57, v32
	v_mov_b32_e32 v58, v32
	v_mov_b32_e32 v59, v32
	v_mov_b32_e32 v60, v32
	v_mov_b32_e32 v61, v32
	v_mov_b32_e32 v62, v32
	v_mov_b32_e32 v63, v32

.LBB0_994:
	ds_read_b128 v[104:107], v181 offset:39968
	ds_read_b128 v[108:111], v181 offset:46624
	s_waitcnt lgkmcnt(3)
	v_mfma_f32_32x32x16_bf16 v[128:143], v[80:83], v[144:147], v[32:47]
	v_exp_f32_e32 v103, v112
	v_exp_f32_e32 v213, v113
	v_exp_f32_e32 v214, v114
	v_exp_f32_e32 v215, v115
	v_exp_f32_e32 v116, v116
	v_exp_f32_e32 v117, v117
	s_waitcnt lgkmcnt(2)
	v_mfma_f32_32x32x16_bf16 v[80:95], v[96:99], v[144:147], v[32:47]
	ds_read_b128 v[96:99], v181 offset:40000
	ds_read_b128 v[112:115], v181 offset:46656
	s_waitcnt lgkmcnt(3)
	v_mfma_f32_32x32x16_bf16 v[128:143], v[104:107], v[148:151], v[128:143]
	v_cvt_pk_bf16_f32 v104, v103, v213
	v_add_f32_e32 v103, v214, v103
	v_add_f32_e32 v106, v215, v213
	v_add_f32_e32 v103, v116, v103
	s_waitcnt lgkmcnt(2)
	v_mfma_f32_32x32x16_bf16 v[80:95], v[108:111], v[148:151], v[80:95]
	ds_read_b128 v[108:111], v181 offset:40032
	v_add_f32_e32 v107, v117, v106
	v_exp_f32_e32 v216, v118
	v_exp_f32_e32 v217, v119
	v_exp_f32_e32 v120, v120
	v_exp_f32_e32 v121, v121
	v_exp_f32_e32 v122, v122
	v_exp_f32_e32 v123, v123
	v_cvt_pk_bf16_f32 v105, v214, v215
	v_cvt_pk_bf16_f32 v106, v116, v117
	ds_read_b128 v[116:119], v181 offset:46688
	s_waitcnt lgkmcnt(3)
	v_mfma_f32_32x32x16_bf16 v[128:143], v[96:99], v[152:155], v[128:143]
	v_add_f32_e32 v96, v216, v103
	v_add_f32_e32 v97, v217, v107
	v_add_f32_e32 v98, v120, v96
	v_add_f32_e32 v97, v121, v97
	v_add_f32_e32 v98, v122, v98
	v_add_f32_e32 v99, v123, v97
	s_waitcnt lgkmcnt(2)
	v_mfma_f32_32x32x16_bf16 v[80:95], v[112:115], v[152:155], v[80:95]
	ds_read_b128 v[112:115], v181 offset:40064
	v_exp_f32_e32 v124, v124
	v_exp_f32_e32 v125, v125
	v_exp_f32_e32 v126, v126
	v_exp_f32_e32 v127, v127
	v_cvt_pk_bf16_f32 v107, v216, v217
	v_cvt_pk_bf16_f32 v96, v120, v121
	v_cvt_pk_bf16_f32 v97, v122, v123
	ds_read_b128 v[120:123], v181 offset:46720
	s_waitcnt lgkmcnt(3)
	v_mfma_f32_32x32x16_bf16 v[128:143], v[108:111], v[156:159], v[128:143]
	v_exp_f32_e32 v103, v64
	v_exp_f32_e32 v213, v65
	v_add_f32_e32 v64, v124, v98
	v_add_f32_e32 v65, v125, v99
	v_exp_f32_e32 v216, v68
	v_exp_f32_e32 v217, v69
	s_waitcnt lgkmcnt(2)
	v_mfma_f32_32x32x16_bf16 v[80:95], v[116:119], v[156:159], v[80:95]
	v_add_f32_e32 v68, v126, v64
	v_add_f32_e32 v69, v127, v65
	v_exp_f32_e32 v214, v66
	v_exp_f32_e32 v215, v67
	ds_read_b128 v[64:67], v181 offset:40096
	ds_read_b128 v[108:111], v181 offset:46752
	v_cvt_pk_bf16_f32 v98, v124, v125
	v_cvt_pk_bf16_f32 v99, v126, v127
	s_waitcnt lgkmcnt(3)
	v_mfma_f32_32x32x16_bf16 v[128:143], v[112:115], v[160:163], v[128:143]
	v_exp_f32_e32 v118, v73
	v_exp_f32_e32 v116, v70
	v_add_f32_e32 v70, v103, v68
	v_add_f32_e32 v69, v213, v69
	v_exp_f32_e32 v117, v72
	v_add_f32_e32 v70, v214, v70
	s_waitcnt lgkmcnt(2)
	v_mfma_f32_32x32x16_bf16 v[80:95], v[120:123], v[160:163], v[80:95]
	v_add_f32_e32 v72, v215, v69
	v_cvt_pk_bf16_f32 v68, v103, v213
	v_add_f32_e32 v103, v216, v70
	v_add_f32_e32 v120, v217, v72
	v_exp_f32_e32 v71, v71
	v_exp_f32_e32 v119, v74
	v_exp_f32_e32 v124, v75
	ds_read_b128 v[72:75], v211 offset:18432
	ds_read_b128 v[112:115], v211 offset:23040
	v_cvt_pk_bf16_f32 v69, v214, v215
	v_cvt_pk_bf16_f32 v70, v216, v217
	s_waitcnt lgkmcnt(3)
	v_mfma_f32_32x32x16_bf16 v[128:143], v[64:67], v[164:167], v[128:143]
	v_add_f32_e32 v64, v116, v103
	v_add_f32_e32 v65, v71, v120
	v_add_f32_e32 v66, v117, v64
	v_add_f32_e32 v65, v118, v65
	v_add_f32_e32 v66, v119, v66
	v_add_f32_e32 v67, v124, v65
	s_waitcnt lgkmcnt(2)
	v_mfma_f32_32x32x16_bf16 v[80:95], v[108:111], v[164:167], v[80:95]
	v_exp_f32_e32 v121, v76
	v_exp_f32_e32 v122, v77
	v_exp_f32_e32 v123, v78
	v_exp_f32_e32 v125, v79
	ds_read_b128 v[76:79], v211 offset:18464
	ds_read_b128 v[108:111], v211 offset:23072
	v_cvt_pk_bf16_f32 v71, v116, v71
	v_cvt_pk_bf16_f32 v64, v117, v118
	v_cvt_pk_bf16_f32 v65, v119, v124
	s_waitcnt lgkmcnt(3)
	v_mfma_f32_32x32x16_bf16 v[0:15], v[72:75], v[104:107], v[0:15]
	v_add_f32_e32 v72, v121, v66
	v_add_f32_e32 v67, v122, v67
	v_add_f32_e32 v103, v123, v72
	ds_read_b128 v[72:75], v211 offset:18496
	v_add_f32_e32 v116, v125, v67
	v_cvt_pk_bf16_f32 v66, v121, v122
	v_cvt_pk_bf16_f32 v67, v123, v125
	s_waitcnt lgkmcnt(3)
	v_mfma_f32_32x32x16_bf16 v[16:31], v[112:115], v[104:107], v[16:31]
	s_waitcnt lgkmcnt(2)
	v_mfma_f32_32x32x16_bf16 v[0:15], v[76:79], v[96:99], v[0:15]
	ds_read_b128 v[76:79], v211 offset:23104
	s_waitcnt lgkmcnt(2)
	v_mfma_f32_32x32x16_bf16 v[16:31], v[108:111], v[96:99], v[16:31]
	ds_read_b128 v[96:99], v211 offset:18528
	ds_read_b128 v[104:107], v211 offset:23136
	s_waitcnt lgkmcnt(3)
	v_mfma_f32_32x32x16_bf16 v[0:15], v[72:75], v[68:71], v[0:15]
	s_waitcnt lgkmcnt(2)
	v_mfma_f32_32x32x16_bf16 v[16:31], v[76:79], v[68:71], v[16:31]
	s_waitcnt lgkmcnt(1)
	v_mfma_f32_32x32x16_bf16 v[0:15], v[96:99], v[64:67], v[0:15]
	v_add_f32_e32 v221, v103, v116
	v_cmp_lt_f32_e32 vcc, s59, v221
	v_add_f32_e32 v118, v102, v221
	s_waitcnt lgkmcnt(0)
	v_mfma_f32_32x32x16_bf16 v[16:31], v[104:107], v[64:67], v[16:31]
	ds_read_b128 v[64:67], v181
	ds_read_b128 v[112:115], v181 offset:6656
	s_cbranch_vccz .LBB0_996
	v_mov_b32_e32 v222, v221
	v_mov_b32_e32 v223, v221
	s_nop 1
	v_permlane32_swap_b32_e32 v222, v223
	v_add_f32_e32 v222, v222, v223
	v_log_f32_e32 v222, v222
	s_nop 0
	v_max_f32_e32 v33, 0, v222
	v_exp_f32_e64 v34, -v33
	v_add_f32_e32 v212, v212, v33
	v_xor_b32_e32 v32, 0x80000000, v212
	v_sub_f32_e32 v143, v143, v33
	v_pk_mul_f32 v[14:15], v[14:15], v[34:35] op_sel_hi:[1,0]
	v_pk_mul_f32 v[12:13], v[12:13], v[34:35] op_sel_hi:[1,0]
	v_pk_mul_f32 v[10:11], v[10:11], v[34:35] op_sel_hi:[1,0]
	v_pk_mul_f32 v[8:9], v[8:9], v[34:35] op_sel_hi:[1,0]
	v_pk_mul_f32 v[6:7], v[6:7], v[34:35] op_sel_hi:[1,0]
	v_pk_mul_f32 v[4:5], v[4:5], v[34:35] op_sel_hi:[1,0]
	v_pk_mul_f32 v[2:3], v[2:3], v[34:35] op_sel_hi:[1,0]
	v_pk_mul_f32 v[0:1], v[0:1], v[34:35] op_sel_hi:[1,0]
	v_pk_mul_f32 v[30:31], v[30:31], v[34:35] op_sel_hi:[1,0]
	v_pk_mul_f32 v[28:29], v[28:29], v[34:35] op_sel_hi:[1,0]
	v_pk_mul_f32 v[26:27], v[26:27], v[34:35] op_sel_hi:[1,0]
	v_pk_mul_f32 v[24:25], v[24:25], v[34:35] op_sel_hi:[1,0]
	v_pk_mul_f32 v[22:23], v[22:23], v[34:35] op_sel_hi:[1,0]
	v_pk_mul_f32 v[20:21], v[20:21], v[34:35] op_sel_hi:[1,0]
	v_pk_mul_f32 v[18:19], v[18:19], v[34:35] op_sel_hi:[1,0]
	v_pk_mul_f32 v[16:17], v[16:17], v[34:35] op_sel_hi:[1,0]
	v_sub_f32_e32 v142, v142, v33
	v_sub_f32_e32 v141, v141, v33
	v_sub_f32_e32 v140, v140, v33
	v_sub_f32_e32 v139, v139, v33
	v_sub_f32_e32 v138, v138, v33
	v_sub_f32_e32 v137, v137, v33
	v_sub_f32_e32 v136, v136, v33
	v_sub_f32_e32 v135, v135, v33
	v_sub_f32_e32 v134, v134, v33
	v_sub_f32_e32 v133, v133, v33
	v_sub_f32_e32 v132, v132, v33
	v_sub_f32_e32 v131, v131, v33
	v_sub_f32_e32 v130, v130, v33
	v_sub_f32_e32 v129, v129, v33
	v_sub_f32_e32 v128, v128, v33
	v_sub_f32_e32 v95, v95, v33
	v_sub_f32_e32 v94, v94, v33
	v_sub_f32_e32 v93, v93, v33
	v_sub_f32_e32 v92, v92, v33
	v_sub_f32_e32 v91, v91, v33
	v_sub_f32_e32 v90, v90, v33
	v_sub_f32_e32 v89, v89, v33
	v_sub_f32_e32 v88, v88, v33
	v_sub_f32_e32 v87, v87, v33
	v_sub_f32_e32 v86, v86, v33
	v_sub_f32_e32 v85, v85, v33
	v_sub_f32_e32 v84, v84, v33
	v_sub_f32_e32 v83, v83, v33
	v_sub_f32_e32 v82, v82, v33
	v_sub_f32_e32 v81, v81, v33
	v_sub_f32_e32 v80, v80, v33
	v_mul_f32_e32 v118, v118, v34
	v_mov_b32_e32 v33, v32
	v_mov_b32_e32 v34, v32
	v_mov_b32_e32 v35, v32
	v_mov_b32_e32 v36, v32
	v_mov_b32_e32 v37, v32
	v_mov_b32_e32 v38, v32
	v_mov_b32_e32 v39, v32
	v_mov_b32_e32 v40, v32
	v_mov_b32_e32 v41, v32
	v_mov_b32_e32 v42, v32
	v_mov_b32_e32 v43, v32
	v_mov_b32_e32 v44, v32
	v_mov_b32_e32 v45, v32
	v_mov_b32_e32 v46, v32
	v_mov_b32_e32 v47, v32
	v_mov_b32_e32 v48, v32
	v_mov_b32_e32 v49, v32
	v_mov_b32_e32 v50, v32
	v_mov_b32_e32 v51, v32
	v_mov_b32_e32 v52, v32
	v_mov_b32_e32 v53, v32
	v_mov_b32_e32 v54, v32
	v_mov_b32_e32 v55, v32
	v_mov_b32_e32 v56, v32
	v_mov_b32_e32 v57, v32
	v_mov_b32_e32 v58, v32
	v_mov_b32_e32 v59, v32
	v_mov_b32_e32 v60, v32
	v_mov_b32_e32 v61, v32
	v_mov_b32_e32 v62, v32
	v_mov_b32_e32 v63, v32

.LBB0_1000:
	ds_read_b128 v[120:123], v181 offset:32
	ds_read_b128 v[124:127], v181 offset:6688
	s_waitcnt lgkmcnt(3)
	v_mfma_f32_32x32x16_bf16 v[96:111], v[64:67], v[144:147], v[32:47]
	v_exp_f32_e32 v119, v128
	v_exp_f32_e32 v213, v129
	v_exp_f32_e32 v214, v130
	v_exp_f32_e32 v215, v131
	v_exp_f32_e32 v132, v132
	v_exp_f32_e32 v133, v133
	s_waitcnt lgkmcnt(2)
	v_mfma_f32_32x32x16_bf16 v[64:79], v[112:115], v[144:147], v[32:47]
	ds_read_b128 v[112:115], v181 offset:64
	ds_read_b128 v[128:131], v181 offset:6720
	s_waitcnt lgkmcnt(3)
	v_mfma_f32_32x32x16_bf16 v[96:111], v[120:123], v[148:151], v[96:111]
	v_cvt_pk_bf16_f32 v120, v119, v213
	v_add_f32_e32 v119, v214, v119
	v_add_f32_e32 v122, v215, v213
	v_add_f32_e32 v119, v132, v119
	s_waitcnt lgkmcnt(2)
	v_mfma_f32_32x32x16_bf16 v[64:79], v[124:127], v[148:151], v[64:79]
	ds_read_b128 v[124:127], v181 offset:96
	v_add_f32_e32 v123, v133, v122
	v_exp_f32_e32 v216, v134
	v_exp_f32_e32 v217, v135
	v_exp_f32_e32 v136, v136
	v_exp_f32_e32 v137, v137
	v_exp_f32_e32 v138, v138
	v_exp_f32_e32 v139, v139
	v_cvt_pk_bf16_f32 v121, v214, v215
	v_cvt_pk_bf16_f32 v122, v132, v133
	ds_read_b128 v[132:135], v181 offset:6752
	s_waitcnt lgkmcnt(3)
	v_mfma_f32_32x32x16_bf16 v[96:111], v[112:115], v[152:155], v[96:111]
	v_add_f32_e32 v112, v216, v119
	v_add_f32_e32 v113, v217, v123
	v_add_f32_e32 v114, v136, v112
	v_add_f32_e32 v113, v137, v113
	v_add_f32_e32 v114, v138, v114
	v_add_f32_e32 v115, v139, v113
	s_waitcnt lgkmcnt(2)
	v_mfma_f32_32x32x16_bf16 v[64:79], v[128:131], v[152:155], v[64:79]
	ds_read_b128 v[128:131], v181 offset:128
	v_exp_f32_e32 v140, v140
	v_exp_f32_e32 v141, v141
	v_exp_f32_e32 v142, v142
	v_exp_f32_e32 v143, v143
	v_cvt_pk_bf16_f32 v123, v216, v217
	v_cvt_pk_bf16_f32 v112, v136, v137
	v_cvt_pk_bf16_f32 v113, v138, v139
	ds_read_b128 v[136:139], v181 offset:6784
	s_waitcnt lgkmcnt(3)
	v_mfma_f32_32x32x16_bf16 v[96:111], v[124:127], v[156:159], v[96:111]
	v_exp_f32_e32 v119, v80
	v_exp_f32_e32 v213, v81
	v_add_f32_e32 v80, v140, v114
	v_add_f32_e32 v81, v141, v115
	v_exp_f32_e32 v216, v84
	v_exp_f32_e32 v217, v85
	s_waitcnt lgkmcnt(2)
	v_mfma_f32_32x32x16_bf16 v[64:79], v[132:135], v[156:159], v[64:79]
	v_add_f32_e32 v84, v142, v80
	v_add_f32_e32 v85, v143, v81
	v_exp_f32_e32 v214, v82
	v_exp_f32_e32 v215, v83
	ds_read_b128 v[80:83], v181 offset:160
	ds_read_b128 v[124:127], v181 offset:6816
	v_cvt_pk_bf16_f32 v114, v140, v141
	v_cvt_pk_bf16_f32 v115, v142, v143
	s_waitcnt lgkmcnt(3)
	v_mfma_f32_32x32x16_bf16 v[96:111], v[128:131], v[160:163], v[96:111]
	v_exp_f32_e32 v132, v86
	v_add_f32_e32 v86, v119, v84
	v_add_f32_e32 v85, v213, v85
	v_exp_f32_e32 v133, v88
	v_add_f32_e32 v86, v214, v86
	v_add_f32_e32 v88, v215, v85
	s_waitcnt lgkmcnt(2)
	v_mfma_f32_32x32x16_bf16 v[64:79], v[136:139], v[160:163], v[64:79]
	v_cvt_pk_bf16_f32 v84, v119, v213
	v_add_f32_e32 v119, v216, v86
	v_add_f32_e32 v136, v217, v88
	v_exp_f32_e32 v87, v87
	v_exp_f32_e32 v134, v89
	v_exp_f32_e32 v135, v90
	v_exp_f32_e32 v140, v91
	ds_read_b128 v[88:91], v211 offset:27648
	ds_read_b128 v[128:131], v211 offset:32256
	v_cvt_pk_bf16_f32 v85, v214, v215
	v_cvt_pk_bf16_f32 v86, v216, v217
	s_waitcnt lgkmcnt(3)
	v_mfma_f32_32x32x16_bf16 v[96:111], v[80:83], v[164:167], v[96:111]
	v_add_f32_e32 v80, v132, v119
	v_add_f32_e32 v81, v87, v136
	v_add_f32_e32 v82, v133, v80
	v_add_f32_e32 v81, v134, v81
	v_add_f32_e32 v82, v135, v82
	v_add_f32_e32 v83, v140, v81
	s_waitcnt lgkmcnt(2)
	v_mfma_f32_32x32x16_bf16 v[64:79], v[124:127], v[164:167], v[64:79]
	v_exp_f32_e32 v137, v92
	v_exp_f32_e32 v138, v93
	v_exp_f32_e32 v139, v94
	v_exp_f32_e32 v141, v95
	ds_read_b128 v[92:95], v211 offset:27680
	ds_read_b128 v[124:127], v211 offset:32288
	v_cvt_pk_bf16_f32 v87, v132, v87
	v_cvt_pk_bf16_f32 v80, v133, v134
	v_cvt_pk_bf16_f32 v81, v135, v140
	s_waitcnt lgkmcnt(3)
	v_mfma_f32_32x32x16_bf16 v[0:15], v[88:91], v[120:123], v[0:15]
	v_add_f32_e32 v88, v137, v82
	v_add_f32_e32 v83, v138, v83
	v_add_f32_e32 v119, v139, v88
	ds_read_b128 v[88:91], v211 offset:27712
	v_add_f32_e32 v132, v141, v83
	v_cvt_pk_bf16_f32 v82, v137, v138
	v_cvt_pk_bf16_f32 v83, v139, v141
	s_waitcnt lgkmcnt(3)
	v_mfma_f32_32x32x16_bf16 v[16:31], v[128:131], v[120:123], v[16:31]
	s_waitcnt lgkmcnt(2)
	v_mfma_f32_32x32x16_bf16 v[0:15], v[92:95], v[112:115], v[0:15]
	ds_read_b128 v[92:95], v211 offset:32320
	s_waitcnt lgkmcnt(2)
	v_mfma_f32_32x32x16_bf16 v[16:31], v[124:127], v[112:115], v[16:31]
	ds_read_b128 v[112:115], v211 offset:27744
	ds_read_b128 v[120:123], v211 offset:32352
	s_waitcnt lgkmcnt(3)
	v_mfma_f32_32x32x16_bf16 v[0:15], v[88:91], v[84:87], v[0:15]
	s_waitcnt lgkmcnt(2)
	v_mfma_f32_32x32x16_bf16 v[16:31], v[92:95], v[84:87], v[16:31]
	s_waitcnt lgkmcnt(1)
	v_mfma_f32_32x32x16_bf16 v[0:15], v[112:115], v[80:83], v[0:15]
	v_add_f32_e32 v221, v119, v132
	v_cmp_lt_f32_e32 vcc, s59, v221
	v_add_f32_e32 v118, v118, v221
	s_waitcnt lgkmcnt(0)
	v_mfma_f32_32x32x16_bf16 v[16:31], v[120:123], v[80:83], v[16:31]
	s_waitcnt vmcnt(0)
	s_barrier
	ds_read_b128 v[80:83], v181 offset:13312
	ds_read_b128 v[112:115], v181 offset:19968
	s_cbranch_vccz .LBB0_1002
	v_mov_b32_e32 v222, v221
	v_mov_b32_e32 v223, v221
	s_nop 1
	v_permlane32_swap_b32_e32 v222, v223
	v_add_f32_e32 v222, v222, v223
	v_log_f32_e32 v222, v222
	s_nop 0
	v_max_f32_e32 v33, 0, v222
	v_exp_f32_e64 v34, -v33
	v_add_f32_e32 v212, v212, v33
	v_xor_b32_e32 v32, 0x80000000, v212
	v_sub_f32_e32 v111, v111, v33
	v_pk_mul_f32 v[14:15], v[14:15], v[34:35] op_sel_hi:[1,0]
	v_pk_mul_f32 v[12:13], v[12:13], v[34:35] op_sel_hi:[1,0]
	v_pk_mul_f32 v[10:11], v[10:11], v[34:35] op_sel_hi:[1,0]
	v_pk_mul_f32 v[8:9], v[8:9], v[34:35] op_sel_hi:[1,0]
	v_pk_mul_f32 v[6:7], v[6:7], v[34:35] op_sel_hi:[1,0]
	v_pk_mul_f32 v[4:5], v[4:5], v[34:35] op_sel_hi:[1,0]
	v_pk_mul_f32 v[2:3], v[2:3], v[34:35] op_sel_hi:[1,0]
	v_pk_mul_f32 v[0:1], v[0:1], v[34:35] op_sel_hi:[1,0]
	v_pk_mul_f32 v[30:31], v[30:31], v[34:35] op_sel_hi:[1,0]
	v_pk_mul_f32 v[28:29], v[28:29], v[34:35] op_sel_hi:[1,0]
	v_pk_mul_f32 v[26:27], v[26:27], v[34:35] op_sel_hi:[1,0]
	v_pk_mul_f32 v[24:25], v[24:25], v[34:35] op_sel_hi:[1,0]
	v_pk_mul_f32 v[22:23], v[22:23], v[34:35] op_sel_hi:[1,0]
	v_pk_mul_f32 v[20:21], v[20:21], v[34:35] op_sel_hi:[1,0]
	v_pk_mul_f32 v[18:19], v[18:19], v[34:35] op_sel_hi:[1,0]
	v_pk_mul_f32 v[16:17], v[16:17], v[34:35] op_sel_hi:[1,0]
	v_sub_f32_e32 v110, v110, v33
	v_sub_f32_e32 v109, v109, v33
	v_sub_f32_e32 v108, v108, v33
	v_sub_f32_e32 v107, v107, v33
	v_sub_f32_e32 v106, v106, v33
	v_sub_f32_e32 v105, v105, v33
	v_sub_f32_e32 v104, v104, v33
	v_sub_f32_e32 v103, v103, v33
	v_sub_f32_e32 v102, v102, v33
	v_sub_f32_e32 v101, v101, v33
	v_sub_f32_e32 v100, v100, v33
	v_sub_f32_e32 v99, v99, v33
	v_sub_f32_e32 v98, v98, v33
	v_sub_f32_e32 v97, v97, v33
	v_sub_f32_e32 v96, v96, v33
	v_sub_f32_e32 v79, v79, v33
	v_sub_f32_e32 v78, v78, v33
	v_sub_f32_e32 v77, v77, v33
	v_sub_f32_e32 v76, v76, v33
	v_sub_f32_e32 v75, v75, v33
	v_sub_f32_e32 v74, v74, v33
	v_sub_f32_e32 v73, v73, v33
	v_sub_f32_e32 v72, v72, v33
	v_sub_f32_e32 v71, v71, v33
	v_sub_f32_e32 v70, v70, v33
	v_sub_f32_e32 v69, v69, v33
	v_sub_f32_e32 v68, v68, v33
	v_sub_f32_e32 v67, v67, v33
	v_sub_f32_e32 v66, v66, v33
	v_sub_f32_e32 v65, v65, v33
	v_sub_f32_e32 v64, v64, v33
	v_mul_f32_e32 v118, v118, v34
	v_mov_b32_e32 v33, v32
	v_mov_b32_e32 v34, v32
	v_mov_b32_e32 v35, v32
	v_mov_b32_e32 v36, v32
	v_mov_b32_e32 v37, v32
	v_mov_b32_e32 v38, v32
	v_mov_b32_e32 v39, v32
	v_mov_b32_e32 v40, v32
	v_mov_b32_e32 v41, v32
	v_mov_b32_e32 v42, v32
	v_mov_b32_e32 v43, v32
	v_mov_b32_e32 v44, v32
	v_mov_b32_e32 v45, v32
	v_mov_b32_e32 v46, v32
	v_mov_b32_e32 v47, v32
	v_mov_b32_e32 v48, v32
	v_mov_b32_e32 v49, v32
	v_mov_b32_e32 v50, v32
	v_mov_b32_e32 v51, v32
	v_mov_b32_e32 v52, v32
	v_mov_b32_e32 v53, v32
	v_mov_b32_e32 v54, v32
	v_mov_b32_e32 v55, v32
	v_mov_b32_e32 v56, v32
	v_mov_b32_e32 v57, v32
	v_mov_b32_e32 v58, v32
	v_mov_b32_e32 v59, v32
	v_mov_b32_e32 v60, v32
	v_mov_b32_e32 v61, v32
	v_mov_b32_e32 v62, v32
	v_mov_b32_e32 v63, v32

.LBB0_1006:
	ds_read_b128 v[138:141], v181 offset:13344
	ds_read_b128 v[214:217], v181 offset:20000
	s_waitcnt lgkmcnt(3)
	v_mfma_f32_32x32x16_bf16 v[122:137], v[80:83], v[144:147], v[32:47]
	v_exp_f32_e32 v116, v96
	v_exp_f32_e32 v117, v97
	v_exp_f32_e32 v119, v98
	v_exp_f32_e32 v120, v99
	ds_read_b128 v[96:99], v181 offset:13376
	v_exp_f32_e32 v121, v100
	v_exp_f32_e32 v142, v101
	s_waitcnt lgkmcnt(3)
	v_mfma_f32_32x32x16_bf16 v[80:95], v[112:115], v[144:147], v[32:47]
	ds_read_b128 v[112:115], v181 offset:20032
	s_waitcnt lgkmcnt(3)
	v_mfma_f32_32x32x16_bf16 v[122:137], v[138:141], v[148:151], v[122:137]
	v_exp_f32_e32 v143, v102
	v_exp_f32_e32 v213, v104
	v_add_f32_e32 v104, v119, v116
	v_add_f32_e32 v102, v120, v117
	s_waitcnt lgkmcnt(2)
	v_mfma_f32_32x32x16_bf16 v[80:95], v[214:217], v[148:151], v[80:95]
	v_cvt_pk_bf16_f32 v100, v116, v117
	v_add_f32_e32 v116, v121, v104
	v_add_f32_e32 v117, v142, v102
	v_exp_f32_e32 v103, v103
	v_exp_f32_e32 v218, v105
	v_exp_f32_e32 v219, v106
	v_exp_f32_e32 v220, v107
	ds_read_b128 v[104:107], v181 offset:13408
	ds_read_b128 v[138:141], v181 offset:20064
	v_cvt_pk_bf16_f32 v101, v119, v120
	v_cvt_pk_bf16_f32 v102, v121, v142
	s_waitcnt lgkmcnt(3)
	v_mfma_f32_32x32x16_bf16 v[122:137], v[96:99], v[152:155], v[122:137]
	v_add_f32_e32 v96, v143, v116
	v_add_f32_e32 v97, v103, v117
	v_add_f32_e32 v98, v213, v96
	v_add_f32_e32 v97, v218, v97
	v_add_f32_e32 v98, v219, v98
	v_add_f32_e32 v99, v220, v97
	s_waitcnt lgkmcnt(2)
	v_mfma_f32_32x32x16_bf16 v[80:95], v[112:115], v[152:155], v[80:95]
	v_exp_f32_e32 v119, v108
	v_exp_f32_e32 v120, v109
	v_exp_f32_e32 v121, v110
	v_exp_f32_e32 v142, v111
	ds_read_b128 v[108:111], v181 offset:13440
	ds_read_b128 v[112:115], v181 offset:20096
	v_cvt_pk_bf16_f32 v103, v143, v103
	v_cvt_pk_bf16_f32 v96, v213, v218
	v_cvt_pk_bf16_f32 v97, v219, v220
	s_waitcnt lgkmcnt(3)
	v_mfma_f32_32x32x16_bf16 v[122:137], v[104:107], v[156:159], v[122:137]
	v_exp_f32_e32 v116, v64
	v_exp_f32_e32 v117, v65
	v_add_f32_e32 v64, v119, v98
	v_add_f32_e32 v65, v120, v99
	v_exp_f32_e32 v214, v68
	v_exp_f32_e32 v215, v69
	s_waitcnt lgkmcnt(2)
	v_mfma_f32_32x32x16_bf16 v[80:95], v[138:141], v[156:159], v[80:95]
	v_add_f32_e32 v68, v121, v64
	v_add_f32_e32 v69, v142, v65
	v_exp_f32_e32 v143, v66
	v_exp_f32_e32 v213, v67
	ds_read_b128 v[64:67], v181 offset:13472
	ds_read_b128 v[104:107], v181 offset:20128
	v_cvt_pk_bf16_f32 v98, v119, v120
	v_cvt_pk_bf16_f32 v99, v121, v142
	s_waitcnt lgkmcnt(3)
	v_mfma_f32_32x32x16_bf16 v[122:137], v[108:111], v[160:163], v[122:137]
	v_exp_f32_e32 v119, v70
	v_add_f32_e32 v70, v116, v68
	v_add_f32_e32 v69, v117, v69
	v_exp_f32_e32 v120, v72
	v_add_f32_e32 v70, v143, v70
	v_add_f32_e32 v72, v213, v69
	s_waitcnt lgkmcnt(2)
	v_mfma_f32_32x32x16_bf16 v[80:95], v[112:115], v[160:163], v[80:95]
	v_add_f32_e32 v112, v214, v70
	v_add_f32_e32 v113, v215, v72
	v_exp_f32_e32 v71, v71
	v_exp_f32_e32 v121, v73
	v_exp_f32_e32 v138, v74
	v_exp_f32_e32 v139, v75
	ds_read_b128 v[72:75], v210 offset:53248
	ds_read_b128 v[108:111], v210 offset:57856
	v_cvt_pk_bf16_f32 v68, v116, v117
	v_cvt_pk_bf16_f32 v69, v143, v213
	v_cvt_pk_bf16_f32 v70, v214, v215
	s_waitcnt lgkmcnt(3)
	v_mfma_f32_32x32x16_bf16 v[122:137], v[64:67], v[164:167], v[122:137]
	v_add_f32_e32 v64, v119, v112
	v_add_f32_e32 v65, v71, v113
	v_add_f32_e32 v66, v120, v64
	v_add_f32_e32 v65, v121, v65
	v_add_f32_e32 v66, v138, v66
	v_add_f32_e32 v67, v139, v65
	s_waitcnt lgkmcnt(2)
	v_mfma_f32_32x32x16_bf16 v[80:95], v[104:107], v[164:167], v[80:95]
	v_exp_f32_e32 v114, v76
	v_exp_f32_e32 v115, v77
	v_exp_f32_e32 v116, v78
	v_exp_f32_e32 v117, v79
	ds_read_b128 v[76:79], v210 offset:53280
	ds_read_b128 v[104:107], v210 offset:57888
	v_cvt_pk_bf16_f32 v71, v119, v71
	v_cvt_pk_bf16_f32 v64, v120, v121
	v_cvt_pk_bf16_f32 v65, v138, v139
	s_waitcnt lgkmcnt(3)
	v_mfma_f32_32x32x16_bf16 v[0:15], v[72:75], v[100:103], v[0:15]
	v_add_f32_e32 v72, v114, v66
	v_add_f32_e32 v67, v115, v67
	v_add_f32_e32 v112, v116, v72
	ds_read_b128 v[72:75], v210 offset:53312
	v_add_f32_e32 v113, v117, v67
	v_cvt_pk_bf16_f32 v66, v114, v115
	v_cvt_pk_bf16_f32 v67, v116, v117
	s_waitcnt lgkmcnt(3)
	v_mfma_f32_32x32x16_bf16 v[16:31], v[108:111], v[100:103], v[16:31]
	s_waitcnt lgkmcnt(2)
	v_mfma_f32_32x32x16_bf16 v[0:15], v[76:79], v[96:99], v[0:15]
	ds_read_b128 v[76:79], v210 offset:57920
	s_waitcnt lgkmcnt(2)
	v_mfma_f32_32x32x16_bf16 v[16:31], v[104:107], v[96:99], v[16:31]
	ds_read_b128 v[96:99], v210 offset:53344
	ds_read_b128 v[102:105], v210 offset:57952
	s_waitcnt lgkmcnt(3)
	v_mfma_f32_32x32x16_bf16 v[0:15], v[72:75], v[68:71], v[0:15]
	s_waitcnt lgkmcnt(2)
	v_mfma_f32_32x32x16_bf16 v[16:31], v[76:79], v[68:71], v[16:31]
	s_waitcnt lgkmcnt(1)
	v_mfma_f32_32x32x16_bf16 v[0:15], v[96:99], v[64:67], v[0:15]
	v_add_f32_e32 v221, v112, v113
	v_cmp_lt_f32_e32 vcc, s59, v221
	v_add_f32_e32 v100, v118, v221
	s_waitcnt lgkmcnt(0)
	v_mfma_f32_32x32x16_bf16 v[16:31], v[102:105], v[64:67], v[16:31]
	ds_read_b128 v[64:67], v181 offset:26624
	ds_read_b128 v[96:99], v181 offset:33280
	s_cbranch_vccz .LBB0_1008
	v_mov_b32_e32 v222, v221
	v_mov_b32_e32 v223, v221
	s_nop 1
	v_permlane32_swap_b32_e32 v222, v223
	v_add_f32_e32 v222, v222, v223
	v_log_f32_e32 v222, v222
	s_nop 0
	v_max_f32_e32 v33, 0, v222
	v_exp_f32_e64 v34, -v33
	v_add_f32_e32 v212, v212, v33
	v_xor_b32_e32 v32, 0x80000000, v212
	v_sub_f32_e32 v137, v137, v33
	v_pk_mul_f32 v[14:15], v[14:15], v[34:35] op_sel_hi:[1,0]
	v_pk_mul_f32 v[12:13], v[12:13], v[34:35] op_sel_hi:[1,0]
	v_pk_mul_f32 v[10:11], v[10:11], v[34:35] op_sel_hi:[1,0]
	v_pk_mul_f32 v[8:9], v[8:9], v[34:35] op_sel_hi:[1,0]
	v_pk_mul_f32 v[6:7], v[6:7], v[34:35] op_sel_hi:[1,0]
	v_pk_mul_f32 v[4:5], v[4:5], v[34:35] op_sel_hi:[1,0]
	v_pk_mul_f32 v[2:3], v[2:3], v[34:35] op_sel_hi:[1,0]
	v_pk_mul_f32 v[0:1], v[0:1], v[34:35] op_sel_hi:[1,0]
	v_pk_mul_f32 v[30:31], v[30:31], v[34:35] op_sel_hi:[1,0]
	v_pk_mul_f32 v[28:29], v[28:29], v[34:35] op_sel_hi:[1,0]
	v_pk_mul_f32 v[26:27], v[26:27], v[34:35] op_sel_hi:[1,0]
	v_pk_mul_f32 v[24:25], v[24:25], v[34:35] op_sel_hi:[1,0]
	v_pk_mul_f32 v[22:23], v[22:23], v[34:35] op_sel_hi:[1,0]
	v_pk_mul_f32 v[20:21], v[20:21], v[34:35] op_sel_hi:[1,0]
	v_pk_mul_f32 v[18:19], v[18:19], v[34:35] op_sel_hi:[1,0]
	v_pk_mul_f32 v[16:17], v[16:17], v[34:35] op_sel_hi:[1,0]
	v_sub_f32_e32 v136, v136, v33
	v_sub_f32_e32 v135, v135, v33
	v_sub_f32_e32 v134, v134, v33
	v_sub_f32_e32 v133, v133, v33
	v_sub_f32_e32 v132, v132, v33
	v_sub_f32_e32 v131, v131, v33
	v_sub_f32_e32 v130, v130, v33
	v_sub_f32_e32 v129, v129, v33
	v_sub_f32_e32 v128, v128, v33
	v_sub_f32_e32 v127, v127, v33
	v_sub_f32_e32 v126, v126, v33
	v_sub_f32_e32 v125, v125, v33
	v_sub_f32_e32 v124, v124, v33
	v_sub_f32_e32 v123, v123, v33
	v_sub_f32_e32 v122, v122, v33
	v_sub_f32_e32 v95, v95, v33
	v_sub_f32_e32 v94, v94, v33
	v_sub_f32_e32 v93, v93, v33
	v_sub_f32_e32 v92, v92, v33
	v_sub_f32_e32 v91, v91, v33
	v_sub_f32_e32 v90, v90, v33
	v_sub_f32_e32 v89, v89, v33
	v_sub_f32_e32 v88, v88, v33
	v_sub_f32_e32 v87, v87, v33
	v_sub_f32_e32 v86, v86, v33
	v_sub_f32_e32 v85, v85, v33
	v_sub_f32_e32 v84, v84, v33
	v_sub_f32_e32 v83, v83, v33
	v_sub_f32_e32 v82, v82, v33
	v_sub_f32_e32 v81, v81, v33
	v_sub_f32_e32 v80, v80, v33
	v_mul_f32_e32 v100, v100, v34
	v_mov_b32_e32 v33, v32
	v_mov_b32_e32 v34, v32
	v_mov_b32_e32 v35, v32
	v_mov_b32_e32 v36, v32
	v_mov_b32_e32 v37, v32
	v_mov_b32_e32 v38, v32
	v_mov_b32_e32 v39, v32
	v_mov_b32_e32 v40, v32
	v_mov_b32_e32 v41, v32
	v_mov_b32_e32 v42, v32
	v_mov_b32_e32 v43, v32
	v_mov_b32_e32 v44, v32
	v_mov_b32_e32 v45, v32
	v_mov_b32_e32 v46, v32
	v_mov_b32_e32 v47, v32
	v_mov_b32_e32 v48, v32
	v_mov_b32_e32 v49, v32
	v_mov_b32_e32 v50, v32
	v_mov_b32_e32 v51, v32
	v_mov_b32_e32 v52, v32
	v_mov_b32_e32 v53, v32
	v_mov_b32_e32 v54, v32
	v_mov_b32_e32 v55, v32
	v_mov_b32_e32 v56, v32
	v_mov_b32_e32 v57, v32
	v_mov_b32_e32 v58, v32
	v_mov_b32_e32 v59, v32
	v_mov_b32_e32 v60, v32
	v_mov_b32_e32 v61, v32
	v_mov_b32_e32 v62, v32
	v_mov_b32_e32 v63, v32

.LBB0_1012:
	ds_read_b128 v[102:105], v181 offset:26656
	ds_read_b128 v[138:141], v181 offset:33312
	s_waitcnt lgkmcnt(3)
	v_mfma_f32_32x32x16_bf16 v[106:121], v[64:67], v[144:147], v[32:47]
	v_exp_f32_e32 v101, v122
	v_exp_f32_e32 v142, v123
	v_exp_f32_e32 v143, v124
	v_exp_f32_e32 v202, v125
	v_exp_f32_e32 v126, v126
	v_exp_f32_e32 v127, v127
	s_waitcnt lgkmcnt(2)
	v_mfma_f32_32x32x16_bf16 v[64:79], v[96:99], v[144:147], v[32:47]
	ds_read_b128 v[96:99], v181 offset:26688
	ds_read_b128 v[122:125], v181 offset:33344
	s_waitcnt lgkmcnt(3)
	v_mfma_f32_32x32x16_bf16 v[106:121], v[102:105], v[148:151], v[106:121]
	v_cvt_pk_bf16_f32 v102, v101, v142
	v_add_f32_e32 v101, v143, v101
	v_add_f32_e32 v104, v202, v142
	v_add_f32_e32 v101, v126, v101
	s_waitcnt lgkmcnt(2)
	v_mfma_f32_32x32x16_bf16 v[64:79], v[138:141], v[148:151], v[64:79]
	v_add_f32_e32 v105, v127, v104
	v_exp_f32_e32 v203, v128
	v_exp_f32_e32 v204, v129
	v_exp_f32_e32 v205, v130
	v_exp_f32_e32 v213, v131
	v_exp_f32_e32 v214, v132
	v_exp_f32_e32 v215, v133
	v_cvt_pk_bf16_f32 v103, v143, v202
	v_cvt_pk_bf16_f32 v104, v126, v127
	ds_read_b128 v[126:129], v181 offset:26720
	ds_read_b128 v[130:133], v181 offset:33376
	s_waitcnt lgkmcnt(3)
	v_mfma_f32_32x32x16_bf16 v[106:121], v[96:99], v[152:155], v[106:121]
	v_add_f32_e32 v96, v203, v101
	v_add_f32_e32 v97, v204, v105
	v_add_f32_e32 v98, v205, v96
	v_add_f32_e32 v97, v213, v97
	v_add_f32_e32 v98, v214, v98
	v_add_f32_e32 v99, v215, v97
	s_waitcnt lgkmcnt(2)
	v_mfma_f32_32x32x16_bf16 v[64:79], v[122:125], v[152:155], v[64:79]
	ds_read_b128 v[122:125], v181 offset:26752
	v_exp_f32_e32 v138, v134
	v_exp_f32_e32 v139, v135
	v_exp_f32_e32 v140, v136
	v_exp_f32_e32 v141, v137
	ds_read_b128 v[134:137], v181 offset:33408
	v_cvt_pk_bf16_f32 v105, v203, v204
	v_cvt_pk_bf16_f32 v96, v205, v213
	v_cvt_pk_bf16_f32 v97, v214, v215
	s_waitcnt lgkmcnt(3)
	v_mfma_f32_32x32x16_bf16 v[106:121], v[126:129], v[156:159], v[106:121]
	v_exp_f32_e32 v101, v80
	v_exp_f32_e32 v142, v81
	v_add_f32_e32 v80, v138, v98
	v_add_f32_e32 v81, v139, v99
	v_exp_f32_e32 v203, v84
	v_exp_f32_e32 v204, v85
	s_waitcnt lgkmcnt(2)
	v_mfma_f32_32x32x16_bf16 v[64:79], v[130:133], v[156:159], v[64:79]
	v_add_f32_e32 v84, v140, v80
	v_add_f32_e32 v85, v141, v81
	v_exp_f32_e32 v143, v82
	v_exp_f32_e32 v202, v83
	ds_read_b128 v[80:83], v181 offset:26784
	ds_read_b128 v[126:129], v181 offset:33440
	v_cvt_pk_bf16_f32 v98, v138, v139
	v_cvt_pk_bf16_f32 v99, v140, v141
	s_waitcnt lgkmcnt(3)
	v_mfma_f32_32x32x16_bf16 v[106:121], v[122:125], v[160:163], v[106:121]
	v_exp_f32_e32 v87, v87
	v_exp_f32_e32 v130, v86
	v_add_f32_e32 v86, v101, v84
	v_add_f32_e32 v85, v142, v85
	v_exp_f32_e32 v131, v88
	v_add_f32_e32 v86, v143, v86
	s_waitcnt lgkmcnt(2)
	v_mfma_f32_32x32x16_bf16 v[64:79], v[134:137], v[160:163], v[64:79]
	v_add_f32_e32 v88, v202, v85
	v_cvt_pk_bf16_f32 v84, v101, v142
	v_add_f32_e32 v101, v203, v86
	v_add_f32_e32 v134, v204, v88
	v_exp_f32_e32 v132, v89
	v_exp_f32_e32 v133, v90
	v_exp_f32_e32 v138, v91
	ds_read_b128 v[88:91], v210 offset:62464
	ds_read_b128 v[122:125], v211 offset:13824
	v_cvt_pk_bf16_f32 v85, v143, v202
	v_cvt_pk_bf16_f32 v86, v203, v204
	s_waitcnt lgkmcnt(3)
	v_mfma_f32_32x32x16_bf16 v[106:121], v[80:83], v[164:167], v[106:121]
	v_add_f32_e32 v80, v130, v101
	v_add_f32_e32 v81, v87, v134
	v_add_f32_e32 v82, v131, v80
	v_add_f32_e32 v81, v132, v81
	v_add_f32_e32 v82, v133, v82
	v_add_f32_e32 v83, v138, v81
	s_waitcnt lgkmcnt(2)
	v_mfma_f32_32x32x16_bf16 v[64:79], v[126:129], v[164:167], v[64:79]
	v_exp_f32_e32 v135, v92
	v_exp_f32_e32 v136, v93
	v_exp_f32_e32 v137, v94
	v_exp_f32_e32 v139, v95
	ds_read_b128 v[92:95], v210 offset:62496
	ds_read_b128 v[126:129], v211 offset:13856
	v_cvt_pk_bf16_f32 v87, v130, v87
	v_cvt_pk_bf16_f32 v80, v131, v132
	v_cvt_pk_bf16_f32 v81, v133, v138
	s_waitcnt lgkmcnt(3)
	v_mfma_f32_32x32x16_bf16 v[0:15], v[88:91], v[102:105], v[0:15]
	v_add_f32_e32 v88, v135, v82
	v_add_f32_e32 v83, v136, v83
	v_add_f32_e32 v101, v137, v88
	ds_read_b128 v[88:91], v210 offset:62528
	v_add_f32_e32 v130, v139, v83
	v_cvt_pk_bf16_f32 v82, v135, v136
	v_cvt_pk_bf16_f32 v83, v137, v139
	s_waitcnt lgkmcnt(3)
	v_mfma_f32_32x32x16_bf16 v[16:31], v[122:125], v[102:105], v[16:31]
	s_waitcnt lgkmcnt(2)
	v_mfma_f32_32x32x16_bf16 v[0:15], v[92:95], v[96:99], v[0:15]
	ds_read_b128 v[92:95], v211 offset:13888
	s_waitcnt lgkmcnt(2)
	v_mfma_f32_32x32x16_bf16 v[16:31], v[126:129], v[96:99], v[16:31]
	ds_read_b128 v[96:99], v210 offset:62560
	ds_read_b128 v[102:105], v211 offset:13920
	s_waitcnt lgkmcnt(3)
	v_mfma_f32_32x32x16_bf16 v[0:15], v[88:91], v[84:87], v[0:15]
	s_waitcnt lgkmcnt(2)
	v_mfma_f32_32x32x16_bf16 v[16:31], v[92:95], v[84:87], v[16:31]
	s_waitcnt lgkmcnt(1)
	v_mfma_f32_32x32x16_bf16 v[0:15], v[96:99], v[80:83], v[0:15]
	v_add_f32_e32 v221, v101, v130
	v_cmp_lt_f32_e32 vcc, s59, v221
	v_add_f32_e32 v88, v100, v221
	s_waitcnt lgkmcnt(0)
	v_mfma_f32_32x32x16_bf16 v[16:31], v[102:105], v[80:83], v[16:31]
	s_waitcnt vmcnt(0)
	s_barrier
	ds_read_b128 v[84:87], v181 offset:39936
	ds_read_b128 v[80:83], v181 offset:46592
	s_cbranch_vccz .LBB0_1014
	v_mov_b32_e32 v222, v221
	v_mov_b32_e32 v223, v221
	s_nop 1
	v_permlane32_swap_b32_e32 v222, v223
	v_add_f32_e32 v222, v222, v223
	v_log_f32_e32 v222, v222
	s_nop 0
	v_max_f32_e32 v33, 0, v222
	v_exp_f32_e64 v34, -v33
	v_add_f32_e32 v212, v212, v33
	v_xor_b32_e32 v32, 0x80000000, v212
	v_sub_f32_e32 v121, v121, v33
	v_pk_mul_f32 v[14:15], v[14:15], v[34:35] op_sel_hi:[1,0]
	v_pk_mul_f32 v[12:13], v[12:13], v[34:35] op_sel_hi:[1,0]
	v_pk_mul_f32 v[10:11], v[10:11], v[34:35] op_sel_hi:[1,0]
	v_pk_mul_f32 v[8:9], v[8:9], v[34:35] op_sel_hi:[1,0]
	v_pk_mul_f32 v[6:7], v[6:7], v[34:35] op_sel_hi:[1,0]
	v_pk_mul_f32 v[4:5], v[4:5], v[34:35] op_sel_hi:[1,0]
	v_pk_mul_f32 v[2:3], v[2:3], v[34:35] op_sel_hi:[1,0]
	v_pk_mul_f32 v[0:1], v[0:1], v[34:35] op_sel_hi:[1,0]
	v_pk_mul_f32 v[30:31], v[30:31], v[34:35] op_sel_hi:[1,0]
	v_pk_mul_f32 v[28:29], v[28:29], v[34:35] op_sel_hi:[1,0]
	v_pk_mul_f32 v[26:27], v[26:27], v[34:35] op_sel_hi:[1,0]
	v_pk_mul_f32 v[24:25], v[24:25], v[34:35] op_sel_hi:[1,0]
	v_pk_mul_f32 v[22:23], v[22:23], v[34:35] op_sel_hi:[1,0]
	v_pk_mul_f32 v[20:21], v[20:21], v[34:35] op_sel_hi:[1,0]
	v_pk_mul_f32 v[18:19], v[18:19], v[34:35] op_sel_hi:[1,0]
	v_pk_mul_f32 v[16:17], v[16:17], v[34:35] op_sel_hi:[1,0]
	v_sub_f32_e32 v120, v120, v33
	v_sub_f32_e32 v119, v119, v33
	v_sub_f32_e32 v118, v118, v33
	v_sub_f32_e32 v117, v117, v33
	v_sub_f32_e32 v116, v116, v33
	v_sub_f32_e32 v115, v115, v33
	v_sub_f32_e32 v114, v114, v33
	v_sub_f32_e32 v113, v113, v33
	v_sub_f32_e32 v112, v112, v33
	v_sub_f32_e32 v111, v111, v33
	v_sub_f32_e32 v110, v110, v33
	v_sub_f32_e32 v109, v109, v33
	v_sub_f32_e32 v108, v108, v33
	v_sub_f32_e32 v107, v107, v33
	v_sub_f32_e32 v106, v106, v33
	v_sub_f32_e32 v79, v79, v33
	v_sub_f32_e32 v78, v78, v33
	v_sub_f32_e32 v77, v77, v33
	v_sub_f32_e32 v76, v76, v33
	v_sub_f32_e32 v75, v75, v33
	v_sub_f32_e32 v74, v74, v33
	v_sub_f32_e32 v73, v73, v33
	v_sub_f32_e32 v72, v72, v33
	v_sub_f32_e32 v71, v71, v33
	v_sub_f32_e32 v70, v70, v33
	v_sub_f32_e32 v69, v69, v33
	v_sub_f32_e32 v68, v68, v33
	v_sub_f32_e32 v67, v67, v33
	v_sub_f32_e32 v66, v66, v33
	v_sub_f32_e32 v65, v65, v33
	v_sub_f32_e32 v64, v64, v33
	v_mul_f32_e32 v88, v88, v34
	v_mov_b32_e32 v33, v32
	v_mov_b32_e32 v34, v32
	v_mov_b32_e32 v35, v32
	v_mov_b32_e32 v36, v32
	v_mov_b32_e32 v37, v32
	v_mov_b32_e32 v38, v32
	v_mov_b32_e32 v39, v32
	v_mov_b32_e32 v40, v32
	v_mov_b32_e32 v41, v32
	v_mov_b32_e32 v42, v32
	v_mov_b32_e32 v43, v32
	v_mov_b32_e32 v44, v32
	v_mov_b32_e32 v45, v32
	v_mov_b32_e32 v46, v32
	v_mov_b32_e32 v47, v32
	v_mov_b32_e32 v48, v32
	v_mov_b32_e32 v49, v32
	v_mov_b32_e32 v50, v32
	v_mov_b32_e32 v51, v32
	v_mov_b32_e32 v52, v32
	v_mov_b32_e32 v53, v32
	v_mov_b32_e32 v54, v32
	v_mov_b32_e32 v55, v32
	v_mov_b32_e32 v56, v32
	v_mov_b32_e32 v57, v32
	v_mov_b32_e32 v58, v32
	v_mov_b32_e32 v59, v32
	v_mov_b32_e32 v60, v32
	v_mov_b32_e32 v61, v32
	v_mov_b32_e32 v62, v32
	v_mov_b32_e32 v63, v32

.LBB0_1018:
	s_waitcnt lgkmcnt(1)
	v_mfma_f32_32x32x16_bf16 v[122:137], v[84:87], v[144:147], v[32:47]
	ds_read_b128 v[84:87], v181 offset:39968
	ds_read_b128 v[90:93], v181 offset:46624
	v_exp_f32_e32 v89, v106
	v_exp_f32_e32 v94, v107
	v_exp_f32_e32 v95, v108
	v_exp_f32_e32 v142, v109
	v_exp_f32_e32 v143, v110
	v_exp_f32_e32 v202, v111
	s_waitcnt lgkmcnt(2)
	v_mfma_f32_32x32x16_bf16 v[96:111], v[80:83], v[144:147], v[32:47]
	ds_read_b128 v[80:83], v181 offset:40000
	ds_read_b128 v[138:141], v181 offset:46656
	s_waitcnt lgkmcnt(3)
	v_mfma_f32_32x32x16_bf16 v[122:137], v[84:87], v[148:151], v[122:137]
	v_exp_f32_e32 v116, v116
	v_add_f32_e32 v87, v95, v89
	v_add_f32_e32 v86, v142, v94
	v_cvt_pk_bf16_f32 v84, v89, v94
	s_waitcnt lgkmcnt(2)
	v_mfma_f32_32x32x16_bf16 v[96:111], v[90:93], v[148:151], v[96:111]
	ds_read_b128 v[90:93], v181 offset:40032
	v_add_f32_e32 v87, v143, v87
	v_add_f32_e32 v89, v202, v86
	v_exp_f32_e32 v203, v112
	v_exp_f32_e32 v204, v113
	v_exp_f32_e32 v205, v114
	v_exp_f32_e32 v213, v115
	ds_read_b128 v[112:115], v181 offset:46688
	v_exp_f32_e32 v117, v117
	v_cvt_pk_bf16_f32 v85, v95, v142
	v_cvt_pk_bf16_f32 v86, v143, v202
	s_waitcnt lgkmcnt(3)
	v_mfma_f32_32x32x16_bf16 v[122:137], v[80:83], v[152:155], v[122:137]
	v_add_f32_e32 v80, v203, v87
	v_add_f32_e32 v81, v204, v89
	v_add_f32_e32 v82, v205, v80
	v_add_f32_e32 v81, v213, v81
	v_add_f32_e32 v82, v116, v82
	v_add_f32_e32 v83, v117, v81
	s_waitcnt lgkmcnt(2)
	v_mfma_f32_32x32x16_bf16 v[96:111], v[138:141], v[152:155], v[96:111]
	v_exp_f32_e32 v94, v118
	v_exp_f32_e32 v95, v119
	v_exp_f32_e32 v120, v120
	v_exp_f32_e32 v121, v121
	v_cvt_pk_bf16_f32 v87, v203, v204
	v_cvt_pk_bf16_f32 v80, v205, v213
	v_cvt_pk_bf16_f32 v81, v116, v117
	ds_read_b128 v[116:119], v181 offset:40064
	ds_read_b128 v[138:141], v181 offset:46720
	s_waitcnt lgkmcnt(3)
	v_mfma_f32_32x32x16_bf16 v[122:137], v[90:93], v[156:159], v[122:137]
	v_exp_f32_e32 v89, v64
	v_exp_f32_e32 v142, v65
	v_add_f32_e32 v64, v94, v82
	v_add_f32_e32 v65, v95, v83
	v_exp_f32_e32 v203, v68
	v_exp_f32_e32 v204, v69
	s_waitcnt lgkmcnt(2)
	v_mfma_f32_32x32x16_bf16 v[96:111], v[112:115], v[156:159], v[96:111]
	v_add_f32_e32 v68, v120, v64
	v_add_f32_e32 v69, v121, v65
	v_exp_f32_e32 v143, v66
	v_exp_f32_e32 v202, v67
	ds_read_b128 v[64:67], v181 offset:40096
	ds_read_b128 v[90:93], v181 offset:46752
	v_cvt_pk_bf16_f32 v82, v94, v95
	v_cvt_pk_bf16_f32 v83, v120, v121
	s_waitcnt lgkmcnt(3)
	v_mfma_f32_32x32x16_bf16 v[122:137], v[116:119], v[160:163], v[122:137]
	v_exp_f32_e32 v116, v74
	v_exp_f32_e32 v94, v70
	v_add_f32_e32 v70, v89, v68
	v_add_f32_e32 v69, v142, v69
	v_exp_f32_e32 v95, v72
	v_add_f32_e32 v70, v143, v70
	s_waitcnt lgkmcnt(2)
	v_mfma_f32_32x32x16_bf16 v[96:111], v[138:141], v[160:163], v[96:111]
	v_add_f32_e32 v72, v202, v69
	v_cvt_pk_bf16_f32 v68, v89, v142
	v_add_f32_e32 v89, v203, v70
	v_add_f32_e32 v118, v204, v72
	v_exp_f32_e32 v71, v71
	v_exp_f32_e32 v120, v73
	v_exp_f32_e32 v117, v75
	ds_read_b128 v[72:75], v211 offset:18432
	ds_read_b128 v[112:115], v211 offset:23040
	v_cvt_pk_bf16_f32 v69, v143, v202
	v_cvt_pk_bf16_f32 v70, v203, v204
	s_waitcnt lgkmcnt(3)
	v_mfma_f32_32x32x16_bf16 v[122:137], v[64:67], v[164:167], v[122:137]
	v_add_f32_e32 v64, v94, v89
	v_add_f32_e32 v65, v71, v118
	v_add_f32_e32 v66, v95, v64
	v_add_f32_e32 v65, v120, v65
	v_add_f32_e32 v66, v116, v66
	v_add_f32_e32 v67, v117, v65
	s_waitcnt lgkmcnt(2)
	v_mfma_f32_32x32x16_bf16 v[96:111], v[90:93], v[164:167], v[96:111]
	v_exp_f32_e32 v119, v76
	v_exp_f32_e32 v121, v77
	v_exp_f32_e32 v138, v78
	v_exp_f32_e32 v139, v79
	ds_read_b128 v[76:79], v211 offset:18464
	ds_read_b128 v[90:93], v211 offset:23072
	v_cvt_pk_bf16_f32 v71, v94, v71
	v_cvt_pk_bf16_f32 v64, v95, v120
	v_cvt_pk_bf16_f32 v65, v116, v117
	s_waitcnt lgkmcnt(3)
	v_mfma_f32_32x32x16_bf16 v[0:15], v[72:75], v[84:87], v[0:15]
	v_add_f32_e32 v72, v119, v66
	v_add_f32_e32 v67, v121, v67
	v_add_f32_e32 v89, v138, v72
	ds_read_b128 v[72:75], v211 offset:18496
	v_add_f32_e32 v94, v139, v67
	v_cvt_pk_bf16_f32 v66, v119, v121
	v_cvt_pk_bf16_f32 v67, v138, v139
	s_waitcnt lgkmcnt(3)
	v_mfma_f32_32x32x16_bf16 v[16:31], v[112:115], v[84:87], v[16:31]
	s_waitcnt lgkmcnt(2)
	v_mfma_f32_32x32x16_bf16 v[0:15], v[76:79], v[80:83], v[0:15]
	ds_read_b128 v[76:79], v211 offset:23104
	s_waitcnt lgkmcnt(2)
	v_mfma_f32_32x32x16_bf16 v[16:31], v[90:93], v[80:83], v[16:31]
	ds_read_b128 v[80:83], v211 offset:18528
	ds_read_b128 v[84:87], v211 offset:23136
	s_waitcnt lgkmcnt(3)
	v_mfma_f32_32x32x16_bf16 v[0:15], v[72:75], v[68:71], v[0:15]
	s_waitcnt lgkmcnt(2)
	v_mfma_f32_32x32x16_bf16 v[16:31], v[76:79], v[68:71], v[16:31]
	s_waitcnt lgkmcnt(1)
	v_mfma_f32_32x32x16_bf16 v[0:15], v[80:83], v[64:67], v[0:15]
	v_add_f32_e32 v221, v89, v94
	v_cmp_lt_f32_e32 vcc, s59, v221
	v_add_f32_e32 v116, v88, v221
	s_waitcnt lgkmcnt(0)
	v_mfma_f32_32x32x16_bf16 v[16:31], v[84:87], v[64:67], v[16:31]
	ds_read_b128 v[64:67], v181
	ds_read_b128 v[112:115], v181 offset:6656
	s_cbranch_vccz .LBB0_1020
	v_mov_b32_e32 v222, v221
	v_mov_b32_e32 v223, v221
	s_nop 1
	v_permlane32_swap_b32_e32 v222, v223
	v_add_f32_e32 v222, v222, v223
	v_log_f32_e32 v222, v222
	s_nop 0
	v_max_f32_e32 v33, 0, v222
	v_exp_f32_e64 v34, -v33
	v_add_f32_e32 v212, v212, v33
	v_xor_b32_e32 v32, 0x80000000, v212
	v_sub_f32_e32 v137, v137, v33
	v_pk_mul_f32 v[14:15], v[14:15], v[34:35] op_sel_hi:[1,0]
	v_pk_mul_f32 v[12:13], v[12:13], v[34:35] op_sel_hi:[1,0]
	v_pk_mul_f32 v[10:11], v[10:11], v[34:35] op_sel_hi:[1,0]
	v_pk_mul_f32 v[8:9], v[8:9], v[34:35] op_sel_hi:[1,0]
	v_pk_mul_f32 v[6:7], v[6:7], v[34:35] op_sel_hi:[1,0]
	v_pk_mul_f32 v[4:5], v[4:5], v[34:35] op_sel_hi:[1,0]
	v_pk_mul_f32 v[2:3], v[2:3], v[34:35] op_sel_hi:[1,0]
	v_pk_mul_f32 v[0:1], v[0:1], v[34:35] op_sel_hi:[1,0]
	v_pk_mul_f32 v[30:31], v[30:31], v[34:35] op_sel_hi:[1,0]
	v_pk_mul_f32 v[28:29], v[28:29], v[34:35] op_sel_hi:[1,0]
	v_pk_mul_f32 v[26:27], v[26:27], v[34:35] op_sel_hi:[1,0]
	v_pk_mul_f32 v[24:25], v[24:25], v[34:35] op_sel_hi:[1,0]
	v_pk_mul_f32 v[22:23], v[22:23], v[34:35] op_sel_hi:[1,0]
	v_pk_mul_f32 v[20:21], v[20:21], v[34:35] op_sel_hi:[1,0]
	v_pk_mul_f32 v[18:19], v[18:19], v[34:35] op_sel_hi:[1,0]
	v_pk_mul_f32 v[16:17], v[16:17], v[34:35] op_sel_hi:[1,0]
	v_sub_f32_e32 v136, v136, v33
	v_sub_f32_e32 v135, v135, v33
	v_sub_f32_e32 v134, v134, v33
	v_sub_f32_e32 v133, v133, v33
	v_sub_f32_e32 v132, v132, v33
	v_sub_f32_e32 v131, v131, v33
	v_sub_f32_e32 v130, v130, v33
	v_sub_f32_e32 v129, v129, v33
	v_sub_f32_e32 v128, v128, v33
	v_sub_f32_e32 v127, v127, v33
	v_sub_f32_e32 v126, v126, v33
	v_sub_f32_e32 v125, v125, v33
	v_sub_f32_e32 v124, v124, v33
	v_sub_f32_e32 v123, v123, v33
	v_sub_f32_e32 v122, v122, v33
	v_sub_f32_e32 v111, v111, v33
	v_sub_f32_e32 v110, v110, v33
	v_sub_f32_e32 v109, v109, v33
	v_sub_f32_e32 v108, v108, v33
	v_sub_f32_e32 v107, v107, v33
	v_sub_f32_e32 v106, v106, v33
	v_sub_f32_e32 v105, v105, v33
	v_sub_f32_e32 v104, v104, v33
	v_sub_f32_e32 v103, v103, v33
	v_sub_f32_e32 v102, v102, v33
	v_sub_f32_e32 v101, v101, v33
	v_sub_f32_e32 v100, v100, v33
	v_sub_f32_e32 v99, v99, v33
	v_sub_f32_e32 v98, v98, v33
	v_sub_f32_e32 v97, v97, v33
	v_sub_f32_e32 v96, v96, v33
	v_mul_f32_e32 v116, v116, v34
	v_mov_b32_e32 v33, v32
	v_mov_b32_e32 v34, v32
	v_mov_b32_e32 v35, v32
	v_mov_b32_e32 v36, v32
	v_mov_b32_e32 v37, v32
	v_mov_b32_e32 v38, v32
	v_mov_b32_e32 v39, v32
	v_mov_b32_e32 v40, v32
	v_mov_b32_e32 v41, v32
	v_mov_b32_e32 v42, v32
	v_mov_b32_e32 v43, v32
	v_mov_b32_e32 v44, v32
	v_mov_b32_e32 v45, v32
	v_mov_b32_e32 v46, v32
	v_mov_b32_e32 v47, v32
	v_mov_b32_e32 v48, v32
	v_mov_b32_e32 v49, v32
	v_mov_b32_e32 v50, v32
	v_mov_b32_e32 v51, v32
	v_mov_b32_e32 v52, v32
	v_mov_b32_e32 v53, v32
	v_mov_b32_e32 v54, v32
	v_mov_b32_e32 v55, v32
	v_mov_b32_e32 v56, v32
	v_mov_b32_e32 v57, v32
	v_mov_b32_e32 v58, v32
	v_mov_b32_e32 v59, v32
	v_mov_b32_e32 v60, v32
	v_mov_b32_e32 v61, v32
	v_mov_b32_e32 v62, v32
	v_mov_b32_e32 v63, v32
